# SSD chunk unit: 16 row loads per conv batch issued together instead of pairwise load-wait; plus pipelined sample attention and P3 K-tile LDS relayout
# speedup vs baseline: 1.0284x; 1.0222x over previous
.LBB0_1114:
	s_mov_b64 s[68:69], 0
	s_and_b64 vcc, exec, s[0:1]
	s_mov_b64 s[0:1], 0
	s_cbranch_vccz .LBB0_1243
	s_add_i32 s0, s63, 0xfffffde0
	s_lshr_b32 s60, s0, 3
	s_lshl_b32 s92, s60, 14
	v_readlane_b32 s12, v254, 29
	s_and_b32 s10, s63, 7
	s_add_i32 s10, s10, s60
	s_and_b32 s10, s10, 7
	s_lshl_b64 s[0:1], s[92:93], 2
	v_readlane_b32 s20, v254, 37
	v_mov_b32_e32 v105, v0
	v_readlane_b32 s21, v254, 38
	s_add_u32 s0, s20, s0
	s_addc_u32 s1, s21, s1
	s_lshl_b32 s2, s10, 2
	v_lshlrev_b32_e32 v2, 2, v105
	s_add_u32 s0, s0, s2
	v_ashrrev_i32_e32 v3, 31, v2
	s_addc_u32 s1, s1, 0
	v_lshlrev_b64 v[4:5], 5, v[2:3]
	v_lshl_add_u64 v[4:5], s[0:1], 0, v[4:5]
	global_load_dword v6, v[4:5], off
	v_or_b32_e32 v4, 1, v2
	v_ashrrev_i32_e32 v5, 31, v4
	v_lshlrev_b64 v[4:5], 5, v[4:5]
	v_lshl_add_u64 v[4:5], s[0:1], 0, v[4:5]
	global_load_dword v7, v[4:5], off
	v_or_b32_e32 v4, 2, v2
	v_ashrrev_i32_e32 v5, 31, v4
	v_or_b32_e32 v2, 3, v2
	v_lshlrev_b64 v[4:5], 5, v[4:5]
	v_ashrrev_i32_e32 v3, 31, v2
	v_lshl_add_u64 v[4:5], s[0:1], 0, v[4:5]
	v_lshlrev_b64 v[2:3], 5, v[2:3]
	global_load_dword v8, v[4:5], off
	v_lshl_add_u64 v[2:3], s[0:1], 0, v[2:3]
	global_load_dword v3, v[2:3], off
	s_add_i32 s34, s63, 0xfffffde0
	s_lshr_b32 s70, s34, 3
	s_and_b32 s71, s34, 7
	s_add_i32 s71, s71, s70
	s_and_b32 s71, s71, 7
	v_lshrrev_b32_e32 v80, 6, v0
	v_and_b32_e32 v77, 15, v0
	v_bfe_u32 v76, v0, 4, 2
	v_readfirstlane_b32 s72, v80
	v_readlane_b32 s34, v254, 33
	v_readlane_b32 s35, v254, 34
	v_readlane_b32 s36, v254, 35
	v_readlane_b32 s37, v254, 36
	v_lshlrev_b32_e32 v72, 11, v76
	v_lshl_add_u32 v72, v77, 4, v72
	v_add_u32_e32 v73, 0x2000, v72
	v_add_u32_e32 v74, 0x4000, v72
	v_add_u32_e32 v75, 0x6000, v72
	v_lshlrev_b32_e32 v81, 10, v77
	v_lshl_add_u32 v81, v76, 4, v81
	s_lshl_b32 s38, s70, 22
	s_lshl_b32 s39, s71, 8
	s_add_i32 s38, s38, s39
	s_lshl_b32 s39, s72, 15
	s_add_i32 s38, s38, s39
	s_add_u32 s74, s34, s38
	s_addc_u32 s75, s35, 0
	s_add_u32 s76, s36, s38
	s_addc_u32 s77, s37, 0
	s_add_u32 s78, s76, 0x40000
	s_addc_u32 s79, s77, 0
	s_lshl_b32 s38, s70, 14
	s_lshl_b32 s39, s71, 7
	s_add_i32 s38, s38, s39
	s_add_i32 s39, s38, 0x7faea00
	s_add_u32 s80, s90, s39
	s_addc_u32 s81, s91, 0
	s_add_i32 s39, s38, 0x1e2ea00
	s_add_u32 s86, s90, s39
	s_addc_u32 s87, s91, 0
	s_lshl_b32 s38, s70, 15
	s_lshl_b32 s39, s71, 8
	s_add_i32 s38, s38, s39
	s_add_i32 s39, s38, 0x821c000
	s_add_u32 s82, s88, s39
	s_addc_u32 s83, s89, 0
	s_add_i32 s39, s38, 0x829c000
	s_add_u32 s84, s88, s39
	s_addc_u32 s85, s89, 0
	s_lshl_b32 s73, s72, 13
	s_add_i32 s73, s73, 0xd400
	global_load_dwordx4 v[64:67], v81, s[80:81]
	global_load_dwordx4 v[68:71], v81, s[80:81] offset:64
	s_cmp_lg_u32 s72, 0
	s_cbranch_scc1 .Lsa_pre_nz
	global_load_dwordx4 v[232:235], v72, s[82:83]
	global_load_dwordx4 v[236:239], v73, s[82:83]
	global_load_dwordx4 v[240:243], v74, s[82:83]
	global_load_dwordx4 v[244:247], v75, s[82:83]
.Lsa_pre_nz:
	global_load_dwordx4 v[16:19], v72, s[74:75]
	global_load_dwordx4 v[20:23], v73, s[74:75]
	global_load_dwordx4 v[24:27], v74, s[74:75]
	global_load_dwordx4 v[28:31], v75, s[74:75]
	s_add_u32 s74, s74, 0x40000
	s_addc_u32 s75, s75, 0
	global_load_dwordx4 v[32:35], v72, s[74:75]
	global_load_dwordx4 v[36:39], v73, s[74:75]
	global_load_dwordx4 v[40:43], v74, s[74:75]
	global_load_dwordx4 v[44:47], v75, s[74:75]
	s_add_u32 s74, s74, 0x40000
	s_addc_u32 s75, s75, 0
	global_load_dwordx4 v[48:51], v72, s[74:75]
	global_load_dwordx4 v[52:55], v73, s[74:75]
	global_load_dwordx4 v[56:59], v74, s[74:75]
	global_load_dwordx4 v[60:63], v75, s[74:75]
	s_add_u32 s74, s74, 0x40000
	s_addc_u32 s75, s75, 0
	global_load_dwordx4 v[180:183], v72, s[74:75]
	global_load_dwordx4 v[184:187], v73, s[74:75]
	global_load_dwordx4 v[188:191], v74, s[74:75]
	global_load_dwordx4 v[192:195], v75, s[74:75]
	s_add_u32 s74, s74, 0x40000
	s_addc_u32 s75, s75, 0
	global_load_dwordx4 v[200:203], v72, s[74:75]
	global_load_dwordx4 v[204:207], v73, s[74:75]
	global_load_dwordx4 v[208:211], v74, s[74:75]
	global_load_dwordx4 v[212:215], v75, s[74:75]
	s_add_u32 s74, s74, 0x40000
	s_addc_u32 s75, s75, 0
	v_cmp_lt_i32_e32 vcc, v87, v84
	v_cmp_lt_i32_e64 s[0:1], v88, v84
	v_and_b32_e32 v106, 63, v105
	v_cndmask_b32_e32 v2, v87, v83, vcc
	v_lshlrev_b32_e32 v9, 2, v2
	v_cmp_eq_u32_e32 vcc, 0, v106
	v_cmp_gt_u32_e64 s[28:29], 16, v106
	v_ashrrev_i32_e32 v107, 6, v105
	v_readlane_b32 s13, v254, 30
	v_readlane_b32 s14, v254, 31
	v_readlane_b32 s15, v254, 32
	v_readlane_b32 s16, v254, 33
	v_readlane_b32 s17, v254, 34
	v_readlane_b32 s18, v254, 35
	v_readlane_b32 s19, v254, 36
	v_readlane_b32 s22, v254, 39
	v_readlane_b32 s23, v254, 40
	v_readlane_b32 s24, v254, 41
	v_readlane_b32 s25, v254, 42
	v_readlane_b32 s26, v254, 43
	v_readlane_b32 s27, v254, 44
	s_waitcnt vmcnt(25)
	v_add_f32_e32 v4, 0, v6
	s_waitcnt vmcnt(24)
	v_add_f32_e32 v5, v4, v7
	v_cndmask_b32_e64 v7, v88, v83, s[0:1]
	v_lshlrev_b32_e32 v7, 2, v7
	s_waitcnt vmcnt(23)
	v_add_f32_e32 v2, v5, v8
	s_waitcnt vmcnt(22)
	v_add_f32_e32 v3, v2, v3
	ds_bpermute_b32 v6, v9, v3
	s_waitcnt lgkmcnt(0)
	v_add_f32_e32 v6, v3, v6
	v_cndmask_b32_e32 v6, v6, v3, vcc
	ds_bpermute_b32 v7, v7, v6
	v_cmp_lt_i32_e32 vcc, v89, v84
	s_waitcnt lgkmcnt(0)
	v_add_f32_e32 v7, v6, v7
	v_cndmask_b32_e32 v8, v89, v83, vcc
	v_cmp_gt_u32_e32 vcc, 2, v106
	v_lshlrev_b32_e32 v8, 2, v8
	s_nop 0
	v_cndmask_b32_e32 v6, v7, v6, vcc
	ds_bpermute_b32 v7, v8, v6
	v_cmp_lt_i32_e32 vcc, v90, v84
	s_waitcnt lgkmcnt(0)
	v_add_f32_e32 v7, v6, v7
	v_cndmask_b32_e32 v8, v90, v83, vcc
	v_cmp_gt_u32_e32 vcc, 4, v106
	v_lshlrev_b32_e32 v8, 2, v8
	s_nop 0
	v_cndmask_b32_e32 v6, v7, v6, vcc
	ds_bpermute_b32 v7, v8, v6
	v_cmp_lt_i32_e32 vcc, v91, v84
	s_waitcnt lgkmcnt(0)
	v_add_f32_e32 v7, v6, v7
	v_cndmask_b32_e32 v8, v91, v83, vcc
	v_cmp_gt_u32_e32 vcc, 8, v106
	v_lshlrev_b32_e32 v8, 2, v8
	s_nop 0
	v_cndmask_b32_e32 v6, v7, v6, vcc
	ds_bpermute_b32 v7, v8, v6
	v_cmp_lt_i32_e32 vcc, v92, v84
	s_waitcnt lgkmcnt(0)
	v_add_f32_e32 v7, v6, v7
	v_cndmask_b32_e32 v8, v92, v83, vcc
	v_lshlrev_b32_e32 v8, 2, v8
	v_cndmask_b32_e64 v6, v7, v6, s[28:29]
	ds_bpermute_b32 v7, v8, v6
	v_cmp_eq_u32_e32 vcc, 63, v106
	s_waitcnt lgkmcnt(0)
	v_add_f32_e32 v7, v6, v7
	s_and_saveexec_b64 s[0:1], vcc
	v_lshl_add_u32 v8, v107, 2, 16
	ds_write_b32 v8, v7 offset:8448
	s_or_b64 exec, exec, s[0:1]
	v_cmp_gt_u32_e32 vcc, 32, v106
	s_waitcnt lgkmcnt(0)
	s_barrier
	v_cndmask_b32_e32 v6, v7, v6, vcc
	v_sub_f32_e32 v6, v6, v3
	v_cmp_lt_i32_e32 vcc, 0, v107
	s_and_saveexec_b64 s[0:1], vcc
	s_cbranch_execz .LBB0_1127
	v_add_u32_e32 v7, -1, v107
	v_cmp_lt_u32_e32 vcc, 6, v7
	v_mov_b32_e32 v7, 0
	s_and_saveexec_b64 s[2:3], vcc
	s_cbranch_execz .LBB0_1122
	v_and_b32_e32 v7, 0x7ffffff8, v107
	s_mov_b32 s4, 0
	s_mov_b64 s[6:7], 0
	v_readlane_b32 s5, v255, 0

.LBB0_1129:
	s_or_b64 exec, exec, s[0:1]
	s_waitcnt lgkmcnt(0)
	s_barrier
	v_lshlrev_b32_e32 v80, 4, v76
	s_lshl_b32 s0, s72, 6
	s_add_i32 s0, s0, 16
	v_add_u32_e32 v80, s0, v80
	v_lshlrev_b32_e32 v81, 2, v0
	v_xor_b32_e32 v15, v77, v76
	v_lshlrev_b32_e32 v15, 4, v15
	v_lshl_add_u32 v15, v76, 8, v15
	v_add_u32_e32 v105, s73, v15
	v_xor_b32_e32 v106, 0x40, v15
	v_add_u32_e32 v106, 0x400, v106
	v_add_u32_e32 v106, s73, v106
	v_xor_b32_e32 v107, 0x80, v15
	v_add_u32_e32 v107, 0x800, v107
	v_add_u32_e32 v107, s73, v107
	v_xor_b32_e32 v108, 0xc0, v15
	v_add_u32_e32 v108, 0xc00, v108
	v_add_u32_e32 v108, s73, v108
	v_lshlrev_b32_e32 v15, 1, v76
	v_xor_b32_e32 v15, v15, v77
	v_lshlrev_b32_e32 v15, 4, v15
	v_lshl_add_u32 v15, v77, 8, v15
	v_add_u32_e32 v109, s73, v15
	v_xor_b32_e32 v110, 0x10, v15
	v_add_u32_e32 v110, s73, v110
	v_xor_b32_e32 v111, 0x80, v15
	v_add_u32_e32 v111, s73, v111
	v_xor_b32_e32 v14, 0x90, v15
	v_add_u32_e32 v14, s73, v14
	v_mov_b32_e32 v176, v101
	v_mov_b32_e32 v177, v101
	v_mov_b32_e32 v178, v101
	v_mov_b32_e32 v179, v101
	s_waitcnt vmcnt(16)
	ds_write_b128 v105, v[16:19]
	ds_write_b128 v106, v[20:23]
	ds_write_b128 v107, v[24:27]
	ds_write_b128 v108, v[28:31]
	global_load_dwordx4 v[16:19], v72, s[74:75]
	global_load_dwordx4 v[20:23], v73, s[74:75]
	global_load_dwordx4 v[24:27], v74, s[74:75]
	global_load_dwordx4 v[28:31], v75, s[74:75]
	s_add_u32 s74, s74, 0x40000
	s_addc_u32 s75, s75, 0
	ds_read_b128 v[216:219], v109
	ds_read_b128 v[220:223], v110
	ds_read_b128 v[224:227], v111
	ds_read_b128 v[228:231], v14
	ds_read_b128 v[112:115], v80
	s_waitcnt lgkmcnt(0)
	v_cvt_pk_bf16_f32 v2, v216, v217
	v_cvt_pk_bf16_f32 v3, v218, v219
	v_cvt_pk_bf16_f32 v4, v220, v221
	v_cvt_pk_bf16_f32 v5, v222, v223
	v_cvt_pk_bf16_f32 v6, v224, v225
	v_cvt_pk_bf16_f32 v7, v226, v227
	v_cvt_pk_bf16_f32 v8, v228, v229
	v_cvt_pk_bf16_f32 v9, v230, v231
	s_nop 0
	v_mfma_f32_16x16x32_bf16 v[112:115], v[2:5], v[64:67], v[112:115]
	v_mfma_f32_16x16x32_bf16 v[112:115], v[6:9], v[68:71], v[112:115]
	s_waitcnt vmcnt(16)
	ds_write_b128 v105, v[32:35]
	ds_write_b128 v106, v[36:39]
	ds_write_b128 v107, v[40:43]
	ds_write_b128 v108, v[44:47]
	global_load_dwordx4 v[32:35], v72, s[74:75]
	global_load_dwordx4 v[36:39], v73, s[74:75]
	global_load_dwordx4 v[40:43], v74, s[74:75]
	global_load_dwordx4 v[44:47], v75, s[74:75]
	s_add_u32 s74, s74, 0x40000
	s_addc_u32 s75, s75, 0
	ds_read_b128 v[216:219], v109
	ds_read_b128 v[220:223], v110
	ds_read_b128 v[224:227], v111
	ds_read_b128 v[228:231], v14
	ds_read_b128 v[116:119], v80 offset:512
	s_waitcnt lgkmcnt(0)
	v_cvt_pk_bf16_f32 v2, v216, v217
	v_cvt_pk_bf16_f32 v3, v218, v219
	v_cvt_pk_bf16_f32 v4, v220, v221
	v_cvt_pk_bf16_f32 v5, v222, v223
	v_cvt_pk_bf16_f32 v6, v224, v225
	v_cvt_pk_bf16_f32 v7, v226, v227
	v_cvt_pk_bf16_f32 v8, v228, v229
	v_cvt_pk_bf16_f32 v9, v230, v231
	s_nop 0
	v_mfma_f32_16x16x32_bf16 v[116:119], v[2:5], v[64:67], v[116:119]
	v_mfma_f32_16x16x32_bf16 v[116:119], v[6:9], v[68:71], v[116:119]
	s_waitcnt vmcnt(16)
	ds_write_b128 v105, v[48:51]
	ds_write_b128 v106, v[52:55]
	ds_write_b128 v107, v[56:59]
	ds_write_b128 v108, v[60:63]
	global_load_dwordx4 v[48:51], v72, s[74:75]
	global_load_dwordx4 v[52:55], v73, s[74:75]
	global_load_dwordx4 v[56:59], v74, s[74:75]
	global_load_dwordx4 v[60:63], v75, s[74:75]
	s_add_u32 s74, s74, 0x40000
	s_addc_u32 s75, s75, 0
	ds_read_b128 v[216:219], v109
	ds_read_b128 v[220:223], v110
	ds_read_b128 v[224:227], v111
	ds_read_b128 v[228:231], v14
	ds_read_b128 v[120:123], v80 offset:1024
	s_waitcnt lgkmcnt(0)
	v_cvt_pk_bf16_f32 v2, v216, v217
	v_cvt_pk_bf16_f32 v3, v218, v219
	v_cvt_pk_bf16_f32 v4, v220, v221
	v_cvt_pk_bf16_f32 v5, v222, v223
	v_cvt_pk_bf16_f32 v6, v224, v225
	v_cvt_pk_bf16_f32 v7, v226, v227
	v_cvt_pk_bf16_f32 v8, v228, v229
	v_cvt_pk_bf16_f32 v9, v230, v231
	s_nop 0
	v_mfma_f32_16x16x32_bf16 v[120:123], v[2:5], v[64:67], v[120:123]
	v_mfma_f32_16x16x32_bf16 v[120:123], v[6:9], v[68:71], v[120:123]
	s_waitcnt vmcnt(16)
	ds_write_b128 v105, v[180:183]
	ds_write_b128 v106, v[184:187]
	ds_write_b128 v107, v[188:191]
	ds_write_b128 v108, v[192:195]
	global_load_dwordx4 v[180:183], v72, s[74:75]
	global_load_dwordx4 v[184:187], v73, s[74:75]
	global_load_dwordx4 v[188:191], v74, s[74:75]
	global_load_dwordx4 v[192:195], v75, s[74:75]
	s_add_u32 s74, s74, 0x40000
	s_addc_u32 s75, s75, 0
	ds_read_b128 v[216:219], v109
	ds_read_b128 v[220:223], v110
	ds_read_b128 v[224:227], v111
	ds_read_b128 v[228:231], v14
	ds_read_b128 v[124:127], v80 offset:1536
	s_waitcnt lgkmcnt(0)
	v_cvt_pk_bf16_f32 v2, v216, v217
	v_cvt_pk_bf16_f32 v3, v218, v219
	v_cvt_pk_bf16_f32 v4, v220, v221
	v_cvt_pk_bf16_f32 v5, v222, v223
	v_cvt_pk_bf16_f32 v6, v224, v225
	v_cvt_pk_bf16_f32 v7, v226, v227
	v_cvt_pk_bf16_f32 v8, v228, v229
	v_cvt_pk_bf16_f32 v9, v230, v231
	s_nop 0
	v_mfma_f32_16x16x32_bf16 v[124:127], v[2:5], v[64:67], v[124:127]
	v_mfma_f32_16x16x32_bf16 v[124:127], v[6:9], v[68:71], v[124:127]
	s_waitcnt vmcnt(16)
	ds_write_b128 v105, v[200:203]
	ds_write_b128 v106, v[204:207]
	ds_write_b128 v107, v[208:211]
	ds_write_b128 v108, v[212:215]
	global_load_dwordx4 v[200:203], v72, s[74:75]
	global_load_dwordx4 v[204:207], v73, s[74:75]
	global_load_dwordx4 v[208:211], v74, s[74:75]
	global_load_dwordx4 v[212:215], v75, s[74:75]
	s_add_u32 s74, s74, 0x40000
	s_addc_u32 s75, s75, 0
	ds_read_b128 v[216:219], v109
	ds_read_b128 v[220:223], v110
	ds_read_b128 v[224:227], v111
	ds_read_b128 v[228:231], v14
	ds_read_b128 v[128:131], v80 offset:2048
	s_waitcnt lgkmcnt(0)
	v_cvt_pk_bf16_f32 v2, v216, v217
	v_cvt_pk_bf16_f32 v3, v218, v219
	v_cvt_pk_bf16_f32 v4, v220, v221
	v_cvt_pk_bf16_f32 v5, v222, v223
	v_cvt_pk_bf16_f32 v6, v224, v225
	v_cvt_pk_bf16_f32 v7, v226, v227
	v_cvt_pk_bf16_f32 v8, v228, v229
	v_cvt_pk_bf16_f32 v9, v230, v231
	s_nop 0
	v_mfma_f32_16x16x32_bf16 v[128:131], v[2:5], v[64:67], v[128:131]
	v_mfma_f32_16x16x32_bf16 v[128:131], v[6:9], v[68:71], v[128:131]
	s_waitcnt vmcnt(16)
	ds_write_b128 v105, v[16:19]
	ds_write_b128 v106, v[20:23]
	ds_write_b128 v107, v[24:27]
	ds_write_b128 v108, v[28:31]
	global_load_dwordx4 v[16:19], v72, s[74:75]
	global_load_dwordx4 v[20:23], v73, s[74:75]
	global_load_dwordx4 v[24:27], v74, s[74:75]
	global_load_dwordx4 v[28:31], v75, s[74:75]
	s_add_u32 s74, s74, 0x40000
	s_addc_u32 s75, s75, 0
	ds_read_b128 v[216:219], v109
	ds_read_b128 v[220:223], v110
	ds_read_b128 v[224:227], v111
	ds_read_b128 v[228:231], v14
	ds_read_b128 v[132:135], v80 offset:2560
	s_waitcnt lgkmcnt(0)
	v_cvt_pk_bf16_f32 v2, v216, v217
	v_cvt_pk_bf16_f32 v3, v218, v219
	v_cvt_pk_bf16_f32 v4, v220, v221
	v_cvt_pk_bf16_f32 v5, v222, v223
	v_cvt_pk_bf16_f32 v6, v224, v225
	v_cvt_pk_bf16_f32 v7, v226, v227
	v_cvt_pk_bf16_f32 v8, v228, v229
	v_cvt_pk_bf16_f32 v9, v230, v231
	s_nop 0
	v_mfma_f32_16x16x32_bf16 v[132:135], v[2:5], v[64:67], v[132:135]
	v_mfma_f32_16x16x32_bf16 v[132:135], v[6:9], v[68:71], v[132:135]
	s_waitcnt vmcnt(16)
	ds_write_b128 v105, v[32:35]
	ds_write_b128 v106, v[36:39]
	ds_write_b128 v107, v[40:43]
	ds_write_b128 v108, v[44:47]
	global_load_dwordx4 v[32:35], v72, s[74:75]
	global_load_dwordx4 v[36:39], v73, s[74:75]
	global_load_dwordx4 v[40:43], v74, s[74:75]
	global_load_dwordx4 v[44:47], v75, s[74:75]
	s_add_u32 s74, s74, 0x40000
	s_addc_u32 s75, s75, 0
	ds_read_b128 v[216:219], v109
	ds_read_b128 v[220:223], v110
	ds_read_b128 v[224:227], v111
	ds_read_b128 v[228:231], v14
	ds_read_b128 v[136:139], v80 offset:3072
	s_waitcnt lgkmcnt(0)
	v_cvt_pk_bf16_f32 v2, v216, v217
	v_cvt_pk_bf16_f32 v3, v218, v219
	v_cvt_pk_bf16_f32 v4, v220, v221
	v_cvt_pk_bf16_f32 v5, v222, v223
	v_cvt_pk_bf16_f32 v6, v224, v225
	v_cvt_pk_bf16_f32 v7, v226, v227
	v_cvt_pk_bf16_f32 v8, v228, v229
	v_cvt_pk_bf16_f32 v9, v230, v231
	s_nop 0
	v_mfma_f32_16x16x32_bf16 v[136:139], v[2:5], v[64:67], v[136:139]
	v_mfma_f32_16x16x32_bf16 v[136:139], v[6:9], v[68:71], v[136:139]
	s_waitcnt vmcnt(16)
	ds_write_b128 v105, v[48:51]
	ds_write_b128 v106, v[52:55]
	ds_write_b128 v107, v[56:59]
	ds_write_b128 v108, v[60:63]
	global_load_dwordx4 v[48:51], v72, s[74:75]
	global_load_dwordx4 v[52:55], v73, s[74:75]
	global_load_dwordx4 v[56:59], v74, s[74:75]
	global_load_dwordx4 v[60:63], v75, s[74:75]
	s_add_u32 s74, s74, 0x40000
	s_addc_u32 s75, s75, 0
	ds_read_b128 v[216:219], v109
	ds_read_b128 v[220:223], v110
	ds_read_b128 v[224:227], v111
	ds_read_b128 v[228:231], v14
	ds_read_b128 v[140:143], v80 offset:3584
	s_waitcnt lgkmcnt(0)
	v_cvt_pk_bf16_f32 v2, v216, v217
	v_cvt_pk_bf16_f32 v3, v218, v219
	v_cvt_pk_bf16_f32 v4, v220, v221
	v_cvt_pk_bf16_f32 v5, v222, v223
	v_cvt_pk_bf16_f32 v6, v224, v225
	v_cvt_pk_bf16_f32 v7, v226, v227
	v_cvt_pk_bf16_f32 v8, v228, v229
	v_cvt_pk_bf16_f32 v9, v230, v231
	s_nop 0
	v_mfma_f32_16x16x32_bf16 v[140:143], v[2:5], v[64:67], v[140:143]
	v_mfma_f32_16x16x32_bf16 v[140:143], v[6:9], v[68:71], v[140:143]
	s_waitcnt vmcnt(16)
	ds_write_b128 v105, v[180:183]
	ds_write_b128 v106, v[184:187]
	ds_write_b128 v107, v[188:191]
	ds_write_b128 v108, v[192:195]
	global_load_dwordx4 v[180:183], v72, s[74:75]
	global_load_dwordx4 v[184:187], v73, s[74:75]
	global_load_dwordx4 v[188:191], v74, s[74:75]
	global_load_dwordx4 v[192:195], v75, s[74:75]
	s_add_u32 s74, s74, 0x40000
	s_addc_u32 s75, s75, 0
	ds_read_b128 v[216:219], v109
	ds_read_b128 v[220:223], v110
	ds_read_b128 v[224:227], v111
	ds_read_b128 v[228:231], v14
	ds_read_b128 v[144:147], v80 offset:4096
	s_waitcnt lgkmcnt(0)
	v_cvt_pk_bf16_f32 v2, v216, v217
	v_cvt_pk_bf16_f32 v3, v218, v219
	v_cvt_pk_bf16_f32 v4, v220, v221
	v_cvt_pk_bf16_f32 v5, v222, v223
	v_cvt_pk_bf16_f32 v6, v224, v225
	v_cvt_pk_bf16_f32 v7, v226, v227
	v_cvt_pk_bf16_f32 v8, v228, v229
	v_cvt_pk_bf16_f32 v9, v230, v231
	s_nop 0
	v_mfma_f32_16x16x32_bf16 v[144:147], v[2:5], v[64:67], v[144:147]
	v_mfma_f32_16x16x32_bf16 v[144:147], v[6:9], v[68:71], v[144:147]
	s_waitcnt vmcnt(16)
	ds_write_b128 v105, v[200:203]
	ds_write_b128 v106, v[204:207]
	ds_write_b128 v107, v[208:211]
	ds_write_b128 v108, v[212:215]
	global_load_dwordx4 v[200:203], v72, s[74:75]
	global_load_dwordx4 v[204:207], v73, s[74:75]
	global_load_dwordx4 v[208:211], v74, s[74:75]
	global_load_dwordx4 v[212:215], v75, s[74:75]
	s_add_u32 s74, s74, 0x40000
	s_addc_u32 s75, s75, 0
	ds_read_b128 v[216:219], v109
	ds_read_b128 v[220:223], v110
	ds_read_b128 v[224:227], v111
	ds_read_b128 v[228:231], v14
	ds_read_b128 v[148:151], v80 offset:4608
	s_waitcnt lgkmcnt(0)
	v_cvt_pk_bf16_f32 v2, v216, v217
	v_cvt_pk_bf16_f32 v3, v218, v219
	v_cvt_pk_bf16_f32 v4, v220, v221
	v_cvt_pk_bf16_f32 v5, v222, v223
	v_cvt_pk_bf16_f32 v6, v224, v225
	v_cvt_pk_bf16_f32 v7, v226, v227
	v_cvt_pk_bf16_f32 v8, v228, v229
	v_cvt_pk_bf16_f32 v9, v230, v231
	s_nop 0
	v_mfma_f32_16x16x32_bf16 v[148:151], v[2:5], v[64:67], v[148:151]
	v_mfma_f32_16x16x32_bf16 v[148:151], v[6:9], v[68:71], v[148:151]
	s_waitcnt vmcnt(16)
	ds_write_b128 v105, v[16:19]
	ds_write_b128 v106, v[20:23]
	ds_write_b128 v107, v[24:27]
	ds_write_b128 v108, v[28:31]
	global_load_dwordx4 v[16:19], v72, s[74:75]
	global_load_dwordx4 v[20:23], v73, s[74:75]
	global_load_dwordx4 v[24:27], v74, s[74:75]
	global_load_dwordx4 v[28:31], v75, s[74:75]
	s_add_u32 s74, s74, 0x40000
	s_addc_u32 s75, s75, 0
	ds_read_b128 v[216:219], v109
	ds_read_b128 v[220:223], v110
	ds_read_b128 v[224:227], v111
	ds_read_b128 v[228:231], v14
	ds_read_b128 v[152:155], v80 offset:5120
	s_waitcnt lgkmcnt(0)
	v_cvt_pk_bf16_f32 v2, v216, v217
	v_cvt_pk_bf16_f32 v3, v218, v219
	v_cvt_pk_bf16_f32 v4, v220, v221
	v_cvt_pk_bf16_f32 v5, v222, v223
	v_cvt_pk_bf16_f32 v6, v224, v225
	v_cvt_pk_bf16_f32 v7, v226, v227
	v_cvt_pk_bf16_f32 v8, v228, v229
	v_cvt_pk_bf16_f32 v9, v230, v231
	s_nop 0
	v_mfma_f32_16x16x32_bf16 v[152:155], v[2:5], v[64:67], v[152:155]
	v_mfma_f32_16x16x32_bf16 v[152:155], v[6:9], v[68:71], v[152:155]
	s_waitcnt vmcnt(16)
	ds_write_b128 v105, v[32:35]
	ds_write_b128 v106, v[36:39]
	ds_write_b128 v107, v[40:43]
	ds_write_b128 v108, v[44:47]
	ds_read_b128 v[216:219], v109
	ds_read_b128 v[220:223], v110
	ds_read_b128 v[224:227], v111
	ds_read_b128 v[228:231], v14
	ds_read_b128 v[156:159], v80 offset:5632
	s_waitcnt lgkmcnt(0)
	v_cvt_pk_bf16_f32 v2, v216, v217
	v_cvt_pk_bf16_f32 v3, v218, v219
	v_cvt_pk_bf16_f32 v4, v220, v221
	v_cvt_pk_bf16_f32 v5, v222, v223
	v_cvt_pk_bf16_f32 v6, v224, v225
	v_cvt_pk_bf16_f32 v7, v226, v227
	v_cvt_pk_bf16_f32 v8, v228, v229
	v_cvt_pk_bf16_f32 v9, v230, v231
	s_nop 0
	v_mfma_f32_16x16x32_bf16 v[156:159], v[2:5], v[64:67], v[156:159]
	v_mfma_f32_16x16x32_bf16 v[156:159], v[6:9], v[68:71], v[156:159]
	s_waitcnt vmcnt(12)
	ds_write_b128 v105, v[48:51]
	ds_write_b128 v106, v[52:55]
	ds_write_b128 v107, v[56:59]
	ds_write_b128 v108, v[60:63]
	ds_read_b128 v[216:219], v109
	ds_read_b128 v[220:223], v110
	ds_read_b128 v[224:227], v111
	ds_read_b128 v[228:231], v14
	ds_read_b128 v[160:163], v80 offset:6144
	s_waitcnt lgkmcnt(0)
	v_cvt_pk_bf16_f32 v2, v216, v217
	v_cvt_pk_bf16_f32 v3, v218, v219
	v_cvt_pk_bf16_f32 v4, v220, v221
	v_cvt_pk_bf16_f32 v5, v222, v223
	v_cvt_pk_bf16_f32 v6, v224, v225
	v_cvt_pk_bf16_f32 v7, v226, v227
	v_cvt_pk_bf16_f32 v8, v228, v229
	v_cvt_pk_bf16_f32 v9, v230, v231
	s_nop 0
	v_mfma_f32_16x16x32_bf16 v[160:163], v[2:5], v[64:67], v[160:163]
	v_mfma_f32_16x16x32_bf16 v[160:163], v[6:9], v[68:71], v[160:163]
	s_waitcnt vmcnt(8)
	ds_write_b128 v105, v[180:183]
	ds_write_b128 v106, v[184:187]
	ds_write_b128 v107, v[188:191]
	ds_write_b128 v108, v[192:195]
	ds_read_b128 v[216:219], v109
	ds_read_b128 v[220:223], v110
	ds_read_b128 v[224:227], v111
	ds_read_b128 v[228:231], v14
	ds_read_b128 v[164:167], v80 offset:6656
	s_waitcnt lgkmcnt(0)
	v_cvt_pk_bf16_f32 v2, v216, v217
	v_cvt_pk_bf16_f32 v3, v218, v219
	v_cvt_pk_bf16_f32 v4, v220, v221
	v_cvt_pk_bf16_f32 v5, v222, v223
	v_cvt_pk_bf16_f32 v6, v224, v225
	v_cvt_pk_bf16_f32 v7, v226, v227
	v_cvt_pk_bf16_f32 v8, v228, v229
	v_cvt_pk_bf16_f32 v9, v230, v231
	s_nop 0
	v_mfma_f32_16x16x32_bf16 v[164:167], v[2:5], v[64:67], v[164:167]
	v_mfma_f32_16x16x32_bf16 v[164:167], v[6:9], v[68:71], v[164:167]
	s_waitcnt vmcnt(4)
	ds_write_b128 v105, v[200:203]
	ds_write_b128 v106, v[204:207]
	ds_write_b128 v107, v[208:211]
	ds_write_b128 v108, v[212:215]
	ds_read_b128 v[216:219], v109
	ds_read_b128 v[220:223], v110
	ds_read_b128 v[224:227], v111
	ds_read_b128 v[228:231], v14
	ds_read_b128 v[168:171], v80 offset:7168
	s_waitcnt lgkmcnt(0)
	v_cvt_pk_bf16_f32 v2, v216, v217
	v_cvt_pk_bf16_f32 v3, v218, v219
	v_cvt_pk_bf16_f32 v4, v220, v221
	v_cvt_pk_bf16_f32 v5, v222, v223
	v_cvt_pk_bf16_f32 v6, v224, v225
	v_cvt_pk_bf16_f32 v7, v226, v227
	v_cvt_pk_bf16_f32 v8, v228, v229
	v_cvt_pk_bf16_f32 v9, v230, v231
	s_nop 0
	v_mfma_f32_16x16x32_bf16 v[168:171], v[2:5], v[64:67], v[168:171]
	v_mfma_f32_16x16x32_bf16 v[168:171], v[6:9], v[68:71], v[168:171]
	s_waitcnt vmcnt(0)
	ds_write_b128 v105, v[16:19]
	ds_write_b128 v106, v[20:23]
	ds_write_b128 v107, v[24:27]
	ds_write_b128 v108, v[28:31]
	ds_read_b128 v[216:219], v109
	ds_read_b128 v[220:223], v110
	ds_read_b128 v[224:227], v111
	ds_read_b128 v[228:231], v14
	ds_read_b128 v[172:175], v80 offset:7680
	s_waitcnt lgkmcnt(0)
	v_cvt_pk_bf16_f32 v2, v216, v217
	v_cvt_pk_bf16_f32 v3, v218, v219
	v_cvt_pk_bf16_f32 v4, v220, v221
	v_cvt_pk_bf16_f32 v5, v222, v223
	v_cvt_pk_bf16_f32 v6, v224, v225
	v_cvt_pk_bf16_f32 v7, v226, v227
	v_cvt_pk_bf16_f32 v8, v228, v229
	v_cvt_pk_bf16_f32 v9, v230, v231
	s_nop 0
	v_mfma_f32_16x16x32_bf16 v[172:175], v[2:5], v[64:67], v[172:175]
	v_mfma_f32_16x16x32_bf16 v[172:175], v[6:9], v[68:71], v[172:175]
	s_cmp_lg_u32 s72, 0
	s_cbranch_scc1 .Lsa_t16_skip
	v_mov_b32_e32 v15, 0x2010
	v_lshl_add_u32 v15, v76, 4, v15
	ds_write_b128 v105, v[232:235]
	ds_write_b128 v106, v[236:239]
	ds_write_b128 v107, v[240:243]
	ds_write_b128 v108, v[244:247]
	global_load_dwordx4 v[232:235], v72, s[84:85]
	global_load_dwordx4 v[236:239], v73, s[84:85]
	global_load_dwordx4 v[240:243], v74, s[84:85]
	global_load_dwordx4 v[244:247], v75, s[84:85]
	ds_read_b128 v[216:219], v109
	ds_read_b128 v[220:223], v110
	ds_read_b128 v[224:227], v111
	ds_read_b128 v[228:231], v14
	ds_read_b128 v[176:179], v15
	s_waitcnt lgkmcnt(0)
	v_cvt_pk_bf16_f32 v2, v216, v217
	v_cvt_pk_bf16_f32 v3, v218, v219
	v_cvt_pk_bf16_f32 v4, v220, v221
	v_cvt_pk_bf16_f32 v5, v222, v223
	v_cvt_pk_bf16_f32 v6, v224, v225
	v_cvt_pk_bf16_f32 v7, v226, v227
	v_cvt_pk_bf16_f32 v8, v228, v229
	v_cvt_pk_bf16_f32 v9, v230, v231
	s_nop 0
	v_mfma_f32_16x16x32_bf16 v[176:179], v[2:5], v[64:67], v[176:179]
	v_mfma_f32_16x16x32_bf16 v[176:179], v[6:9], v[68:71], v[176:179]
	v_lshlrev_b32_e32 v15, 2, v76
	s_nop 7
	s_nop 1
	v_add_u32_e32 v78, 0, v15
	v_cmp_gt_u32_e32 vcc, v78, v77
	s_nop 1
	v_cndmask_b32_e32 v176, v176, v101, vcc
	v_add_u32_e32 v78, 1, v15
	v_cmp_gt_u32_e32 vcc, v78, v77
	s_nop 1
	v_cndmask_b32_e32 v177, v177, v101, vcc
	v_add_u32_e32 v78, 2, v15
	v_cmp_gt_u32_e32 vcc, v78, v77
	s_nop 1
	v_cndmask_b32_e32 v178, v178, v101, vcc
	v_add_u32_e32 v78, 3, v15
	v_cmp_gt_u32_e32 vcc, v78, v77
	s_nop 1
	v_cndmask_b32_e32 v179, v179, v101, vcc
.Lsa_t16_skip:
	global_load_dwordx4 v[16:19], v72, s[76:77]
	global_load_dwordx4 v[20:23], v73, s[76:77]
	global_load_dwordx4 v[24:27], v74, s[76:77]
	global_load_dwordx4 v[28:31], v75, s[76:77]
	global_load_dwordx4 v[32:35], v72, s[78:79]
	global_load_dwordx4 v[36:39], v73, s[78:79]
	global_load_dwordx4 v[40:43], v74, s[78:79]
	global_load_dwordx4 v[44:47], v75, s[78:79]
	s_add_u32 s76, s76, 0x80000
	s_addc_u32 s77, s77, 0
	s_add_u32 s78, s78, 0x80000
	s_addc_u32 s79, s79, 0
	global_load_dwordx4 v[48:51], v72, s[76:77]
	global_load_dwordx4 v[52:55], v73, s[76:77]
	global_load_dwordx4 v[56:59], v74, s[76:77]
	global_load_dwordx4 v[60:63], v75, s[76:77]
	global_load_dwordx4 v[200:203], v72, s[78:79]
	global_load_dwordx4 v[204:207], v73, s[78:79]
	global_load_dwordx4 v[208:211], v74, s[78:79]
	global_load_dwordx4 v[212:215], v75, s[78:79]
	s_add_u32 s76, s76, 0x80000
	s_addc_u32 s77, s77, 0
	s_add_u32 s78, s78, 0x80000
	s_addc_u32 s79, s79, 0
	s_nop 7
	s_nop 1
	v_max3_f32 v248, v112, v113, v114
	v_max3_f32 v248, v248, v115, v116
	v_max3_f32 v248, v248, v117, v118
	v_max3_f32 v248, v248, v119, v120
	v_max3_f32 v248, v248, v121, v122
	v_max3_f32 v248, v248, v123, v124
	v_max3_f32 v248, v248, v125, v126
	v_max3_f32 v248, v248, v127, v128
	v_max3_f32 v248, v248, v129, v130
	v_max3_f32 v248, v248, v131, v132
	v_max3_f32 v248, v248, v133, v134
	v_max3_f32 v248, v248, v135, v136
	v_max3_f32 v248, v248, v137, v138
	v_max3_f32 v248, v248, v139, v140
	v_max3_f32 v248, v248, v141, v142
	v_max3_f32 v248, v248, v143, v144
	v_max3_f32 v248, v248, v145, v146
	v_max3_f32 v248, v248, v147, v148
	v_max3_f32 v248, v248, v149, v150
	v_max3_f32 v248, v248, v151, v152
	v_max3_f32 v248, v248, v153, v154
	v_max3_f32 v248, v248, v155, v156
	v_max3_f32 v248, v248, v157, v158
	v_max3_f32 v248, v248, v159, v160
	v_max3_f32 v248, v248, v161, v162
	v_max3_f32 v248, v248, v163, v164
	v_max3_f32 v248, v248, v165, v166
	v_max3_f32 v248, v248, v167, v168
	v_max3_f32 v248, v248, v169, v170
	v_max3_f32 v248, v248, v171, v172
	v_max3_f32 v248, v248, v173, v174
	v_max3_f32 v248, v248, v175, v176
	v_max3_f32 v248, v248, v177, v178
	v_max3_f32 v248, v248, v179, v179
	ds_write_b32 v81, v248 offset:49168
	v_lshlrev_b32_e32 v105, 2, v77
	v_add_u32_e32 v105, 0xc010, v105
	v_add_u32_e32 v106, 64, v105
	v_add_u32_e32 v107, 0x80, v105
	v_add_u32_e32 v108, 0xc0, v105
	s_waitcnt lgkmcnt(0)
	s_barrier
	ds_read2st64_b32 v[180:181], v105 offset0:0 offset1:1
	ds_read2st64_b32 v[182:183], v105 offset0:2 offset1:3
	ds_read2st64_b32 v[184:185], v105 offset0:4 offset1:5
	ds_read2st64_b32 v[186:187], v105 offset0:6 offset1:7
	ds_read2st64_b32 v[188:189], v106 offset0:0 offset1:1
	ds_read2st64_b32 v[190:191], v106 offset0:2 offset1:3
	ds_read2st64_b32 v[192:193], v106 offset0:4 offset1:5
	ds_read2st64_b32 v[194:195], v106 offset0:6 offset1:7
	ds_read2st64_b32 v[216:217], v107 offset0:0 offset1:1
	ds_read2st64_b32 v[218:219], v107 offset0:2 offset1:3
	ds_read2st64_b32 v[220:221], v107 offset0:4 offset1:5
	ds_read2st64_b32 v[222:223], v107 offset0:6 offset1:7
	ds_read2st64_b32 v[224:225], v108 offset0:0 offset1:1
	ds_read2st64_b32 v[226:227], v108 offset0:2 offset1:3
	ds_read2st64_b32 v[228:229], v108 offset0:4 offset1:5
	ds_read2st64_b32 v[230:231], v108 offset0:6 offset1:7
	s_waitcnt lgkmcnt(0)
	v_max3_f32 v248, v180, v181, v182
	v_max3_f32 v248, v248, v183, v184
	v_max3_f32 v248, v248, v185, v186
	v_max3_f32 v248, v248, v187, v188
	v_max3_f32 v248, v248, v189, v190
	v_max3_f32 v248, v248, v191, v192
	v_max3_f32 v248, v248, v193, v194
	v_max3_f32 v248, v248, v195, v216
	v_max3_f32 v248, v248, v217, v218
	v_max3_f32 v248, v248, v219, v220
	v_max3_f32 v248, v248, v221, v222
	v_max3_f32 v248, v248, v223, v224
	v_max3_f32 v248, v248, v225, v226
	v_max3_f32 v248, v248, v227, v228
	v_max3_f32 v248, v248, v229, v230
	v_max3_f32 v248, v248, v231, v231
	v_mov_b32_e32 v249, 0
	v_sub_f32_e32 v112, v112, v248
	v_sub_f32_e32 v113, v113, v248
	v_sub_f32_e32 v114, v114, v248
	v_sub_f32_e32 v115, v115, v248
	v_cmp_gt_f32_e64 s[24:25], s61, v112
	v_cmp_gt_f32_e64 s[26:27], s61, v113
	v_cmp_gt_f32_e64 s[28:29], s61, v114
	v_cmp_gt_f32_e64 s[34:35], s61, v115
	v_cndmask_b32_e64 v180, 0, v102, s[24:25]
	v_cndmask_b32_e64 v181, 0, v102, s[26:27]
	v_cndmask_b32_e64 v182, 0, v102, s[28:29]
	v_cndmask_b32_e64 v183, 0, v102, s[34:35]
	v_add_f32_e32 v112, v112, v180
	v_add_f32_e32 v113, v113, v181
	v_add_f32_e32 v114, v114, v182
	v_add_f32_e32 v115, v115, v183
	v_exp_f32_e32 v112, v112
	v_exp_f32_e32 v113, v113
	v_exp_f32_e32 v114, v114
	v_exp_f32_e32 v115, v115
	v_cndmask_b32_e64 v180, 0, v103, s[24:25]
	v_cndmask_b32_e64 v181, 0, v103, s[26:27]
	v_cndmask_b32_e64 v182, 0, v103, s[28:29]
	v_cndmask_b32_e64 v183, 0, v103, s[34:35]
	v_ldexp_f32 v112, v112, v180
	v_ldexp_f32 v113, v113, v181
	v_ldexp_f32 v114, v114, v182
	v_ldexp_f32 v115, v115, v183
	v_add_f32_e32 v249, v249, v112
	v_add_f32_e32 v249, v249, v113
	v_add_f32_e32 v249, v249, v114
	v_add_f32_e32 v249, v249, v115
	v_sub_f32_e32 v116, v116, v248
	v_sub_f32_e32 v117, v117, v248
	v_sub_f32_e32 v118, v118, v248
	v_sub_f32_e32 v119, v119, v248
	v_cmp_gt_f32_e64 s[24:25], s61, v116
	v_cmp_gt_f32_e64 s[26:27], s61, v117
	v_cmp_gt_f32_e64 s[28:29], s61, v118
	v_cmp_gt_f32_e64 s[34:35], s61, v119
	v_cndmask_b32_e64 v180, 0, v102, s[24:25]
	v_cndmask_b32_e64 v181, 0, v102, s[26:27]
	v_cndmask_b32_e64 v182, 0, v102, s[28:29]
	v_cndmask_b32_e64 v183, 0, v102, s[34:35]
	v_add_f32_e32 v116, v116, v180
	v_add_f32_e32 v117, v117, v181
	v_add_f32_e32 v118, v118, v182
	v_add_f32_e32 v119, v119, v183
	v_exp_f32_e32 v116, v116
	v_exp_f32_e32 v117, v117
	v_exp_f32_e32 v118, v118
	v_exp_f32_e32 v119, v119
	v_cndmask_b32_e64 v180, 0, v103, s[24:25]
	v_cndmask_b32_e64 v181, 0, v103, s[26:27]
	v_cndmask_b32_e64 v182, 0, v103, s[28:29]
	v_cndmask_b32_e64 v183, 0, v103, s[34:35]
	v_ldexp_f32 v116, v116, v180
	v_ldexp_f32 v117, v117, v181
	v_ldexp_f32 v118, v118, v182
	v_ldexp_f32 v119, v119, v183
	v_add_f32_e32 v249, v249, v116
	v_add_f32_e32 v249, v249, v117
	v_add_f32_e32 v249, v249, v118
	v_add_f32_e32 v249, v249, v119
	v_sub_f32_e32 v120, v120, v248
	v_sub_f32_e32 v121, v121, v248
	v_sub_f32_e32 v122, v122, v248
	v_sub_f32_e32 v123, v123, v248
	v_cmp_gt_f32_e64 s[24:25], s61, v120
	v_cmp_gt_f32_e64 s[26:27], s61, v121
	v_cmp_gt_f32_e64 s[28:29], s61, v122
	v_cmp_gt_f32_e64 s[34:35], s61, v123
	v_cndmask_b32_e64 v180, 0, v102, s[24:25]
	v_cndmask_b32_e64 v181, 0, v102, s[26:27]
	v_cndmask_b32_e64 v182, 0, v102, s[28:29]
	v_cndmask_b32_e64 v183, 0, v102, s[34:35]
	v_add_f32_e32 v120, v120, v180
	v_add_f32_e32 v121, v121, v181
	v_add_f32_e32 v122, v122, v182
	v_add_f32_e32 v123, v123, v183
	v_exp_f32_e32 v120, v120
	v_exp_f32_e32 v121, v121
	v_exp_f32_e32 v122, v122
	v_exp_f32_e32 v123, v123
	v_cndmask_b32_e64 v180, 0, v103, s[24:25]
	v_cndmask_b32_e64 v181, 0, v103, s[26:27]
	v_cndmask_b32_e64 v182, 0, v103, s[28:29]
	v_cndmask_b32_e64 v183, 0, v103, s[34:35]
	v_ldexp_f32 v120, v120, v180
	v_ldexp_f32 v121, v121, v181
	v_ldexp_f32 v122, v122, v182
	v_ldexp_f32 v123, v123, v183
	v_add_f32_e32 v249, v249, v120
	v_add_f32_e32 v249, v249, v121
	v_add_f32_e32 v249, v249, v122
	v_add_f32_e32 v249, v249, v123
	v_sub_f32_e32 v124, v124, v248
	v_sub_f32_e32 v125, v125, v248
	v_sub_f32_e32 v126, v126, v248
	v_sub_f32_e32 v127, v127, v248
	v_cmp_gt_f32_e64 s[24:25], s61, v124
	v_cmp_gt_f32_e64 s[26:27], s61, v125
	v_cmp_gt_f32_e64 s[28:29], s61, v126
	v_cmp_gt_f32_e64 s[34:35], s61, v127
	v_cndmask_b32_e64 v180, 0, v102, s[24:25]
	v_cndmask_b32_e64 v181, 0, v102, s[26:27]
	v_cndmask_b32_e64 v182, 0, v102, s[28:29]
	v_cndmask_b32_e64 v183, 0, v102, s[34:35]
	v_add_f32_e32 v124, v124, v180
	v_add_f32_e32 v125, v125, v181
	v_add_f32_e32 v126, v126, v182
	v_add_f32_e32 v127, v127, v183
	v_exp_f32_e32 v124, v124
	v_exp_f32_e32 v125, v125
	v_exp_f32_e32 v126, v126
	v_exp_f32_e32 v127, v127
	v_cndmask_b32_e64 v180, 0, v103, s[24:25]
	v_cndmask_b32_e64 v181, 0, v103, s[26:27]
	v_cndmask_b32_e64 v182, 0, v103, s[28:29]
	v_cndmask_b32_e64 v183, 0, v103, s[34:35]
	v_ldexp_f32 v124, v124, v180
	v_ldexp_f32 v125, v125, v181
	v_ldexp_f32 v126, v126, v182
	v_ldexp_f32 v127, v127, v183
	v_add_f32_e32 v249, v249, v124
	v_add_f32_e32 v249, v249, v125
	v_add_f32_e32 v249, v249, v126
	v_add_f32_e32 v249, v249, v127
	v_sub_f32_e32 v128, v128, v248
	v_sub_f32_e32 v129, v129, v248
	v_sub_f32_e32 v130, v130, v248
	v_sub_f32_e32 v131, v131, v248
	v_cmp_gt_f32_e64 s[24:25], s61, v128
	v_cmp_gt_f32_e64 s[26:27], s61, v129
	v_cmp_gt_f32_e64 s[28:29], s61, v130
	v_cmp_gt_f32_e64 s[34:35], s61, v131
	v_cndmask_b32_e64 v180, 0, v102, s[24:25]
	v_cndmask_b32_e64 v181, 0, v102, s[26:27]
	v_cndmask_b32_e64 v182, 0, v102, s[28:29]
	v_cndmask_b32_e64 v183, 0, v102, s[34:35]
	v_add_f32_e32 v128, v128, v180
	v_add_f32_e32 v129, v129, v181
	v_add_f32_e32 v130, v130, v182
	v_add_f32_e32 v131, v131, v183
	v_exp_f32_e32 v128, v128
	v_exp_f32_e32 v129, v129
	v_exp_f32_e32 v130, v130
	v_exp_f32_e32 v131, v131
	v_cndmask_b32_e64 v180, 0, v103, s[24:25]
	v_cndmask_b32_e64 v181, 0, v103, s[26:27]
	v_cndmask_b32_e64 v182, 0, v103, s[28:29]
	v_cndmask_b32_e64 v183, 0, v103, s[34:35]
	v_ldexp_f32 v128, v128, v180
	v_ldexp_f32 v129, v129, v181
	v_ldexp_f32 v130, v130, v182
	v_ldexp_f32 v131, v131, v183
	v_add_f32_e32 v249, v249, v128
	v_add_f32_e32 v249, v249, v129
	v_add_f32_e32 v249, v249, v130
	v_add_f32_e32 v249, v249, v131
	v_sub_f32_e32 v132, v132, v248
	v_sub_f32_e32 v133, v133, v248
	v_sub_f32_e32 v134, v134, v248
	v_sub_f32_e32 v135, v135, v248
	v_cmp_gt_f32_e64 s[24:25], s61, v132
	v_cmp_gt_f32_e64 s[26:27], s61, v133
	v_cmp_gt_f32_e64 s[28:29], s61, v134
	v_cmp_gt_f32_e64 s[34:35], s61, v135
	v_cndmask_b32_e64 v180, 0, v102, s[24:25]
	v_cndmask_b32_e64 v181, 0, v102, s[26:27]
	v_cndmask_b32_e64 v182, 0, v102, s[28:29]
	v_cndmask_b32_e64 v183, 0, v102, s[34:35]
	v_add_f32_e32 v132, v132, v180
	v_add_f32_e32 v133, v133, v181
	v_add_f32_e32 v134, v134, v182
	v_add_f32_e32 v135, v135, v183
	v_exp_f32_e32 v132, v132
	v_exp_f32_e32 v133, v133
	v_exp_f32_e32 v134, v134
	v_exp_f32_e32 v135, v135
	v_cndmask_b32_e64 v180, 0, v103, s[24:25]
	v_cndmask_b32_e64 v181, 0, v103, s[26:27]
	v_cndmask_b32_e64 v182, 0, v103, s[28:29]
	v_cndmask_b32_e64 v183, 0, v103, s[34:35]
	v_ldexp_f32 v132, v132, v180
	v_ldexp_f32 v133, v133, v181
	v_ldexp_f32 v134, v134, v182
	v_ldexp_f32 v135, v135, v183
	v_add_f32_e32 v249, v249, v132
	v_add_f32_e32 v249, v249, v133
	v_add_f32_e32 v249, v249, v134
	v_add_f32_e32 v249, v249, v135
	v_sub_f32_e32 v136, v136, v248
	v_sub_f32_e32 v137, v137, v248
	v_sub_f32_e32 v138, v138, v248
	v_sub_f32_e32 v139, v139, v248
	v_cmp_gt_f32_e64 s[24:25], s61, v136
	v_cmp_gt_f32_e64 s[26:27], s61, v137
	v_cmp_gt_f32_e64 s[28:29], s61, v138
	v_cmp_gt_f32_e64 s[34:35], s61, v139
	v_cndmask_b32_e64 v180, 0, v102, s[24:25]
	v_cndmask_b32_e64 v181, 0, v102, s[26:27]
	v_cndmask_b32_e64 v182, 0, v102, s[28:29]
	v_cndmask_b32_e64 v183, 0, v102, s[34:35]
	v_add_f32_e32 v136, v136, v180
	v_add_f32_e32 v137, v137, v181
	v_add_f32_e32 v138, v138, v182
	v_add_f32_e32 v139, v139, v183
	v_exp_f32_e32 v136, v136
	v_exp_f32_e32 v137, v137
	v_exp_f32_e32 v138, v138
	v_exp_f32_e32 v139, v139
	v_cndmask_b32_e64 v180, 0, v103, s[24:25]
	v_cndmask_b32_e64 v181, 0, v103, s[26:27]
	v_cndmask_b32_e64 v182, 0, v103, s[28:29]
	v_cndmask_b32_e64 v183, 0, v103, s[34:35]
	v_ldexp_f32 v136, v136, v180
	v_ldexp_f32 v137, v137, v181
	v_ldexp_f32 v138, v138, v182
	v_ldexp_f32 v139, v139, v183
	v_add_f32_e32 v249, v249, v136
	v_add_f32_e32 v249, v249, v137
	v_add_f32_e32 v249, v249, v138
	v_add_f32_e32 v249, v249, v139
	v_sub_f32_e32 v140, v140, v248
	v_sub_f32_e32 v141, v141, v248
	v_sub_f32_e32 v142, v142, v248
	v_sub_f32_e32 v143, v143, v248
	v_cmp_gt_f32_e64 s[24:25], s61, v140
	v_cmp_gt_f32_e64 s[26:27], s61, v141
	v_cmp_gt_f32_e64 s[28:29], s61, v142
	v_cmp_gt_f32_e64 s[34:35], s61, v143
	v_cndmask_b32_e64 v180, 0, v102, s[24:25]
	v_cndmask_b32_e64 v181, 0, v102, s[26:27]
	v_cndmask_b32_e64 v182, 0, v102, s[28:29]
	v_cndmask_b32_e64 v183, 0, v102, s[34:35]
	v_add_f32_e32 v140, v140, v180
	v_add_f32_e32 v141, v141, v181
	v_add_f32_e32 v142, v142, v182
	v_add_f32_e32 v143, v143, v183
	v_exp_f32_e32 v140, v140
	v_exp_f32_e32 v141, v141
	v_exp_f32_e32 v142, v142
	v_exp_f32_e32 v143, v143
	v_cndmask_b32_e64 v180, 0, v103, s[24:25]
	v_cndmask_b32_e64 v181, 0, v103, s[26:27]
	v_cndmask_b32_e64 v182, 0, v103, s[28:29]
	v_cndmask_b32_e64 v183, 0, v103, s[34:35]
	v_ldexp_f32 v140, v140, v180
	v_ldexp_f32 v141, v141, v181
	v_ldexp_f32 v142, v142, v182
	v_ldexp_f32 v143, v143, v183
	v_add_f32_e32 v249, v249, v140
	v_add_f32_e32 v249, v249, v141
	v_add_f32_e32 v249, v249, v142
	v_add_f32_e32 v249, v249, v143
	v_sub_f32_e32 v144, v144, v248
	v_sub_f32_e32 v145, v145, v248
	v_sub_f32_e32 v146, v146, v248
	v_sub_f32_e32 v147, v147, v248
	v_cmp_gt_f32_e64 s[24:25], s61, v144
	v_cmp_gt_f32_e64 s[26:27], s61, v145
	v_cmp_gt_f32_e64 s[28:29], s61, v146
	v_cmp_gt_f32_e64 s[34:35], s61, v147
	v_cndmask_b32_e64 v180, 0, v102, s[24:25]
	v_cndmask_b32_e64 v181, 0, v102, s[26:27]
	v_cndmask_b32_e64 v182, 0, v102, s[28:29]
	v_cndmask_b32_e64 v183, 0, v102, s[34:35]
	v_add_f32_e32 v144, v144, v180
	v_add_f32_e32 v145, v145, v181
	v_add_f32_e32 v146, v146, v182
	v_add_f32_e32 v147, v147, v183
	v_exp_f32_e32 v144, v144
	v_exp_f32_e32 v145, v145
	v_exp_f32_e32 v146, v146
	v_exp_f32_e32 v147, v147
	v_cndmask_b32_e64 v180, 0, v103, s[24:25]
	v_cndmask_b32_e64 v181, 0, v103, s[26:27]
	v_cndmask_b32_e64 v182, 0, v103, s[28:29]
	v_cndmask_b32_e64 v183, 0, v103, s[34:35]
	v_ldexp_f32 v144, v144, v180
	v_ldexp_f32 v145, v145, v181
	v_ldexp_f32 v146, v146, v182
	v_ldexp_f32 v147, v147, v183
	v_add_f32_e32 v249, v249, v144
	v_add_f32_e32 v249, v249, v145
	v_add_f32_e32 v249, v249, v146
	v_add_f32_e32 v249, v249, v147
	v_sub_f32_e32 v148, v148, v248
	v_sub_f32_e32 v149, v149, v248
	v_sub_f32_e32 v150, v150, v248
	v_sub_f32_e32 v151, v151, v248
	v_cmp_gt_f32_e64 s[24:25], s61, v148
	v_cmp_gt_f32_e64 s[26:27], s61, v149
	v_cmp_gt_f32_e64 s[28:29], s61, v150
	v_cmp_gt_f32_e64 s[34:35], s61, v151
	v_cndmask_b32_e64 v180, 0, v102, s[24:25]
	v_cndmask_b32_e64 v181, 0, v102, s[26:27]
	v_cndmask_b32_e64 v182, 0, v102, s[28:29]
	v_cndmask_b32_e64 v183, 0, v102, s[34:35]
	v_add_f32_e32 v148, v148, v180
	v_add_f32_e32 v149, v149, v181
	v_add_f32_e32 v150, v150, v182
	v_add_f32_e32 v151, v151, v183
	v_exp_f32_e32 v148, v148
	v_exp_f32_e32 v149, v149
	v_exp_f32_e32 v150, v150
	v_exp_f32_e32 v151, v151
	v_cndmask_b32_e64 v180, 0, v103, s[24:25]
	v_cndmask_b32_e64 v181, 0, v103, s[26:27]
	v_cndmask_b32_e64 v182, 0, v103, s[28:29]
	v_cndmask_b32_e64 v183, 0, v103, s[34:35]
	v_ldexp_f32 v148, v148, v180
	v_ldexp_f32 v149, v149, v181
	v_ldexp_f32 v150, v150, v182
	v_ldexp_f32 v151, v151, v183
	v_add_f32_e32 v249, v249, v148
	v_add_f32_e32 v249, v249, v149
	v_add_f32_e32 v249, v249, v150
	v_add_f32_e32 v249, v249, v151
	v_sub_f32_e32 v152, v152, v248
	v_sub_f32_e32 v153, v153, v248
	v_sub_f32_e32 v154, v154, v248
	v_sub_f32_e32 v155, v155, v248
	v_cmp_gt_f32_e64 s[24:25], s61, v152
	v_cmp_gt_f32_e64 s[26:27], s61, v153
	v_cmp_gt_f32_e64 s[28:29], s61, v154
	v_cmp_gt_f32_e64 s[34:35], s61, v155
	v_cndmask_b32_e64 v180, 0, v102, s[24:25]
	v_cndmask_b32_e64 v181, 0, v102, s[26:27]
	v_cndmask_b32_e64 v182, 0, v102, s[28:29]
	v_cndmask_b32_e64 v183, 0, v102, s[34:35]
	v_add_f32_e32 v152, v152, v180
	v_add_f32_e32 v153, v153, v181
	v_add_f32_e32 v154, v154, v182
	v_add_f32_e32 v155, v155, v183
	v_exp_f32_e32 v152, v152
	v_exp_f32_e32 v153, v153
	v_exp_f32_e32 v154, v154
	v_exp_f32_e32 v155, v155
	v_cndmask_b32_e64 v180, 0, v103, s[24:25]
	v_cndmask_b32_e64 v181, 0, v103, s[26:27]
	v_cndmask_b32_e64 v182, 0, v103, s[28:29]
	v_cndmask_b32_e64 v183, 0, v103, s[34:35]
	v_ldexp_f32 v152, v152, v180
	v_ldexp_f32 v153, v153, v181
	v_ldexp_f32 v154, v154, v182
	v_ldexp_f32 v155, v155, v183
	v_add_f32_e32 v249, v249, v152
	v_add_f32_e32 v249, v249, v153
	v_add_f32_e32 v249, v249, v154
	v_add_f32_e32 v249, v249, v155
	v_sub_f32_e32 v156, v156, v248
	v_sub_f32_e32 v157, v157, v248
	v_sub_f32_e32 v158, v158, v248
	v_sub_f32_e32 v159, v159, v248
	v_cmp_gt_f32_e64 s[24:25], s61, v156
	v_cmp_gt_f32_e64 s[26:27], s61, v157
	v_cmp_gt_f32_e64 s[28:29], s61, v158
	v_cmp_gt_f32_e64 s[34:35], s61, v159
	v_cndmask_b32_e64 v180, 0, v102, s[24:25]
	v_cndmask_b32_e64 v181, 0, v102, s[26:27]
	v_cndmask_b32_e64 v182, 0, v102, s[28:29]
	v_cndmask_b32_e64 v183, 0, v102, s[34:35]
	v_add_f32_e32 v156, v156, v180
	v_add_f32_e32 v157, v157, v181
	v_add_f32_e32 v158, v158, v182
	v_add_f32_e32 v159, v159, v183
	v_exp_f32_e32 v156, v156
	v_exp_f32_e32 v157, v157
	v_exp_f32_e32 v158, v158
	v_exp_f32_e32 v159, v159
	v_cndmask_b32_e64 v180, 0, v103, s[24:25]
	v_cndmask_b32_e64 v181, 0, v103, s[26:27]
	v_cndmask_b32_e64 v182, 0, v103, s[28:29]
	v_cndmask_b32_e64 v183, 0, v103, s[34:35]
	v_ldexp_f32 v156, v156, v180
	v_ldexp_f32 v157, v157, v181
	v_ldexp_f32 v158, v158, v182
	v_ldexp_f32 v159, v159, v183
	v_add_f32_e32 v249, v249, v156
	v_add_f32_e32 v249, v249, v157
	v_add_f32_e32 v249, v249, v158
	v_add_f32_e32 v249, v249, v159
	v_sub_f32_e32 v160, v160, v248
	v_sub_f32_e32 v161, v161, v248
	v_sub_f32_e32 v162, v162, v248
	v_sub_f32_e32 v163, v163, v248
	v_cmp_gt_f32_e64 s[24:25], s61, v160
	v_cmp_gt_f32_e64 s[26:27], s61, v161
	v_cmp_gt_f32_e64 s[28:29], s61, v162
	v_cmp_gt_f32_e64 s[34:35], s61, v163
	v_cndmask_b32_e64 v180, 0, v102, s[24:25]
	v_cndmask_b32_e64 v181, 0, v102, s[26:27]
	v_cndmask_b32_e64 v182, 0, v102, s[28:29]
	v_cndmask_b32_e64 v183, 0, v102, s[34:35]
	v_add_f32_e32 v160, v160, v180
	v_add_f32_e32 v161, v161, v181
	v_add_f32_e32 v162, v162, v182
	v_add_f32_e32 v163, v163, v183
	v_exp_f32_e32 v160, v160
	v_exp_f32_e32 v161, v161
	v_exp_f32_e32 v162, v162
	v_exp_f32_e32 v163, v163
	v_cndmask_b32_e64 v180, 0, v103, s[24:25]
	v_cndmask_b32_e64 v181, 0, v103, s[26:27]
	v_cndmask_b32_e64 v182, 0, v103, s[28:29]
	v_cndmask_b32_e64 v183, 0, v103, s[34:35]
	v_ldexp_f32 v160, v160, v180
	v_ldexp_f32 v161, v161, v181
	v_ldexp_f32 v162, v162, v182
	v_ldexp_f32 v163, v163, v183
	v_add_f32_e32 v249, v249, v160
	v_add_f32_e32 v249, v249, v161
	v_add_f32_e32 v249, v249, v162
	v_add_f32_e32 v249, v249, v163
	v_sub_f32_e32 v164, v164, v248
	v_sub_f32_e32 v165, v165, v248
	v_sub_f32_e32 v166, v166, v248
	v_sub_f32_e32 v167, v167, v248
	v_cmp_gt_f32_e64 s[24:25], s61, v164
	v_cmp_gt_f32_e64 s[26:27], s61, v165
	v_cmp_gt_f32_e64 s[28:29], s61, v166
	v_cmp_gt_f32_e64 s[34:35], s61, v167
	v_cndmask_b32_e64 v180, 0, v102, s[24:25]
	v_cndmask_b32_e64 v181, 0, v102, s[26:27]
	v_cndmask_b32_e64 v182, 0, v102, s[28:29]
	v_cndmask_b32_e64 v183, 0, v102, s[34:35]
	v_add_f32_e32 v164, v164, v180
	v_add_f32_e32 v165, v165, v181
	v_add_f32_e32 v166, v166, v182
	v_add_f32_e32 v167, v167, v183
	v_exp_f32_e32 v164, v164
	v_exp_f32_e32 v165, v165
	v_exp_f32_e32 v166, v166
	v_exp_f32_e32 v167, v167
	v_cndmask_b32_e64 v180, 0, v103, s[24:25]
	v_cndmask_b32_e64 v181, 0, v103, s[26:27]
	v_cndmask_b32_e64 v182, 0, v103, s[28:29]
	v_cndmask_b32_e64 v183, 0, v103, s[34:35]
	v_ldexp_f32 v164, v164, v180
	v_ldexp_f32 v165, v165, v181
	v_ldexp_f32 v166, v166, v182
	v_ldexp_f32 v167, v167, v183
	v_add_f32_e32 v249, v249, v164
	v_add_f32_e32 v249, v249, v165
	v_add_f32_e32 v249, v249, v166
	v_add_f32_e32 v249, v249, v167
	v_sub_f32_e32 v168, v168, v248
	v_sub_f32_e32 v169, v169, v248
	v_sub_f32_e32 v170, v170, v248
	v_sub_f32_e32 v171, v171, v248
	v_cmp_gt_f32_e64 s[24:25], s61, v168
	v_cmp_gt_f32_e64 s[26:27], s61, v169
	v_cmp_gt_f32_e64 s[28:29], s61, v170
	v_cmp_gt_f32_e64 s[34:35], s61, v171
	v_cndmask_b32_e64 v180, 0, v102, s[24:25]
	v_cndmask_b32_e64 v181, 0, v102, s[26:27]
	v_cndmask_b32_e64 v182, 0, v102, s[28:29]
	v_cndmask_b32_e64 v183, 0, v102, s[34:35]
	v_add_f32_e32 v168, v168, v180
	v_add_f32_e32 v169, v169, v181
	v_add_f32_e32 v170, v170, v182
	v_add_f32_e32 v171, v171, v183
	v_exp_f32_e32 v168, v168
	v_exp_f32_e32 v169, v169
	v_exp_f32_e32 v170, v170
	v_exp_f32_e32 v171, v171
	v_cndmask_b32_e64 v180, 0, v103, s[24:25]
	v_cndmask_b32_e64 v181, 0, v103, s[26:27]
	v_cndmask_b32_e64 v182, 0, v103, s[28:29]
	v_cndmask_b32_e64 v183, 0, v103, s[34:35]
	v_ldexp_f32 v168, v168, v180
	v_ldexp_f32 v169, v169, v181
	v_ldexp_f32 v170, v170, v182
	v_ldexp_f32 v171, v171, v183
	v_add_f32_e32 v249, v249, v168
	v_add_f32_e32 v249, v249, v169
	v_add_f32_e32 v249, v249, v170
	v_add_f32_e32 v249, v249, v171
	v_sub_f32_e32 v172, v172, v248
	v_sub_f32_e32 v173, v173, v248
	v_sub_f32_e32 v174, v174, v248
	v_sub_f32_e32 v175, v175, v248
	v_cmp_gt_f32_e64 s[24:25], s61, v172
	v_cmp_gt_f32_e64 s[26:27], s61, v173
	v_cmp_gt_f32_e64 s[28:29], s61, v174
	v_cmp_gt_f32_e64 s[34:35], s61, v175
	v_cndmask_b32_e64 v180, 0, v102, s[24:25]
	v_cndmask_b32_e64 v181, 0, v102, s[26:27]
	v_cndmask_b32_e64 v182, 0, v102, s[28:29]
	v_cndmask_b32_e64 v183, 0, v102, s[34:35]
	v_add_f32_e32 v172, v172, v180
	v_add_f32_e32 v173, v173, v181
	v_add_f32_e32 v174, v174, v182
	v_add_f32_e32 v175, v175, v183
	v_exp_f32_e32 v172, v172
	v_exp_f32_e32 v173, v173
	v_exp_f32_e32 v174, v174
	v_exp_f32_e32 v175, v175
	v_cndmask_b32_e64 v180, 0, v103, s[24:25]
	v_cndmask_b32_e64 v181, 0, v103, s[26:27]
	v_cndmask_b32_e64 v182, 0, v103, s[28:29]
	v_cndmask_b32_e64 v183, 0, v103, s[34:35]
	v_ldexp_f32 v172, v172, v180
	v_ldexp_f32 v173, v173, v181
	v_ldexp_f32 v174, v174, v182
	v_ldexp_f32 v175, v175, v183
	v_add_f32_e32 v249, v249, v172
	v_add_f32_e32 v249, v249, v173
	v_add_f32_e32 v249, v249, v174
	v_add_f32_e32 v249, v249, v175
	v_sub_f32_e32 v176, v176, v248
	v_sub_f32_e32 v177, v177, v248
	v_sub_f32_e32 v178, v178, v248
	v_sub_f32_e32 v179, v179, v248
	v_cmp_gt_f32_e64 s[24:25], s61, v176
	v_cmp_gt_f32_e64 s[26:27], s61, v177
	v_cmp_gt_f32_e64 s[28:29], s61, v178
	v_cmp_gt_f32_e64 s[34:35], s61, v179
	v_cndmask_b32_e64 v180, 0, v102, s[24:25]
	v_cndmask_b32_e64 v181, 0, v102, s[26:27]
	v_cndmask_b32_e64 v182, 0, v102, s[28:29]
	v_cndmask_b32_e64 v183, 0, v102, s[34:35]
	v_add_f32_e32 v176, v176, v180
	v_add_f32_e32 v177, v177, v181
	v_add_f32_e32 v178, v178, v182
	v_add_f32_e32 v179, v179, v183
	v_exp_f32_e32 v176, v176
	v_exp_f32_e32 v177, v177
	v_exp_f32_e32 v178, v178
	v_exp_f32_e32 v179, v179
	v_cndmask_b32_e64 v180, 0, v103, s[24:25]
	v_cndmask_b32_e64 v181, 0, v103, s[26:27]
	v_cndmask_b32_e64 v182, 0, v103, s[28:29]
	v_cndmask_b32_e64 v183, 0, v103, s[34:35]
	v_ldexp_f32 v176, v176, v180
	v_ldexp_f32 v177, v177, v181
	v_ldexp_f32 v178, v178, v182
	v_ldexp_f32 v179, v179, v183
	v_add_f32_e32 v249, v249, v176
	v_add_f32_e32 v249, v249, v177
	v_add_f32_e32 v249, v249, v178
	v_add_f32_e32 v249, v249, v179
	ds_write_b32 v81, v249 offset:51216
	v_mov_b32_e32 v180, 0
	v_mov_b32_e32 v181, 0
	v_mov_b32_e32 v182, 0
	v_mov_b32_e32 v183, 0
	v_mov_b32_e32 v184, 0
	v_mov_b32_e32 v185, 0
	v_mov_b32_e32 v186, 0
	v_mov_b32_e32 v187, 0
	v_mov_b32_e32 v188, 0
	v_mov_b32_e32 v189, 0
	v_mov_b32_e32 v190, 0
	v_mov_b32_e32 v191, 0
	v_mov_b32_e32 v192, 0
	v_mov_b32_e32 v193, 0
	v_mov_b32_e32 v194, 0
	v_mov_b32_e32 v195, 0
	v_and_b32_e32 v15, 63, v0
	v_lshlrev_b32_e32 v15, 4, v15
	v_add_u32_e32 v105, s73, v15
	v_xor_b32_e32 v106, 64, v105
	v_lshlrev_b32_e32 v15, 10, v76
	v_lshl_add_u32 v15, v77, 2, v15
	v_and_b32_e32 v78, 1, v76
	v_lshl_add_u32 v15, v78, 6, v15
	v_add_u32_e32 v109, s73, v15
	v_xor_b32_e32 v110, 64, v109
	v_add_u32_e32 v111, 0x80, v109
	v_add_u32_e32 v14, 0x80, v110
	s_waitcnt vmcnt(8)
	ds_write_b128 v105, v[16:19]
	ds_write_b128 v106, v[20:23] offset:1024
	ds_write_b128 v105, v[24:27] offset:2048
	ds_write_b128 v106, v[28:31] offset:3072
	ds_write_b128 v105, v[32:35] offset:4096
	ds_write_b128 v106, v[36:39] offset:5120
	ds_write_b128 v105, v[40:43] offset:6144
	ds_write_b128 v106, v[44:47] offset:7168
	global_load_dwordx4 v[16:19], v72, s[76:77]
	global_load_dwordx4 v[20:23], v73, s[76:77]
	global_load_dwordx4 v[24:27], v74, s[76:77]
	global_load_dwordx4 v[28:31], v75, s[76:77]
	global_load_dwordx4 v[32:35], v72, s[78:79]
	global_load_dwordx4 v[36:39], v73, s[78:79]
	global_load_dwordx4 v[40:43], v74, s[78:79]
	global_load_dwordx4 v[44:47], v75, s[78:79]
	s_add_u32 s76, s76, 0x80000
	s_addc_u32 s77, s77, 0
	s_add_u32 s78, s78, 0x80000
	s_addc_u32 s79, s79, 0
	v_cvt_pk_bf16_f32 v10, v112, v113
	v_cvt_pk_bf16_f32 v11, v114, v115
	v_cvt_pk_bf16_f32 v12, v116, v117
	v_cvt_pk_bf16_f32 v13, v118, v119
	ds_read2st64_b32 v[2:3], v109 offset0:0 offset1:1
	ds_read2st64_b32 v[4:5], v109 offset0:2 offset1:3
	ds_read2st64_b32 v[6:7], v109 offset0:16 offset1:17
	ds_read2st64_b32 v[8:9], v109 offset0:18 offset1:19
	s_waitcnt lgkmcnt(0)
	v_cvt_pk_bf16_f32 v250, v2, v3
	v_cvt_pk_bf16_f32 v251, v4, v5
	v_cvt_pk_bf16_f32 v252, v6, v7
	v_cvt_pk_bf16_f32 v253, v8, v9
	s_nop 1
	v_mfma_f32_16x16x32_bf16 v[180:183], v[250:253], v[10:13], v[180:183]
	ds_read2st64_b32 v[2:3], v110 offset0:0 offset1:1
	ds_read2st64_b32 v[4:5], v110 offset0:2 offset1:3
	ds_read2st64_b32 v[6:7], v110 offset0:16 offset1:17
	ds_read2st64_b32 v[8:9], v110 offset0:18 offset1:19
	s_waitcnt lgkmcnt(0)
	v_cvt_pk_bf16_f32 v250, v2, v3
	v_cvt_pk_bf16_f32 v251, v4, v5
	v_cvt_pk_bf16_f32 v252, v6, v7
	v_cvt_pk_bf16_f32 v253, v8, v9
	s_nop 1
	v_mfma_f32_16x16x32_bf16 v[184:187], v[250:253], v[10:13], v[184:187]
	ds_read2st64_b32 v[2:3], v111 offset0:0 offset1:1
	ds_read2st64_b32 v[4:5], v111 offset0:2 offset1:3
	ds_read2st64_b32 v[6:7], v111 offset0:16 offset1:17
	ds_read2st64_b32 v[8:9], v111 offset0:18 offset1:19
	s_waitcnt lgkmcnt(0)
	v_cvt_pk_bf16_f32 v250, v2, v3
	v_cvt_pk_bf16_f32 v251, v4, v5
	v_cvt_pk_bf16_f32 v252, v6, v7
	v_cvt_pk_bf16_f32 v253, v8, v9
	s_nop 1
	v_mfma_f32_16x16x32_bf16 v[188:191], v[250:253], v[10:13], v[188:191]
	ds_read2st64_b32 v[2:3], v14 offset0:0 offset1:1
	ds_read2st64_b32 v[4:5], v14 offset0:2 offset1:3
	ds_read2st64_b32 v[6:7], v14 offset0:16 offset1:17
	ds_read2st64_b32 v[8:9], v14 offset0:18 offset1:19
	s_waitcnt lgkmcnt(0)
	v_cvt_pk_bf16_f32 v250, v2, v3
	v_cvt_pk_bf16_f32 v251, v4, v5
	v_cvt_pk_bf16_f32 v252, v6, v7
	v_cvt_pk_bf16_f32 v253, v8, v9
	s_nop 1
	v_mfma_f32_16x16x32_bf16 v[192:195], v[250:253], v[10:13], v[192:195]
	s_waitcnt vmcnt(8)
	ds_write_b128 v105, v[48:51]
	ds_write_b128 v106, v[52:55] offset:1024
	ds_write_b128 v105, v[56:59] offset:2048
	ds_write_b128 v106, v[60:63] offset:3072
	ds_write_b128 v105, v[200:203] offset:4096
	ds_write_b128 v106, v[204:207] offset:5120
	ds_write_b128 v105, v[208:211] offset:6144
	ds_write_b128 v106, v[212:215] offset:7168
	global_load_dwordx4 v[48:51], v72, s[76:77]
	global_load_dwordx4 v[52:55], v73, s[76:77]
	global_load_dwordx4 v[56:59], v74, s[76:77]
	global_load_dwordx4 v[60:63], v75, s[76:77]
	global_load_dwordx4 v[200:203], v72, s[78:79]
	global_load_dwordx4 v[204:207], v73, s[78:79]
	global_load_dwordx4 v[208:211], v74, s[78:79]
	global_load_dwordx4 v[212:215], v75, s[78:79]
	s_add_u32 s76, s76, 0x80000
	s_addc_u32 s77, s77, 0
	s_add_u32 s78, s78, 0x80000
	s_addc_u32 s79, s79, 0
	v_cvt_pk_bf16_f32 v10, v120, v121
	v_cvt_pk_bf16_f32 v11, v122, v123
	v_cvt_pk_bf16_f32 v12, v124, v125
	v_cvt_pk_bf16_f32 v13, v126, v127
	ds_read2st64_b32 v[2:3], v109 offset0:0 offset1:1
	ds_read2st64_b32 v[4:5], v109 offset0:2 offset1:3
	ds_read2st64_b32 v[6:7], v109 offset0:16 offset1:17
	ds_read2st64_b32 v[8:9], v109 offset0:18 offset1:19
	s_waitcnt lgkmcnt(0)
	v_cvt_pk_bf16_f32 v250, v2, v3
	v_cvt_pk_bf16_f32 v251, v4, v5
	v_cvt_pk_bf16_f32 v252, v6, v7
	v_cvt_pk_bf16_f32 v253, v8, v9
	s_nop 1
	v_mfma_f32_16x16x32_bf16 v[180:183], v[250:253], v[10:13], v[180:183]
	ds_read2st64_b32 v[2:3], v110 offset0:0 offset1:1
	ds_read2st64_b32 v[4:5], v110 offset0:2 offset1:3
	ds_read2st64_b32 v[6:7], v110 offset0:16 offset1:17
	ds_read2st64_b32 v[8:9], v110 offset0:18 offset1:19
	s_waitcnt lgkmcnt(0)
	v_cvt_pk_bf16_f32 v250, v2, v3
	v_cvt_pk_bf16_f32 v251, v4, v5
	v_cvt_pk_bf16_f32 v252, v6, v7
	v_cvt_pk_bf16_f32 v253, v8, v9
	s_nop 1
	v_mfma_f32_16x16x32_bf16 v[184:187], v[250:253], v[10:13], v[184:187]
	ds_read2st64_b32 v[2:3], v111 offset0:0 offset1:1
	ds_read2st64_b32 v[4:5], v111 offset0:2 offset1:3
	ds_read2st64_b32 v[6:7], v111 offset0:16 offset1:17
	ds_read2st64_b32 v[8:9], v111 offset0:18 offset1:19
	s_waitcnt lgkmcnt(0)
	v_cvt_pk_bf16_f32 v250, v2, v3
	v_cvt_pk_bf16_f32 v251, v4, v5
	v_cvt_pk_bf16_f32 v252, v6, v7
	v_cvt_pk_bf16_f32 v253, v8, v9
	s_nop 1
	v_mfma_f32_16x16x32_bf16 v[188:191], v[250:253], v[10:13], v[188:191]
	ds_read2st64_b32 v[2:3], v14 offset0:0 offset1:1
	ds_read2st64_b32 v[4:5], v14 offset0:2 offset1:3
	ds_read2st64_b32 v[6:7], v14 offset0:16 offset1:17
	ds_read2st64_b32 v[8:9], v14 offset0:18 offset1:19
	s_waitcnt lgkmcnt(0)
	v_cvt_pk_bf16_f32 v250, v2, v3
	v_cvt_pk_bf16_f32 v251, v4, v5
	v_cvt_pk_bf16_f32 v252, v6, v7
	v_cvt_pk_bf16_f32 v253, v8, v9
	s_nop 1
	v_mfma_f32_16x16x32_bf16 v[192:195], v[250:253], v[10:13], v[192:195]
	s_waitcnt vmcnt(8)
	ds_write_b128 v105, v[16:19]
	ds_write_b128 v106, v[20:23] offset:1024
	ds_write_b128 v105, v[24:27] offset:2048
	ds_write_b128 v106, v[28:31] offset:3072
	ds_write_b128 v105, v[32:35] offset:4096
	ds_write_b128 v106, v[36:39] offset:5120
	ds_write_b128 v105, v[40:43] offset:6144
	ds_write_b128 v106, v[44:47] offset:7168
	global_load_dwordx4 v[16:19], v72, s[76:77]
	global_load_dwordx4 v[20:23], v73, s[76:77]
	global_load_dwordx4 v[24:27], v74, s[76:77]
	global_load_dwordx4 v[28:31], v75, s[76:77]
	global_load_dwordx4 v[32:35], v72, s[78:79]
	global_load_dwordx4 v[36:39], v73, s[78:79]
	global_load_dwordx4 v[40:43], v74, s[78:79]
	global_load_dwordx4 v[44:47], v75, s[78:79]
	s_add_u32 s76, s76, 0x80000
	s_addc_u32 s77, s77, 0
	s_add_u32 s78, s78, 0x80000
	s_addc_u32 s79, s79, 0
	v_cvt_pk_bf16_f32 v10, v128, v129
	v_cvt_pk_bf16_f32 v11, v130, v131
	v_cvt_pk_bf16_f32 v12, v132, v133
	v_cvt_pk_bf16_f32 v13, v134, v135
	ds_read2st64_b32 v[2:3], v109 offset0:0 offset1:1
	ds_read2st64_b32 v[4:5], v109 offset0:2 offset1:3
	ds_read2st64_b32 v[6:7], v109 offset0:16 offset1:17
	ds_read2st64_b32 v[8:9], v109 offset0:18 offset1:19
	s_waitcnt lgkmcnt(0)
	v_cvt_pk_bf16_f32 v250, v2, v3
	v_cvt_pk_bf16_f32 v251, v4, v5
	v_cvt_pk_bf16_f32 v252, v6, v7
	v_cvt_pk_bf16_f32 v253, v8, v9
	s_nop 1
	v_mfma_f32_16x16x32_bf16 v[180:183], v[250:253], v[10:13], v[180:183]
	ds_read2st64_b32 v[2:3], v110 offset0:0 offset1:1
	ds_read2st64_b32 v[4:5], v110 offset0:2 offset1:3
	ds_read2st64_b32 v[6:7], v110 offset0:16 offset1:17
	ds_read2st64_b32 v[8:9], v110 offset0:18 offset1:19
	s_waitcnt lgkmcnt(0)
	v_cvt_pk_bf16_f32 v250, v2, v3
	v_cvt_pk_bf16_f32 v251, v4, v5
	v_cvt_pk_bf16_f32 v252, v6, v7
	v_cvt_pk_bf16_f32 v253, v8, v9
	s_nop 1
	v_mfma_f32_16x16x32_bf16 v[184:187], v[250:253], v[10:13], v[184:187]
	ds_read2st64_b32 v[2:3], v111 offset0:0 offset1:1
	ds_read2st64_b32 v[4:5], v111 offset0:2 offset1:3
	ds_read2st64_b32 v[6:7], v111 offset0:16 offset1:17
	ds_read2st64_b32 v[8:9], v111 offset0:18 offset1:19
	s_waitcnt lgkmcnt(0)
	v_cvt_pk_bf16_f32 v250, v2, v3
	v_cvt_pk_bf16_f32 v251, v4, v5
	v_cvt_pk_bf16_f32 v252, v6, v7
	v_cvt_pk_bf16_f32 v253, v8, v9
	s_nop 1
	v_mfma_f32_16x16x32_bf16 v[188:191], v[250:253], v[10:13], v[188:191]
	ds_read2st64_b32 v[2:3], v14 offset0:0 offset1:1
	ds_read2st64_b32 v[4:5], v14 offset0:2 offset1:3
	ds_read2st64_b32 v[6:7], v14 offset0:16 offset1:17
	ds_read2st64_b32 v[8:9], v14 offset0:18 offset1:19
	s_waitcnt lgkmcnt(0)
	v_cvt_pk_bf16_f32 v250, v2, v3
	v_cvt_pk_bf16_f32 v251, v4, v5
	v_cvt_pk_bf16_f32 v252, v6, v7
	v_cvt_pk_bf16_f32 v253, v8, v9
	s_nop 1
	v_mfma_f32_16x16x32_bf16 v[192:195], v[250:253], v[10:13], v[192:195]
	s_waitcnt vmcnt(8)
	ds_write_b128 v105, v[48:51]
	ds_write_b128 v106, v[52:55] offset:1024
	ds_write_b128 v105, v[56:59] offset:2048
	ds_write_b128 v106, v[60:63] offset:3072
	ds_write_b128 v105, v[200:203] offset:4096
	ds_write_b128 v106, v[204:207] offset:5120
	ds_write_b128 v105, v[208:211] offset:6144
	ds_write_b128 v106, v[212:215] offset:7168
	global_load_dwordx4 v[48:51], v72, s[76:77]
	global_load_dwordx4 v[52:55], v73, s[76:77]
	global_load_dwordx4 v[56:59], v74, s[76:77]
	global_load_dwordx4 v[60:63], v75, s[76:77]
	global_load_dwordx4 v[200:203], v72, s[78:79]
	global_load_dwordx4 v[204:207], v73, s[78:79]
	global_load_dwordx4 v[208:211], v74, s[78:79]
	global_load_dwordx4 v[212:215], v75, s[78:79]
	s_add_u32 s76, s76, 0x80000
	s_addc_u32 s77, s77, 0
	s_add_u32 s78, s78, 0x80000
	s_addc_u32 s79, s79, 0
	v_cvt_pk_bf16_f32 v10, v136, v137
	v_cvt_pk_bf16_f32 v11, v138, v139
	v_cvt_pk_bf16_f32 v12, v140, v141
	v_cvt_pk_bf16_f32 v13, v142, v143
	ds_read2st64_b32 v[2:3], v109 offset0:0 offset1:1
	ds_read2st64_b32 v[4:5], v109 offset0:2 offset1:3
	ds_read2st64_b32 v[6:7], v109 offset0:16 offset1:17
	ds_read2st64_b32 v[8:9], v109 offset0:18 offset1:19
	s_waitcnt lgkmcnt(0)
	v_cvt_pk_bf16_f32 v250, v2, v3
	v_cvt_pk_bf16_f32 v251, v4, v5
	v_cvt_pk_bf16_f32 v252, v6, v7
	v_cvt_pk_bf16_f32 v253, v8, v9
	s_nop 1
	v_mfma_f32_16x16x32_bf16 v[180:183], v[250:253], v[10:13], v[180:183]
	ds_read2st64_b32 v[2:3], v110 offset0:0 offset1:1
	ds_read2st64_b32 v[4:5], v110 offset0:2 offset1:3
	ds_read2st64_b32 v[6:7], v110 offset0:16 offset1:17
	ds_read2st64_b32 v[8:9], v110 offset0:18 offset1:19
	s_waitcnt lgkmcnt(0)
	v_cvt_pk_bf16_f32 v250, v2, v3
	v_cvt_pk_bf16_f32 v251, v4, v5
	v_cvt_pk_bf16_f32 v252, v6, v7
	v_cvt_pk_bf16_f32 v253, v8, v9
	s_nop 1
	v_mfma_f32_16x16x32_bf16 v[184:187], v[250:253], v[10:13], v[184:187]
	ds_read2st64_b32 v[2:3], v111 offset0:0 offset1:1
	ds_read2st64_b32 v[4:5], v111 offset0:2 offset1:3
	ds_read2st64_b32 v[6:7], v111 offset0:16 offset1:17
	ds_read2st64_b32 v[8:9], v111 offset0:18 offset1:19
	s_waitcnt lgkmcnt(0)
	v_cvt_pk_bf16_f32 v250, v2, v3
	v_cvt_pk_bf16_f32 v251, v4, v5
	v_cvt_pk_bf16_f32 v252, v6, v7
	v_cvt_pk_bf16_f32 v253, v8, v9
	s_nop 1
	v_mfma_f32_16x16x32_bf16 v[188:191], v[250:253], v[10:13], v[188:191]
	ds_read2st64_b32 v[2:3], v14 offset0:0 offset1:1
	ds_read2st64_b32 v[4:5], v14 offset0:2 offset1:3
	ds_read2st64_b32 v[6:7], v14 offset0:16 offset1:17
	ds_read2st64_b32 v[8:9], v14 offset0:18 offset1:19
	s_waitcnt lgkmcnt(0)
	v_cvt_pk_bf16_f32 v250, v2, v3
	v_cvt_pk_bf16_f32 v251, v4, v5
	v_cvt_pk_bf16_f32 v252, v6, v7
	v_cvt_pk_bf16_f32 v253, v8, v9
	s_nop 1
	v_mfma_f32_16x16x32_bf16 v[192:195], v[250:253], v[10:13], v[192:195]
	s_waitcnt vmcnt(8)
	ds_write_b128 v105, v[16:19]
	ds_write_b128 v106, v[20:23] offset:1024
	ds_write_b128 v105, v[24:27] offset:2048
	ds_write_b128 v106, v[28:31] offset:3072
	ds_write_b128 v105, v[32:35] offset:4096
	ds_write_b128 v106, v[36:39] offset:5120
	ds_write_b128 v105, v[40:43] offset:6144
	ds_write_b128 v106, v[44:47] offset:7168
	global_load_dwordx4 v[16:19], v72, s[76:77]
	global_load_dwordx4 v[20:23], v73, s[76:77]
	global_load_dwordx4 v[24:27], v74, s[76:77]
	global_load_dwordx4 v[28:31], v75, s[76:77]
	global_load_dwordx4 v[32:35], v72, s[78:79]
	global_load_dwordx4 v[36:39], v73, s[78:79]
	global_load_dwordx4 v[40:43], v74, s[78:79]
	global_load_dwordx4 v[44:47], v75, s[78:79]
	s_add_u32 s76, s76, 0x80000
	s_addc_u32 s77, s77, 0
	s_add_u32 s78, s78, 0x80000
	s_addc_u32 s79, s79, 0
	v_cvt_pk_bf16_f32 v10, v144, v145
	v_cvt_pk_bf16_f32 v11, v146, v147
	v_cvt_pk_bf16_f32 v12, v148, v149
	v_cvt_pk_bf16_f32 v13, v150, v151
	ds_read2st64_b32 v[2:3], v109 offset0:0 offset1:1
	ds_read2st64_b32 v[4:5], v109 offset0:2 offset1:3
	ds_read2st64_b32 v[6:7], v109 offset0:16 offset1:17
	ds_read2st64_b32 v[8:9], v109 offset0:18 offset1:19
	s_waitcnt lgkmcnt(0)
	v_cvt_pk_bf16_f32 v250, v2, v3
	v_cvt_pk_bf16_f32 v251, v4, v5
	v_cvt_pk_bf16_f32 v252, v6, v7
	v_cvt_pk_bf16_f32 v253, v8, v9
	s_nop 1
	v_mfma_f32_16x16x32_bf16 v[180:183], v[250:253], v[10:13], v[180:183]
	ds_read2st64_b32 v[2:3], v110 offset0:0 offset1:1
	ds_read2st64_b32 v[4:5], v110 offset0:2 offset1:3
	ds_read2st64_b32 v[6:7], v110 offset0:16 offset1:17
	ds_read2st64_b32 v[8:9], v110 offset0:18 offset1:19
	s_waitcnt lgkmcnt(0)
	v_cvt_pk_bf16_f32 v250, v2, v3
	v_cvt_pk_bf16_f32 v251, v4, v5
	v_cvt_pk_bf16_f32 v252, v6, v7
	v_cvt_pk_bf16_f32 v253, v8, v9
	s_nop 1
	v_mfma_f32_16x16x32_bf16 v[184:187], v[250:253], v[10:13], v[184:187]
	ds_read2st64_b32 v[2:3], v111 offset0:0 offset1:1
	ds_read2st64_b32 v[4:5], v111 offset0:2 offset1:3
	ds_read2st64_b32 v[6:7], v111 offset0:16 offset1:17
	ds_read2st64_b32 v[8:9], v111 offset0:18 offset1:19
	s_waitcnt lgkmcnt(0)
	v_cvt_pk_bf16_f32 v250, v2, v3
	v_cvt_pk_bf16_f32 v251, v4, v5
	v_cvt_pk_bf16_f32 v252, v6, v7
	v_cvt_pk_bf16_f32 v253, v8, v9
	s_nop 1
	v_mfma_f32_16x16x32_bf16 v[188:191], v[250:253], v[10:13], v[188:191]
	ds_read2st64_b32 v[2:3], v14 offset0:0 offset1:1
	ds_read2st64_b32 v[4:5], v14 offset0:2 offset1:3
	ds_read2st64_b32 v[6:7], v14 offset0:16 offset1:17
	ds_read2st64_b32 v[8:9], v14 offset0:18 offset1:19
	s_waitcnt lgkmcnt(0)
	v_cvt_pk_bf16_f32 v250, v2, v3
	v_cvt_pk_bf16_f32 v251, v4, v5
	v_cvt_pk_bf16_f32 v252, v6, v7
	v_cvt_pk_bf16_f32 v253, v8, v9
	s_nop 1
	v_mfma_f32_16x16x32_bf16 v[192:195], v[250:253], v[10:13], v[192:195]
	s_waitcnt vmcnt(8)
	ds_write_b128 v105, v[48:51]
	ds_write_b128 v106, v[52:55] offset:1024
	ds_write_b128 v105, v[56:59] offset:2048
	ds_write_b128 v106, v[60:63] offset:3072
	ds_write_b128 v105, v[200:203] offset:4096
	ds_write_b128 v106, v[204:207] offset:5120
	ds_write_b128 v105, v[208:211] offset:6144
	ds_write_b128 v106, v[212:215] offset:7168
	global_load_dwordx4 v[48:51], v72, s[76:77]
	global_load_dwordx4 v[52:55], v73, s[76:77]
	global_load_dwordx4 v[56:59], v74, s[76:77]
	global_load_dwordx4 v[60:63], v75, s[76:77]
	global_load_dwordx4 v[200:203], v72, s[78:79]
	global_load_dwordx4 v[204:207], v73, s[78:79]
	global_load_dwordx4 v[208:211], v74, s[78:79]
	global_load_dwordx4 v[212:215], v75, s[78:79]
	s_add_u32 s76, s76, 0x80000
	s_addc_u32 s77, s77, 0
	s_add_u32 s78, s78, 0x80000
	s_addc_u32 s79, s79, 0
	v_cvt_pk_bf16_f32 v10, v152, v153
	v_cvt_pk_bf16_f32 v11, v154, v155
	v_cvt_pk_bf16_f32 v12, v156, v157
	v_cvt_pk_bf16_f32 v13, v158, v159
	ds_read2st64_b32 v[2:3], v109 offset0:0 offset1:1
	ds_read2st64_b32 v[4:5], v109 offset0:2 offset1:3
	ds_read2st64_b32 v[6:7], v109 offset0:16 offset1:17
	ds_read2st64_b32 v[8:9], v109 offset0:18 offset1:19
	s_waitcnt lgkmcnt(0)
	v_cvt_pk_bf16_f32 v250, v2, v3
	v_cvt_pk_bf16_f32 v251, v4, v5
	v_cvt_pk_bf16_f32 v252, v6, v7
	v_cvt_pk_bf16_f32 v253, v8, v9
	s_nop 1
	v_mfma_f32_16x16x32_bf16 v[180:183], v[250:253], v[10:13], v[180:183]
	ds_read2st64_b32 v[2:3], v110 offset0:0 offset1:1
	ds_read2st64_b32 v[4:5], v110 offset0:2 offset1:3
	ds_read2st64_b32 v[6:7], v110 offset0:16 offset1:17
	ds_read2st64_b32 v[8:9], v110 offset0:18 offset1:19
	s_waitcnt lgkmcnt(0)
	v_cvt_pk_bf16_f32 v250, v2, v3
	v_cvt_pk_bf16_f32 v251, v4, v5
	v_cvt_pk_bf16_f32 v252, v6, v7
	v_cvt_pk_bf16_f32 v253, v8, v9
	s_nop 1
	v_mfma_f32_16x16x32_bf16 v[184:187], v[250:253], v[10:13], v[184:187]
	ds_read2st64_b32 v[2:3], v111 offset0:0 offset1:1
	ds_read2st64_b32 v[4:5], v111 offset0:2 offset1:3
	ds_read2st64_b32 v[6:7], v111 offset0:16 offset1:17
	ds_read2st64_b32 v[8:9], v111 offset0:18 offset1:19
	s_waitcnt lgkmcnt(0)
	v_cvt_pk_bf16_f32 v250, v2, v3
	v_cvt_pk_bf16_f32 v251, v4, v5
	v_cvt_pk_bf16_f32 v252, v6, v7
	v_cvt_pk_bf16_f32 v253, v8, v9
	s_nop 1
	v_mfma_f32_16x16x32_bf16 v[188:191], v[250:253], v[10:13], v[188:191]
	ds_read2st64_b32 v[2:3], v14 offset0:0 offset1:1
	ds_read2st64_b32 v[4:5], v14 offset0:2 offset1:3
	ds_read2st64_b32 v[6:7], v14 offset0:16 offset1:17
	ds_read2st64_b32 v[8:9], v14 offset0:18 offset1:19
	s_waitcnt lgkmcnt(0)
	v_cvt_pk_bf16_f32 v250, v2, v3
	v_cvt_pk_bf16_f32 v251, v4, v5
	v_cvt_pk_bf16_f32 v252, v6, v7
	v_cvt_pk_bf16_f32 v253, v8, v9
	s_nop 1
	v_mfma_f32_16x16x32_bf16 v[192:195], v[250:253], v[10:13], v[192:195]
	s_waitcnt vmcnt(8)
	ds_write_b128 v105, v[16:19]
	ds_write_b128 v106, v[20:23] offset:1024
	ds_write_b128 v105, v[24:27] offset:2048
	ds_write_b128 v106, v[28:31] offset:3072
	ds_write_b128 v105, v[32:35] offset:4096
	ds_write_b128 v106, v[36:39] offset:5120
	ds_write_b128 v105, v[40:43] offset:6144
	ds_write_b128 v106, v[44:47] offset:7168
	v_cvt_pk_bf16_f32 v10, v160, v161
	v_cvt_pk_bf16_f32 v11, v162, v163
	v_cvt_pk_bf16_f32 v12, v164, v165
	v_cvt_pk_bf16_f32 v13, v166, v167
	ds_read2st64_b32 v[2:3], v109 offset0:0 offset1:1
	ds_read2st64_b32 v[4:5], v109 offset0:2 offset1:3
	ds_read2st64_b32 v[6:7], v109 offset0:16 offset1:17
	ds_read2st64_b32 v[8:9], v109 offset0:18 offset1:19
	s_waitcnt lgkmcnt(0)
	v_cvt_pk_bf16_f32 v250, v2, v3
	v_cvt_pk_bf16_f32 v251, v4, v5
	v_cvt_pk_bf16_f32 v252, v6, v7
	v_cvt_pk_bf16_f32 v253, v8, v9
	s_nop 1
	v_mfma_f32_16x16x32_bf16 v[180:183], v[250:253], v[10:13], v[180:183]
	ds_read2st64_b32 v[2:3], v110 offset0:0 offset1:1
	ds_read2st64_b32 v[4:5], v110 offset0:2 offset1:3
	ds_read2st64_b32 v[6:7], v110 offset0:16 offset1:17
	ds_read2st64_b32 v[8:9], v110 offset0:18 offset1:19
	s_waitcnt lgkmcnt(0)
	v_cvt_pk_bf16_f32 v250, v2, v3
	v_cvt_pk_bf16_f32 v251, v4, v5
	v_cvt_pk_bf16_f32 v252, v6, v7
	v_cvt_pk_bf16_f32 v253, v8, v9
	s_nop 1
	v_mfma_f32_16x16x32_bf16 v[184:187], v[250:253], v[10:13], v[184:187]
	ds_read2st64_b32 v[2:3], v111 offset0:0 offset1:1
	ds_read2st64_b32 v[4:5], v111 offset0:2 offset1:3
	ds_read2st64_b32 v[6:7], v111 offset0:16 offset1:17
	ds_read2st64_b32 v[8:9], v111 offset0:18 offset1:19
	s_waitcnt lgkmcnt(0)
	v_cvt_pk_bf16_f32 v250, v2, v3
	v_cvt_pk_bf16_f32 v251, v4, v5
	v_cvt_pk_bf16_f32 v252, v6, v7
	v_cvt_pk_bf16_f32 v253, v8, v9
	s_nop 1
	v_mfma_f32_16x16x32_bf16 v[188:191], v[250:253], v[10:13], v[188:191]
	ds_read2st64_b32 v[2:3], v14 offset0:0 offset1:1
	ds_read2st64_b32 v[4:5], v14 offset0:2 offset1:3
	ds_read2st64_b32 v[6:7], v14 offset0:16 offset1:17
	ds_read2st64_b32 v[8:9], v14 offset0:18 offset1:19
	s_waitcnt lgkmcnt(0)
	v_cvt_pk_bf16_f32 v250, v2, v3
	v_cvt_pk_bf16_f32 v251, v4, v5
	v_cvt_pk_bf16_f32 v252, v6, v7
	v_cvt_pk_bf16_f32 v253, v8, v9
	s_nop 1
	v_mfma_f32_16x16x32_bf16 v[192:195], v[250:253], v[10:13], v[192:195]
	s_waitcnt vmcnt(0)
	ds_write_b128 v105, v[48:51]
	ds_write_b128 v106, v[52:55] offset:1024
	ds_write_b128 v105, v[56:59] offset:2048
	ds_write_b128 v106, v[60:63] offset:3072
	ds_write_b128 v105, v[200:203] offset:4096
	ds_write_b128 v106, v[204:207] offset:5120
	ds_write_b128 v105, v[208:211] offset:6144
	ds_write_b128 v106, v[212:215] offset:7168
	v_cvt_pk_bf16_f32 v10, v168, v169
	v_cvt_pk_bf16_f32 v11, v170, v171
	v_cvt_pk_bf16_f32 v12, v172, v173
	v_cvt_pk_bf16_f32 v13, v174, v175
	ds_read2st64_b32 v[2:3], v109 offset0:0 offset1:1
	ds_read2st64_b32 v[4:5], v109 offset0:2 offset1:3
	ds_read2st64_b32 v[6:7], v109 offset0:16 offset1:17
	ds_read2st64_b32 v[8:9], v109 offset0:18 offset1:19
	s_waitcnt lgkmcnt(0)
	v_cvt_pk_bf16_f32 v250, v2, v3
	v_cvt_pk_bf16_f32 v251, v4, v5
	v_cvt_pk_bf16_f32 v252, v6, v7
	v_cvt_pk_bf16_f32 v253, v8, v9
	s_nop 1
	v_mfma_f32_16x16x32_bf16 v[180:183], v[250:253], v[10:13], v[180:183]
	ds_read2st64_b32 v[2:3], v110 offset0:0 offset1:1
	ds_read2st64_b32 v[4:5], v110 offset0:2 offset1:3
	ds_read2st64_b32 v[6:7], v110 offset0:16 offset1:17
	ds_read2st64_b32 v[8:9], v110 offset0:18 offset1:19
	s_waitcnt lgkmcnt(0)
	v_cvt_pk_bf16_f32 v250, v2, v3
	v_cvt_pk_bf16_f32 v251, v4, v5
	v_cvt_pk_bf16_f32 v252, v6, v7
	v_cvt_pk_bf16_f32 v253, v8, v9
	s_nop 1
	v_mfma_f32_16x16x32_bf16 v[184:187], v[250:253], v[10:13], v[184:187]
	ds_read2st64_b32 v[2:3], v111 offset0:0 offset1:1
	ds_read2st64_b32 v[4:5], v111 offset0:2 offset1:3
	ds_read2st64_b32 v[6:7], v111 offset0:16 offset1:17
	ds_read2st64_b32 v[8:9], v111 offset0:18 offset1:19
	s_waitcnt lgkmcnt(0)
	v_cvt_pk_bf16_f32 v250, v2, v3
	v_cvt_pk_bf16_f32 v251, v4, v5
	v_cvt_pk_bf16_f32 v252, v6, v7
	v_cvt_pk_bf16_f32 v253, v8, v9
	s_nop 1
	v_mfma_f32_16x16x32_bf16 v[188:191], v[250:253], v[10:13], v[188:191]
	ds_read2st64_b32 v[2:3], v14 offset0:0 offset1:1
	ds_read2st64_b32 v[4:5], v14 offset0:2 offset1:3
	ds_read2st64_b32 v[6:7], v14 offset0:16 offset1:17
	ds_read2st64_b32 v[8:9], v14 offset0:18 offset1:19
	s_waitcnt lgkmcnt(0)
	v_cvt_pk_bf16_f32 v250, v2, v3
	v_cvt_pk_bf16_f32 v251, v4, v5
	v_cvt_pk_bf16_f32 v252, v6, v7
	v_cvt_pk_bf16_f32 v253, v8, v9
	s_nop 1
	v_mfma_f32_16x16x32_bf16 v[192:195], v[250:253], v[10:13], v[192:195]
	s_cmp_lg_u32 s72, 0
	s_cbranch_scc1 .Lsa_pv16_skip
	ds_write_b128 v105, v[232:235]
	ds_write_b128 v106, v[236:239] offset:1024
	ds_write_b128 v105, v[240:243] offset:2048
	ds_write_b128 v106, v[244:247] offset:3072
	v_cvt_pk_bf16_f32 v10, v176, v177
	v_cvt_pk_bf16_f32 v11, v178, v179
	v_mov_b32_e32 v12, 0
	v_mov_b32_e32 v13, 0
	ds_read2st64_b32 v[2:3], v109 offset0:0 offset1:1
	ds_read2st64_b32 v[4:5], v109 offset0:2 offset1:3
	s_waitcnt lgkmcnt(0)
	v_cvt_pk_bf16_f32 v250, v2, v3
	v_cvt_pk_bf16_f32 v251, v4, v5
	v_mov_b32_e32 v252, 0
	v_mov_b32_e32 v253, 0
	s_nop 1
	v_mfma_f32_16x16x32_bf16 v[180:183], v[250:253], v[10:13], v[180:183]
	ds_read2st64_b32 v[2:3], v110 offset0:0 offset1:1
	ds_read2st64_b32 v[4:5], v110 offset0:2 offset1:3
	s_waitcnt lgkmcnt(0)
	v_cvt_pk_bf16_f32 v250, v2, v3
	v_cvt_pk_bf16_f32 v251, v4, v5
	v_mov_b32_e32 v252, 0
	v_mov_b32_e32 v253, 0
	s_nop 1
	v_mfma_f32_16x16x32_bf16 v[184:187], v[250:253], v[10:13], v[184:187]
	ds_read2st64_b32 v[2:3], v111 offset0:0 offset1:1
	ds_read2st64_b32 v[4:5], v111 offset0:2 offset1:3
	s_waitcnt lgkmcnt(0)
	v_cvt_pk_bf16_f32 v250, v2, v3
	v_cvt_pk_bf16_f32 v251, v4, v5
	v_mov_b32_e32 v252, 0
	v_mov_b32_e32 v253, 0
	s_nop 1
	v_mfma_f32_16x16x32_bf16 v[188:191], v[250:253], v[10:13], v[188:191]
	ds_read2st64_b32 v[2:3], v14 offset0:0 offset1:1
	ds_read2st64_b32 v[4:5], v14 offset0:2 offset1:3
	s_waitcnt lgkmcnt(0)
	v_cvt_pk_bf16_f32 v250, v2, v3
	v_cvt_pk_bf16_f32 v251, v4, v5
	v_mov_b32_e32 v252, 0
	v_mov_b32_e32 v253, 0
	s_nop 1
	v_mfma_f32_16x16x32_bf16 v[192:195], v[250:253], v[10:13], v[192:195]
.Lsa_pv16_skip:
	v_lshlrev_b32_e32 v105, 8, v77
	v_lshl_add_u32 v105, v76, 4, v105
	s_lshl_b32 s0, s72, 12
	s_add_i32 s0, s0, 0x4010
	v_add_u32_e32 v105, s0, v105
	s_nop 7
	s_nop 1
	ds_write_b128 v105, v[180:183]
	ds_write_b128 v105, v[184:187] offset:64
	ds_write_b128 v105, v[188:191] offset:128
	ds_write_b128 v105, v[192:195] offset:192
	v_and_b32_e32 v106, 63, v0
	v_lshlrev_b32_e32 v106, 2, v106
	v_lshrrev_b32_e32 v111, 1, v106
	s_waitcnt lgkmcnt(0)
	s_barrier
	s_add_i32 s0, s72, 0
	s_lshl_b32 s1, s0, 8
	s_add_i32 s1, s1, 0x4010
	v_add_u32_e32 v107, s1, v106
	ds_read_b32 v200, v107
	ds_read_b32 v201, v107 offset:4096
	ds_read_b32 v202, v107 offset:8192
	ds_read_b32 v203, v107 offset:12288
	ds_read_b32 v204, v107 offset:16384
	ds_read_b32 v205, v107 offset:20480
	ds_read_b32 v206, v107 offset:24576
	ds_read_b32 v207, v107 offset:28672
	s_lshl_b32 s1, s0, 2
	s_add_i32 s1, s1, 0xc810
	v_mov_b32_e32 v108, s1
	v_add_u32_e32 v109, 64, v108
	v_add_u32_e32 v110, 0x80, v108
	v_add_u32_e32 v105, 0xc0, v108
	ds_read2st64_b32 v[208:209], v108 offset0:0 offset1:1
	ds_read2st64_b32 v[210:211], v108 offset0:2 offset1:3
	ds_read2st64_b32 v[212:213], v108 offset0:4 offset1:5
	ds_read2st64_b32 v[214:215], v108 offset0:6 offset1:7
	ds_read2st64_b32 v[216:217], v109 offset0:0 offset1:1
	ds_read2st64_b32 v[218:219], v109 offset0:2 offset1:3
	ds_read2st64_b32 v[220:221], v109 offset0:4 offset1:5
	ds_read2st64_b32 v[222:223], v109 offset0:6 offset1:7
	ds_read2st64_b32 v[224:225], v110 offset0:0 offset1:1
	ds_read2st64_b32 v[226:227], v110 offset0:2 offset1:3
	ds_read2st64_b32 v[228:229], v110 offset0:4 offset1:5
	ds_read2st64_b32 v[230:231], v110 offset0:6 offset1:7
	ds_read2st64_b32 v[232:233], v105 offset0:0 offset1:1
	ds_read2st64_b32 v[234:235], v105 offset0:2 offset1:3
	ds_read2st64_b32 v[236:237], v105 offset0:4 offset1:5
	ds_read2st64_b32 v[238:239], v105 offset0:6 offset1:7
	s_waitcnt lgkmcnt(0)
	v_add_f32_e32 v200, v200, v201
	v_add_f32_e32 v200, v200, v202
	v_add_f32_e32 v200, v200, v203
	v_add_f32_e32 v200, v200, v204
	v_add_f32_e32 v200, v200, v205
	v_add_f32_e32 v200, v200, v206
	v_add_f32_e32 v200, v200, v207
	v_add_f32_e32 v208, v208, v209
	v_add_f32_e32 v208, v208, v210
	v_add_f32_e32 v208, v208, v211
	v_add_f32_e32 v208, v208, v212
	v_add_f32_e32 v208, v208, v213
	v_add_f32_e32 v208, v208, v214
	v_add_f32_e32 v208, v208, v215
	v_add_f32_e32 v208, v208, v216
	v_add_f32_e32 v208, v208, v217
	v_add_f32_e32 v208, v208, v218
	v_add_f32_e32 v208, v208, v219
	v_add_f32_e32 v208, v208, v220
	v_add_f32_e32 v208, v208, v221
	v_add_f32_e32 v208, v208, v222
	v_add_f32_e32 v208, v208, v223
	v_add_f32_e32 v208, v208, v224
	v_add_f32_e32 v208, v208, v225
	v_add_f32_e32 v208, v208, v226
	v_add_f32_e32 v208, v208, v227
	v_add_f32_e32 v208, v208, v228
	v_add_f32_e32 v208, v208, v229
	v_add_f32_e32 v208, v208, v230
	v_add_f32_e32 v208, v208, v231
	v_add_f32_e32 v208, v208, v232
	v_add_f32_e32 v208, v208, v233
	v_add_f32_e32 v208, v208, v234
	v_add_f32_e32 v208, v208, v235
	v_add_f32_e32 v208, v208, v236
	v_add_f32_e32 v208, v208, v237
	v_add_f32_e32 v208, v208, v238
	v_add_f32_e32 v208, v208, v239
	v_div_scale_f32 v2, s[4:5], v208, v208, v200
	v_rcp_f32_e32 v3, v2
	s_nop 0
	v_fma_f32 v4, -v2, v3, 1.0
	v_fmac_f32_e32 v3, v4, v3
	v_div_scale_f32 v4, vcc, v200, v208, v200
	v_mul_f32_e32 v5, v4, v3
	v_fma_f32 v6, -v2, v5, v4
	v_fmac_f32_e32 v5, v6, v3
	v_fma_f32 v2, -v2, v5, v4
	v_div_fmas_f32 v2, v2, v3, v5
	v_div_fixup_f32 v2, v2, v208, v200
	v_cvt_pk_bf16_f32 v2, v2, v79
	s_lshl_b32 s1, s0, 10
	s_add_u32 s2, s86, s1
	s_addc_u32 s3, s87, 0
	global_store_short v111, v2, s[2:3]
	s_add_i32 s0, s72, 8
	s_lshl_b32 s1, s0, 8
	s_add_i32 s1, s1, 0x4010
	v_add_u32_e32 v107, s1, v106
	ds_read_b32 v200, v107
	ds_read_b32 v201, v107 offset:4096
	ds_read_b32 v202, v107 offset:8192
	ds_read_b32 v203, v107 offset:12288
	ds_read_b32 v204, v107 offset:16384
	ds_read_b32 v205, v107 offset:20480
	ds_read_b32 v206, v107 offset:24576
	ds_read_b32 v207, v107 offset:28672
	s_lshl_b32 s1, s0, 2
	s_add_i32 s1, s1, 0xc810
	v_mov_b32_e32 v108, s1
	v_add_u32_e32 v109, 64, v108
	v_add_u32_e32 v110, 0x80, v108
	v_add_u32_e32 v105, 0xc0, v108
	ds_read2st64_b32 v[208:209], v108 offset0:0 offset1:1
	ds_read2st64_b32 v[210:211], v108 offset0:2 offset1:3
	ds_read2st64_b32 v[212:213], v108 offset0:4 offset1:5
	ds_read2st64_b32 v[214:215], v108 offset0:6 offset1:7
	ds_read2st64_b32 v[216:217], v109 offset0:0 offset1:1
	ds_read2st64_b32 v[218:219], v109 offset0:2 offset1:3
	ds_read2st64_b32 v[220:221], v109 offset0:4 offset1:5
	ds_read2st64_b32 v[222:223], v109 offset0:6 offset1:7
	ds_read2st64_b32 v[224:225], v110 offset0:0 offset1:1
	ds_read2st64_b32 v[226:227], v110 offset0:2 offset1:3
	ds_read2st64_b32 v[228:229], v110 offset0:4 offset1:5
	ds_read2st64_b32 v[230:231], v110 offset0:6 offset1:7
	ds_read2st64_b32 v[232:233], v105 offset0:0 offset1:1
	ds_read2st64_b32 v[234:235], v105 offset0:2 offset1:3
	ds_read2st64_b32 v[236:237], v105 offset0:4 offset1:5
	ds_read2st64_b32 v[238:239], v105 offset0:6 offset1:7
	s_waitcnt lgkmcnt(0)
	v_add_f32_e32 v200, v200, v201
	v_add_f32_e32 v200, v200, v202
	v_add_f32_e32 v200, v200, v203
	v_add_f32_e32 v200, v200, v204
	v_add_f32_e32 v200, v200, v205
	v_add_f32_e32 v200, v200, v206
	v_add_f32_e32 v200, v200, v207
	v_add_f32_e32 v208, v208, v209
	v_add_f32_e32 v208, v208, v210
	v_add_f32_e32 v208, v208, v211
	v_add_f32_e32 v208, v208, v212
	v_add_f32_e32 v208, v208, v213
	v_add_f32_e32 v208, v208, v214
	v_add_f32_e32 v208, v208, v215
	v_add_f32_e32 v208, v208, v216
	v_add_f32_e32 v208, v208, v217
	v_add_f32_e32 v208, v208, v218
	v_add_f32_e32 v208, v208, v219
	v_add_f32_e32 v208, v208, v220
	v_add_f32_e32 v208, v208, v221
	v_add_f32_e32 v208, v208, v222
	v_add_f32_e32 v208, v208, v223
	v_add_f32_e32 v208, v208, v224
	v_add_f32_e32 v208, v208, v225
	v_add_f32_e32 v208, v208, v226
	v_add_f32_e32 v208, v208, v227
	v_add_f32_e32 v208, v208, v228
	v_add_f32_e32 v208, v208, v229
	v_add_f32_e32 v208, v208, v230
	v_add_f32_e32 v208, v208, v231
	v_add_f32_e32 v208, v208, v232
	v_add_f32_e32 v208, v208, v233
	v_add_f32_e32 v208, v208, v234
	v_add_f32_e32 v208, v208, v235
	v_add_f32_e32 v208, v208, v236
	v_add_f32_e32 v208, v208, v237
	v_add_f32_e32 v208, v208, v238
	v_add_f32_e32 v208, v208, v239
	v_div_scale_f32 v2, s[4:5], v208, v208, v200
	v_rcp_f32_e32 v3, v2
	s_nop 0
	v_fma_f32 v4, -v2, v3, 1.0
	v_fmac_f32_e32 v3, v4, v3
	v_div_scale_f32 v4, vcc, v200, v208, v200
	v_mul_f32_e32 v5, v4, v3
	v_fma_f32 v6, -v2, v5, v4
	v_fmac_f32_e32 v5, v6, v3
	v_fma_f32 v2, -v2, v5, v4
	v_div_fmas_f32 v2, v2, v3, v5
	v_div_fixup_f32 v2, v2, v208, v200
	v_cvt_pk_bf16_f32 v2, v2, v79
	s_lshl_b32 s1, s0, 10
	s_add_u32 s2, s86, s1
	s_addc_u32 s3, s87, 0
	global_store_short v111, v2, s[2:3]
	v_readlane_b32 s22, v255, 3
	s_branch .LBB0_1797

.LBB0_1258:
	s_and_b64 vcc, exec, s[6:7]
	v_mov_b32_e32 v28, 0
	v_mov_b32_e32 v19, 0
	v_mov_b32_e32 v27, 0
	v_mov_b32_e32 v18, 0
	v_mov_b32_e32 v24, 0
	v_mov_b32_e32 v23, 0
	v_mov_b32_e32 v25, 0
	v_mov_b32_e32 v42, 0
	v_mov_b32_e32 v44, 0
	v_mov_b32_e32 v43, 0
	v_mov_b32_e32 v45, 0
	v_mov_b32_e32 v46, 0
	v_mov_b32_e32 v47, 0
	v_mov_b32_e32 v48, 0
	v_mov_b32_e32 v50, 0
	s_cbranch_vccnz .LBB0_1260
	global_load_ushort v112, v[6:7], off
	global_load_ushort v113, v[6:7], off offset:2048
	v_add_co_u32_e32 v4, vcc, 0x1000, v6
	s_nop 1
	v_addc_co_u32_e32 v5, vcc, 0, v7, vcc
	global_load_ushort v114, v[4:5], off
	global_load_ushort v115, v[4:5], off offset:2048
	v_add_co_u32_e32 v4, vcc, 0x2000, v6
	s_nop 1
	v_addc_co_u32_e32 v5, vcc, 0, v7, vcc
	global_load_ushort v116, v[4:5], off
	global_load_ushort v117, v[4:5], off offset:2048
	v_add_co_u32_e32 v4, vcc, 0x3000, v6
	s_nop 1
	v_addc_co_u32_e32 v5, vcc, 0, v7, vcc
	global_load_ushort v118, v[4:5], off
	global_load_ushort v119, v[4:5], off offset:2048
	v_add_co_u32_e32 v4, vcc, 0x4000, v6
	s_nop 1
	v_addc_co_u32_e32 v5, vcc, 0, v7, vcc
	global_load_ushort v120, v[4:5], off
	global_load_ushort v121, v[4:5], off offset:2048
	v_add_co_u32_e32 v4, vcc, 0x5000, v6
	s_nop 1
	v_addc_co_u32_e32 v5, vcc, 0, v7, vcc
	global_load_ushort v122, v[4:5], off
	global_load_ushort v123, v[4:5], off offset:2048
	v_add_co_u32_e32 v4, vcc, 0x6000, v6
	s_nop 1
	v_addc_co_u32_e32 v5, vcc, 0, v7, vcc
	global_load_ushort v124, v[4:5], off offset:2048
	global_load_ushort v125, v[4:5], off
	v_add_co_u32_e32 v4, vcc, 0x7000, v6
	s_nop 1
	v_addc_co_u32_e32 v5, vcc, 0, v7, vcc
	global_load_ushort v126, v[4:5], off
	global_load_ushort v127, v[4:5], off offset:2048
	s_waitcnt vmcnt(0)
	v_lshlrev_b32_e32 v50, 16, v112
	v_lshlrev_b32_e32 v48, 16, v113
	v_lshlrev_b32_e32 v47, 16, v114
	v_lshlrev_b32_e32 v46, 16, v115
	v_lshlrev_b32_e32 v45, 16, v116
	v_lshlrev_b32_e32 v43, 16, v117
	v_lshlrev_b32_e32 v44, 16, v118
	v_lshlrev_b32_e32 v42, 16, v119
	v_lshlrev_b32_e32 v25, 16, v120
	v_lshlrev_b32_e32 v23, 16, v121
	v_lshlrev_b32_e32 v24, 16, v122
	v_lshlrev_b32_e32 v18, 16, v123
	v_lshlrev_b32_e32 v27, 16, v124
	v_lshlrev_b32_e32 v19, 16, v125
	v_lshlrev_b32_e32 v28, 16, v126
	v_lshlrev_b32_e32 v26, 16, v127

.LBB0_1271:
	s_or_b64 exec, exec, s[12:13]
	s_xor_b64 s[8:9], s[10:11], -1
	v_mov_b32_e32 v41, 0
	s_and_b64 vcc, exec, s[6:7]
	v_mov_b32_e32 v40, 0
	v_mov_b32_e32 v39, 0
	v_mov_b32_e32 v37, 0
	v_mov_b32_e32 v38, 0
	v_mov_b32_e32 v35, 0
	v_mov_b32_e32 v36, 0
	v_mov_b32_e32 v33, 0
	v_mov_b32_e32 v34, 0
	v_mov_b32_e32 v31, 0
	v_mov_b32_e32 v32, 0
	v_mov_b32_e32 v29, 0
	v_mov_b32_e32 v30, 0
	v_mov_b32_e32 v20, 0
	v_mov_b32_e32 v22, 0
	v_mov_b32_e32 v21, 0
	s_waitcnt lgkmcnt(0)
	s_barrier
	s_cbranch_vccnz .LBB0_1273
	v_add_co_u32_e32 v4, vcc, 0x8000, v6
	s_nop 1
	v_addc_co_u32_e32 v5, vcc, 0, v7, vcc
	global_load_ushort v112, v[4:5], off offset:2048
	global_load_ushort v113, v[4:5], off
	v_add_co_u32_e32 v4, vcc, 0x9000, v6
	s_nop 1
	v_addc_co_u32_e32 v5, vcc, 0, v7, vcc
	global_load_ushort v114, v[4:5], off offset:2048
	global_load_ushort v115, v[4:5], off
	v_add_co_u32_e32 v4, vcc, 0xa000, v6
	s_nop 1
	v_addc_co_u32_e32 v5, vcc, 0, v7, vcc
	global_load_ushort v116, v[4:5], off offset:2048
	global_load_ushort v117, v[4:5], off
	v_add_co_u32_e32 v4, vcc, 0xb000, v6
	s_nop 1
	v_addc_co_u32_e32 v5, vcc, 0, v7, vcc
	global_load_ushort v118, v[4:5], off offset:2048
	global_load_ushort v119, v[4:5], off
	v_add_co_u32_e32 v4, vcc, 0xc000, v6
	s_nop 1
	v_addc_co_u32_e32 v5, vcc, 0, v7, vcc
	global_load_ushort v120, v[4:5], off offset:2048
	global_load_ushort v121, v[4:5], off
	v_add_co_u32_e32 v4, vcc, 0xd000, v6
	s_nop 1
	v_addc_co_u32_e32 v5, vcc, 0, v7, vcc
	global_load_ushort v122, v[4:5], off offset:2048
	global_load_ushort v123, v[4:5], off
	v_add_co_u32_e32 v4, vcc, 0xe000, v6
	s_nop 1
	v_addc_co_u32_e32 v5, vcc, 0, v7, vcc
	global_load_ushort v124, v[4:5], off offset:2048
	global_load_ushort v125, v[4:5], off
	v_add_co_u32_e32 v4, vcc, 0xf000, v6
	s_nop 1
	v_addc_co_u32_e32 v5, vcc, 0, v7, vcc
	global_load_ushort v126, v[4:5], off offset:2048
	global_load_ushort v127, v[4:5], off
	s_waitcnt vmcnt(0)
	v_lshlrev_b32_e32 v40, 16, v112
	v_lshlrev_b32_e32 v41, 16, v113
	v_lshlrev_b32_e32 v37, 16, v114
	v_lshlrev_b32_e32 v39, 16, v115
	v_lshlrev_b32_e32 v35, 16, v116
	v_lshlrev_b32_e32 v38, 16, v117
	v_lshlrev_b32_e32 v33, 16, v118
	v_lshlrev_b32_e32 v36, 16, v119
	v_lshlrev_b32_e32 v31, 16, v120
	v_lshlrev_b32_e32 v34, 16, v121
	v_lshlrev_b32_e32 v29, 16, v122
	v_lshlrev_b32_e32 v32, 16, v123
	v_lshlrev_b32_e32 v20, 16, v124
	v_lshlrev_b32_e32 v30, 16, v125
	v_lshlrev_b32_e32 v21, 16, v126
	v_lshlrev_b32_e32 v22, 16, v127

.LBB0_1312:
	s_or_b64 exec, exec, s[10:11]
	s_and_b64 vcc, exec, s[6:7]
	s_mov_b64 s[6:7], -1
	s_cbranch_vccnz .LBB0_1314
	v_add_co_u32_e32 v24, vcc, 0x10000, v6
	s_nop 1
	v_addc_co_u32_e32 v25, vcc, 0, v7, vcc
	global_load_ushort v112, v[24:25], off offset:2048
	global_load_ushort v113, v[24:25], off
	v_add_co_u32_e32 v24, vcc, 0x11000, v6
	s_nop 1
	v_addc_co_u32_e32 v25, vcc, 0, v7, vcc
	global_load_ushort v114, v[24:25], off offset:2048
	global_load_ushort v115, v[24:25], off
	v_add_co_u32_e32 v24, vcc, 0x12000, v6
	s_nop 1
	v_addc_co_u32_e32 v25, vcc, 0, v7, vcc
	global_load_ushort v116, v[24:25], off offset:2048
	global_load_ushort v117, v[24:25], off
	v_add_co_u32_e32 v24, vcc, 0x13000, v6
	s_nop 1
	v_addc_co_u32_e32 v25, vcc, 0, v7, vcc
	global_load_ushort v118, v[24:25], off offset:2048
	global_load_ushort v119, v[24:25], off
	v_add_co_u32_e32 v24, vcc, 0x14000, v6
	s_nop 1
	v_addc_co_u32_e32 v25, vcc, 0, v7, vcc
	global_load_ushort v120, v[24:25], off offset:2048
	global_load_ushort v121, v[24:25], off
	v_add_co_u32_e32 v24, vcc, 0x15000, v6
	s_nop 1
	v_addc_co_u32_e32 v25, vcc, 0, v7, vcc
	global_load_ushort v122, v[24:25], off offset:2048
	global_load_ushort v123, v[24:25], off
	v_add_co_u32_e32 v24, vcc, 0x16000, v6
	s_nop 1
	v_addc_co_u32_e32 v25, vcc, 0, v7, vcc
	global_load_ushort v124, v[24:25], off offset:2048
	global_load_ushort v125, v[24:25], off
	s_waitcnt vmcnt(0)
	v_lshlrev_b32_e32 v53, 16, v112
	v_lshlrev_b32_e32 v54, 16, v113
	v_lshlrev_b32_e32 v51, 16, v114
	v_lshlrev_b32_e32 v52, 16, v115
	v_lshlrev_b32_e32 v48, 16, v116
	v_lshlrev_b32_e32 v50, 16, v117
	v_lshlrev_b32_e32 v47, 16, v118
	v_lshlrev_b32_e32 v49, 16, v119
	v_lshlrev_b32_e32 v44, 16, v120
	v_lshlrev_b32_e32 v46, 16, v121
	v_lshlrev_b32_e32 v42, 16, v122
	v_lshlrev_b32_e32 v45, 16, v123
	v_lshlrev_b32_e32 v23, 16, v124
	v_lshlrev_b32_e32 v43, 16, v125
	v_add_co_u32_e32 v24, vcc, 0x17000, v6
	s_nop 1
	v_addc_co_u32_e32 v25, vcc, 0, v7, vcc
	global_load_ushort v55, v[24:25], off offset:2048
	s_nop 0
	global_load_ushort v24, v[24:25], off
	s_waitcnt vmcnt(0)
	v_lshlrev_b32_e32 v25, 16, v24
	v_lshlrev_b32_e32 v24, 16, v55
	s_cbranch_execz .LBB0_1315
	s_branch .LBB0_1316

.LBB0_1901:
	s_or_b64 exec, exec, s[0:1]
	s_and_b32 s34, s68, 7
	s_ashr_i32 s76, s4, 6
	s_lshl_b64 s[24:25], s[22:23], 13
	s_ashr_i32 s0, s71, 31
	s_add_u32 s1, s24, s71
	s_addc_u32 s0, s25, s0
	s_lshl_b32 s8, s76, 5
	s_ashr_i32 s6, s8, 31
	s_add_u32 s30, s1, s8
	s_addc_u32 s31, s0, s6
	s_lshl_b64 s[0:1], s[30:31], 10
	s_add_u32 s0, s96, s0
	s_addc_u32 s1, s97, s1
	s_lshl_b32 s35, s34, 7
	s_add_u32 s6, s0, s35
	s_addc_u32 s7, s1, 0
	s_lshl_b64 s[0:1], s[22:23], 23
	v_readlane_b32 s2, v254, 23
	v_readlane_b32 s3, v254, 24
	s_add_u32 s23, s2, s0
	s_addc_u32 s27, s3, s1
	s_add_u32 s26, s23, s35
	s_addc_u32 s27, s27, 0
	s_lshl_b32 s28, s76, 3
	v_and_b32_e32 v202, 63, v38
	s_ashr_i32 s29, s28, 31
	v_readlane_b32 s2, v254, 25
	v_lshlrev_b32_e32 v2, 10, v202
	v_readlane_b32 s3, v254, 26
	s_add_u32 s0, s2, s0
	v_lshl_add_u64 v[4:5], s[26:27], 0, v[2:3]
	s_addc_u32 s1, s3, s1
	v_lshl_add_u64 v[186:187], s[28:29], 1, v[4:5]
	v_bfe_u32 v220, v38, 2, 6
	v_bfe_u32 v221, v38, 4, 2
	v_and_b32_e32 v222, 3, v38
	v_xor_b32_e32 v221, v221, v222
	v_bfe_u32 v222, v38, 8, 1
	v_lshl_add_u32 v221, v222, 2, v221
	v_lshlrev_b32_e32 v221, 4, v221
	v_lshl_add_u32 v220, v220, 10, v221
	v_mov_b32_e32 v221, 0
	v_lshl_add_u64 v[186:187], s[26:27], 0, v[220:221]
	s_add_u32 s28, s0, s35
	s_addc_u32 s29, s1, 0
	s_lshl_b32 s0, s76, 4
	v_bfe_u32 v2, v38, 2, 4
	v_and_or_b32 v2, s0, 48, v2
	s_ashr_i32 s0, s4, 3
	v_lshlrev_b32_e32 v2, 10, v2
	s_andn2_b32 s0, s0, 31
	v_lshl_add_u64 v[4:5], s[28:29], 0, v[2:3]
	s_ashr_i32 s1, s0, 31
	v_lshl_add_u64 v[4:5], s[0:1], 1, v[4:5]
	s_lshl_b32 s0, s76, 10
	v_lshlrev_b32_e32 v203, 3, v38
	s_cmp_lg_u32 16, -1
	s_waitcnt vmcnt(0) lgkmcnt(0)
	v_and_b32_e32 v39, 24, v203
	s_cselect_b32 s1, 16, 0
	v_bfe_u32 v194, v38, 5, 1
	v_lshlrev_b32_e32 v2, 1, v39
	s_add_i32 s77, s0, s1
	s_mov_b32 s1, m0
	s_mov_b32 m0, s77
	s_nop 0
	global_load_lds_dwordx4 v[186:187], off
	s_mov_b32 m0, s1
	v_and_b32_e32 v204, 31, v38
	v_lshl_add_u64 v[36:37], v[4:5], 0, v[2:3]
	s_add_i32 s78, s77, 0x6000
	s_mov_b32 s1, m0
	s_mov_b32 m0, s78
	s_nop 0
	global_load_lds_dwordx4 v[36:37], off
	s_mov_b32 m0, s1
	v_lshlrev_b32_e32 v195, 4, v194
	v_lshl_add_u64 v[4:5], v[186:187], 0, s[10:11]
	s_add_i32 s1, s77, 0x2000
	s_mov_b32 s23, m0
	s_mov_b32 m0, s1
	s_nop 0
	global_load_lds_dwordx4 v[4:5], off
	s_mov_b32 m0, s23
	v_lshl_or_b32 v2, v204, 10, v195
	global_load_dwordx4 v[126:129], v2, s[6:7]
	global_load_dwordx4 v[122:125], v2, s[6:7] offset:32
	global_load_dwordx4 v[118:121], v2, s[6:7] offset:64
	global_load_dwordx4 v[114:117], v2, s[6:7] offset:96
	v_lshlrev_b32_e32 v2, 10, v194
	v_lshlrev_b32_e32 v4, 4, v204
	v_add3_u32 v210, 16, v2, v4
	v_bfe_u32 v222, v204, 2, 2
	v_and_b32_e32 v223, 1, v222
	v_xor_b32_e32 v223, v223, v194
	v_and_b32_e32 v222, 2, v222
	v_or_b32_e32 v222, v222, v223
	v_lshlrev_b32_e32 v222, 4, v222
	v_lshl_add_u32 v210, v204, 6, v222
	v_xor_b32_e32 v224, 32, v210
	v_add_u32_e32 v210, 16, v210
	v_add_u32_e32 v224, 16, v224
	v_lshl_add_u64 v[4:5], v[186:187], 0, s[12:13]
	s_add_i32 s1, s77, 0x4000
	s_mov_b32 s6, m0
	s_mov_b32 m0, s1
	s_nop 0
	global_load_lds_dwordx4 v[4:5], off
	s_mov_b32 m0, s6
	v_add_u32_e32 v2, 16, v195
	s_waitcnt vmcnt(3) lgkmcnt(0)
	s_barrier
	v_add_u32_e32 v2, 0x14800, v2
	ds_read_b128 v[20:23], v210
	ds_read_b128 v[4:7], v2
	ds_read_b128 v[8:11], v2 offset:32
	ds_read_b128 v[12:15], v2 offset:64
	ds_read_b128 v[16:19], v2 offset:96
	ds_read_b128 v[42:45], v210 offset:2048
	v_or_b32_e32 v209, s8, v204
	s_cmp_eq_u32 s5, 0
	v_lshlrev_b32_e32 v205, 2, v194
	s_waitcnt vmcnt(3) lgkmcnt(1)
	v_mfma_f32_32x32x16_bf16 v[4:19], v[20:23], v[126:129], v[4:19]
	ds_read_b128 v[20:23], v2 offset:128
	ds_read_b128 v[24:27], v2 offset:160
	ds_read_b128 v[28:31], v2 offset:192
	ds_read_b128 v[32:35], v2 offset:224
	s_waitcnt lgkmcnt(0)
	v_mfma_f32_32x32x16_bf16 v[20:35], v[42:45], v[126:129], v[20:35]
	ds_read_b128 v[42:45], v224
	ds_read_b128 v[46:49], v224 offset:2048
	s_waitcnt vmcnt(2) lgkmcnt(1)
	v_mfma_f32_32x32x16_bf16 v[4:19], v[42:45], v[122:125], v[4:19]
	s_waitcnt lgkmcnt(0)
	v_mfma_f32_32x32x16_bf16 v[20:35], v[46:49], v[122:125], v[20:35]
	ds_read_b128 v[42:45], v210 offset:4096
	ds_read_b128 v[46:49], v210 offset:6144
	s_waitcnt vmcnt(1) lgkmcnt(1)
	v_mfma_f32_32x32x16_bf16 v[4:19], v[42:45], v[118:121], v[4:19]
	s_waitcnt lgkmcnt(0)
	v_mfma_f32_32x32x16_bf16 v[20:35], v[46:49], v[118:121], v[20:35]
	ds_read_b128 v[42:45], v224 offset:4096
	ds_read_b128 v[46:49], v224 offset:6144
	s_waitcnt vmcnt(0) lgkmcnt(1)
	v_mfma_f32_32x32x16_bf16 v[4:19], v[42:45], v[114:117], v[4:19]
	s_waitcnt lgkmcnt(0)
	v_mfma_f32_32x32x16_bf16 v[20:35], v[46:49], v[114:117], v[20:35]
	s_cbranch_scc0 .LBB0_1903
	v_lshlrev_b32_e32 v2, 2, v194
	v_or_b32_e32 v41, 32, v2
	v_cmp_le_i32_e32 vcc, v41, v209
	v_or_b32_e32 v41, 33, v2
	s_nop 6
	v_cndmask_b32_e32 v20, v199, v20, vcc
	v_cmp_lt_i32_e32 vcc, v2, v209
	s_nop 1
	v_cndmask_b32_e32 v5, v199, v5, vcc
	v_cmp_le_i32_e32 vcc, v2, v209
	s_nop 1
	v_cndmask_b32_e32 v4, v199, v4, vcc
	v_cmp_le_i32_e32 vcc, v41, v209
	v_or_b32_e32 v41, 2, v2
	s_nop 0
	v_cndmask_b32_e32 v21, v199, v21, vcc
	v_cmp_le_i32_e32 vcc, v41, v209
	v_or_b32_e32 v41, 34, v2
	s_nop 0
	v_cndmask_b32_e32 v6, v199, v6, vcc
	v_cmp_le_i32_e32 vcc, v41, v209
	v_or_b32_e32 v41, 3, v2
	s_nop 0
	v_cndmask_b32_e32 v22, v199, v22, vcc
	v_cmp_le_i32_e32 vcc, v41, v209
	v_or_b32_e32 v41, 35, v2
	s_nop 0
	v_cndmask_b32_e32 v7, v199, v7, vcc
	v_cmp_le_i32_e32 vcc, v41, v209
	v_or_b32_e32 v41, 8, v2
	s_nop 0
	v_cndmask_b32_e32 v23, v199, v23, vcc
	v_cmp_le_i32_e32 vcc, v41, v209
	v_or_b32_e32 v41, 40, v2
	s_nop 0
	v_cndmask_b32_e32 v8, v199, v8, vcc
	v_cmp_le_i32_e32 vcc, v41, v209
	v_or_b32_e32 v41, 9, v2
	s_nop 0
	v_cndmask_b32_e32 v24, v199, v24, vcc
	v_cmp_le_i32_e32 vcc, v41, v209
	v_or_b32_e32 v41, 41, v2
	s_nop 0
	v_cndmask_b32_e32 v9, v199, v9, vcc
	v_cmp_le_i32_e32 vcc, v41, v209
	v_or_b32_e32 v41, 10, v2
	s_nop 0
	v_cndmask_b32_e32 v25, v199, v25, vcc
	v_cmp_le_i32_e32 vcc, v41, v209
	v_or_b32_e32 v41, 42, v2
	s_nop 0
	v_cndmask_b32_e32 v10, v199, v10, vcc
	v_cmp_le_i32_e32 vcc, v41, v209
	v_or_b32_e32 v41, 11, v2
	s_nop 0
	v_cndmask_b32_e32 v26, v199, v26, vcc
	v_cmp_le_i32_e32 vcc, v41, v209
	v_or_b32_e32 v41, 43, v2
	s_nop 0
	v_cndmask_b32_e32 v11, v199, v11, vcc
	v_cmp_le_i32_e32 vcc, v41, v209
	v_or_b32_e32 v41, 16, v2
	s_nop 0
	v_cndmask_b32_e32 v27, v199, v27, vcc
	v_cmp_le_i32_e32 vcc, v41, v209
	v_or_b32_e32 v41, 48, v2
	s_nop 0
	v_cndmask_b32_e32 v12, v199, v12, vcc
	v_cmp_le_i32_e32 vcc, v41, v209
	v_or_b32_e32 v41, 17, v2
	s_nop 0
	v_cndmask_b32_e32 v28, v199, v28, vcc
	v_cmp_le_i32_e32 vcc, v41, v209
	v_or_b32_e32 v41, 49, v2
	s_nop 0
	v_cndmask_b32_e32 v13, v199, v13, vcc
	v_cmp_le_i32_e32 vcc, v41, v209
	v_or_b32_e32 v41, 18, v2
	s_nop 0
	v_cndmask_b32_e32 v29, v199, v29, vcc
	v_cmp_le_i32_e32 vcc, v41, v209
	v_or_b32_e32 v41, 50, v2
	s_nop 0
	v_cndmask_b32_e32 v14, v199, v14, vcc
	v_cmp_le_i32_e32 vcc, v41, v209
	v_or_b32_e32 v41, 19, v2
	s_nop 0
	v_cndmask_b32_e32 v30, v199, v30, vcc
	v_cmp_le_i32_e32 vcc, v41, v209
	v_or_b32_e32 v41, 51, v2
	s_nop 0
	v_cndmask_b32_e32 v15, v199, v15, vcc
	v_cmp_le_i32_e32 vcc, v41, v209
	v_or_b32_e32 v41, 24, v2
	s_nop 0
	v_cndmask_b32_e32 v31, v199, v31, vcc
	v_cmp_le_i32_e32 vcc, v41, v209
	v_or_b32_e32 v41, 56, v2
	s_nop 0
	v_cndmask_b32_e32 v16, v199, v16, vcc
	v_cmp_le_i32_e32 vcc, v41, v209
	v_or_b32_e32 v41, 25, v2
	s_nop 0
	v_cndmask_b32_e32 v32, v199, v32, vcc
	v_cmp_le_i32_e32 vcc, v41, v209
	v_or_b32_e32 v41, 57, v2
	s_nop 0
	v_cndmask_b32_e32 v17, v199, v17, vcc
	v_cmp_le_i32_e32 vcc, v41, v209
	v_or_b32_e32 v41, 26, v2
	s_nop 0
	v_cndmask_b32_e32 v33, v199, v33, vcc
	v_cmp_le_i32_e32 vcc, v41, v209
	v_or_b32_e32 v41, 58, v2
	s_nop 0
	v_cndmask_b32_e32 v18, v199, v18, vcc
	v_cmp_le_i32_e32 vcc, v41, v209
	v_or_b32_e32 v41, 27, v2
	v_or_b32_e32 v2, 59, v2
	v_cndmask_b32_e32 v34, v199, v34, vcc
	v_cmp_le_i32_e32 vcc, v41, v209
	s_nop 1
	v_cndmask_b32_e32 v19, v199, v19, vcc
	v_cmp_le_i32_e32 vcc, v2, v209
	s_nop 1
	v_cndmask_b32_e32 v35, v199, v35, vcc
.LBB0_1903:
	v_lshlrev_b32_e32 v2, 1, v38
	v_and_b32_e32 v2, 32, v2
	v_add3_u32 v2, 16, v2, v39
	v_lshlrev_b32_e32 v38, 8, v194
	v_and_b32_e32 v39, 0xc0, v40
	v_add3_u32 v206, v2, v38, v39
	s_nop 2
	v_max_f32_e32 v2, v5, v5
	v_max_f32_e32 v38, v4, v4
	v_max_f32_e32 v2, v38, v2
	v_max3_f32 v38, v6, v7, v21
	v_max3_f32 v2, v2, v20, v22
	v_max3_f32 v2, v2, v23, v8
	v_max3_f32 v38, v38, v10, v11
	v_max3_f32 v2, v2, v9, v24
	v_max3_f32 v38, v38, v26, v27
	v_max3_f32 v2, v2, v25, v12
	v_max3_f32 v38, v38, v14, v15
	v_max3_f32 v2, v2, v13, v28
	v_max3_f32 v38, v38, v30, v31
	v_max3_f32 v2, v2, v29, v16
	v_max3_f32 v38, v38, v18, v19
	v_max3_f32 v2, v2, v17, v32
	v_max3_f32 v38, v38, v34, v35
	v_max3_f32 v2, v2, v33, v38
	v_mov_b32_e32 v38, v2
	s_nop 1
	v_permlane32_swap_b32_e32 v2, v38
	v_max_f32_e32 v38, v38, v38
	v_max_f32_e32 v2, v2, v2
	v_max_f32_e32 v208, v2, v38
	v_sub_f32_e32 v2, v4, v208
	v_exp_f32_e32 v98, v2
	v_sub_f32_e32 v2, v20, v208
	v_exp_f32_e32 v82, v2
	v_sub_f32_e32 v2, v5, v208
	v_exp_f32_e32 v99, v2
	v_sub_f32_e32 v2, v21, v208
	v_exp_f32_e32 v83, v2
	v_sub_f32_e32 v2, v6, v208
	v_exp_f32_e32 v100, v2
	v_sub_f32_e32 v2, v22, v208
	v_exp_f32_e32 v84, v2
	v_sub_f32_e32 v2, v7, v208
	v_exp_f32_e32 v101, v2
	v_sub_f32_e32 v2, v23, v208
	v_exp_f32_e32 v85, v2
	v_sub_f32_e32 v2, v8, v208
	v_exp_f32_e32 v102, v2
	v_sub_f32_e32 v2, v24, v208
	v_exp_f32_e32 v86, v2
	v_sub_f32_e32 v2, v9, v208
	v_exp_f32_e32 v103, v2
	v_sub_f32_e32 v2, v25, v208
	v_exp_f32_e32 v87, v2
	v_sub_f32_e32 v2, v10, v208
	v_exp_f32_e32 v104, v2
	v_sub_f32_e32 v2, v26, v208
	v_exp_f32_e32 v88, v2
	v_sub_f32_e32 v2, v11, v208
	v_exp_f32_e32 v105, v2
	v_sub_f32_e32 v2, v27, v208
	v_exp_f32_e32 v89, v2
	v_sub_f32_e32 v2, v12, v208
	v_exp_f32_e32 v106, v2
	v_sub_f32_e32 v2, v28, v208
	v_exp_f32_e32 v90, v2
	v_sub_f32_e32 v2, v13, v208
	v_exp_f32_e32 v107, v2
	v_sub_f32_e32 v2, v29, v208
	v_exp_f32_e32 v91, v2
	v_sub_f32_e32 v2, v14, v208
	v_exp_f32_e32 v108, v2
	v_sub_f32_e32 v2, v30, v208
	v_exp_f32_e32 v92, v2
	v_sub_f32_e32 v2, v15, v208
	v_exp_f32_e32 v109, v2
	v_sub_f32_e32 v2, v31, v208
	v_exp_f32_e32 v93, v2
	v_sub_f32_e32 v2, v16, v208
	s_add_i32 s1, s71, 0x100
	v_exp_f32_e32 v110, v2
	v_sub_f32_e32 v2, v32, v208
	s_ashr_i32 s79, s1, 6
	s_and_b32 s1, s4, 0x3fffffc0
	v_exp_f32_e32 v94, v2
	v_sub_f32_e32 v2, v17, v208
	s_lshl_b32 s1, s1, 2
	v_exp_f32_e32 v111, v2
	v_sub_f32_e32 v2, v33, v208
	s_add_i32 s23, s1, 16
	v_exp_f32_e32 v95, v2
	v_sub_f32_e32 v2, v18, v208
	s_waitcnt vmcnt(0) lgkmcnt(0)
	s_barrier
	v_exp_f32_e32 v112, v2
	v_sub_f32_e32 v2, v34, v208
	v_lshl_add_u64 v[4:5], v[186:187], 0, s[14:15]
	s_mov_b32 s1, m0
	s_mov_b32 m0, s77
	s_nop 0
	global_load_lds_dwordx4 v[4:5], off
	s_mov_b32 m0, s1
	s_cmp_lg_u32 16, -1
	v_exp_f32_e32 v96, v2
	v_sub_f32_e32 v2, v19, v208
	s_cselect_b32 s1, 16, 0
	v_exp_f32_e32 v113, v2
	v_sub_f32_e32 v2, v35, v208
	s_add_i32 s0, s1, s0
	v_exp_f32_e32 v97, v2
	v_lshl_add_u64 v[188:189], v[36:37], 0, s[10:11]
	s_add_i32 s0, s0, 0x8000
	s_mov_b32 s1, m0
	s_mov_b32 m0, s0
	s_nop 0
	global_load_lds_dwordx4 v[188:189], off
	s_mov_b32 m0, s1
	v_lshl_add_u32 v2, v194, 4, 16
	ds_read_b128 v[174:177], v210 offset:8192
	ds_read_b128 v[170:173], v210 offset:10240
	ds_read_b128 v[166:169], v224 offset:8192
	ds_read_b128 v[162:165], v224 offset:10240
	ds_read_b128 v[158:161], v210 offset:12288
	ds_read_b128 v[154:157], v210 offset:14336
	ds_read_b128 v[150:153], v224 offset:12288
	ds_read_b128 v[146:149], v224 offset:14336
	s_waitcnt vmcnt(2) lgkmcnt(0)
	s_barrier
	v_add_u32_e32 v2, 0x14900, v2
	ds_read_b128 v[66:69], v2
	ds_read_b128 v[70:73], v2 offset:32
	ds_read_b128 v[50:53], v2 offset:128
	ds_read_b128 v[54:57], v2 offset:160
	ds_read_b128 v[74:77], v2 offset:64
	ds_read_b128 v[78:81], v2 offset:96
	ds_read_b128 v[58:61], v2 offset:192
	ds_read_b128 v[62:65], v2 offset:224
	s_mov_b32 s8, 1
	s_mov_b32 s35, 0
	s_cmp_lt_i32 s79, 7
	v_cmp_gt_u32_e64 s[0:1], 32, v202
	v_lshl_add_u32 v207, v204, 2, s23
	s_cbranch_scc1 .LBB0_1919
	v_mov_b32_e32 v16, v3
	v_mov_b32_e32 v17, v3
	v_lshl_add_u64 v[190:191], v[36:37], 0, s[14:15]
	v_mov_b32_e32 v2, v3
	v_mov_b32_e32 v4, v3
	v_mov_b32_e32 v5, v3
	v_mov_b32_e32 v6, v3
	v_mov_b32_e32 v7, v3
	v_mov_b32_e32 v8, v3
	v_mov_b32_e32 v9, v3
	v_mov_b32_e32 v10, v3
	v_mov_b32_e32 v11, v3
	v_mov_b32_e32 v12, v3
	v_mov_b32_e32 v13, v3
	v_mov_b32_e32 v14, v3
	v_mov_b32_e32 v15, v3
	v_mov_b64_e32 v[48:49], v[16:17]
	v_mov_b64_e32 v[32:33], v[16:17]
	s_add_i32 s36, s79, -5
	v_add_u32_e32 v196, s65, v195
	v_lshl_add_u64 v[192:193], v[186:187], 0, s[16:17]
	s_mov_b32 s4, 0
	s_movk_i32 s35, 0x4000
	s_movk_i32 s37, 0x2000
	v_mov_b32_e32 v211, 0
	v_mov_b64_e32 v[46:47], v[14:15]
	v_mov_b64_e32 v[44:45], v[12:13]
	v_mov_b64_e32 v[42:43], v[10:11]
	v_mov_b64_e32 v[40:41], v[8:9]
	v_mov_b64_e32 v[38:39], v[6:7]
	v_mov_b64_e32 v[36:37], v[4:5]
	v_mov_b64_e32 v[34:35], v[2:3]
	v_mov_b64_e32 v[30:31], v[14:15]
	v_mov_b64_e32 v[28:29], v[12:13]
	v_mov_b64_e32 v[26:27], v[10:11]
	v_mov_b64_e32 v[24:25], v[8:9]
	v_mov_b64_e32 v[22:23], v[6:7]
	v_mov_b64_e32 v[20:21], v[4:5]
	v_mov_b64_e32 v[18:19], v[2:3]

.LBB0_1909:
	ds_read_b128 v[98:101], v196
	ds_read_b128 v[102:105], v196 offset:32
	ds_read_b128 v[82:85], v196 offset:128
	ds_read_b128 v[86:89], v196 offset:160
	ds_read_b128 v[106:109], v196 offset:64
	ds_read_b128 v[110:113], v196 offset:96
	ds_read_b128 v[90:93], v196 offset:192
	ds_read_b128 v[94:97], v196 offset:224
	s_waitcnt lgkmcnt(14)
	v_mfma_f32_32x32x16_bf16 v[34:49], v[142:145], v[182:185], v[34:49]
	v_sub_f32_e32 v2, v66, v208
	v_exp_f32_e32 v66, v2
	v_sub_f32_e32 v2, v67, v208
	v_exp_f32_e32 v67, v2
	v_sub_f32_e32 v2, v68, v208
	v_exp_f32_e32 v68, v2
	v_sub_f32_e32 v2, v69, v208
	v_exp_f32_e32 v69, v2
	v_mfma_f32_32x32x16_bf16 v[18:33], v[142:145], v[178:181], v[18:33]
	v_sub_f32_e32 v2, v70, v208
	v_exp_f32_e32 v70, v2
	v_sub_f32_e32 v2, v71, v208
	v_exp_f32_e32 v71, v2
	v_sub_f32_e32 v2, v72, v208
	v_exp_f32_e32 v72, v2
	v_sub_f32_e32 v2, v73, v208
	v_exp_f32_e32 v73, v2
	v_add_u32_e32 v2, s35, v210
	v_add_u32_e32 v226, s35, v224
	ds_read_b128 v[162:165], v2
	ds_read_b128 v[154:157], v2 offset:2048
	v_mfma_f32_32x32x16_bf16 v[34:49], v[138:141], v[12:15], v[34:49]
	v_sub_f32_e32 v12, v74, v208
	v_exp_f32_e32 v74, v12
	v_sub_f32_e32 v12, v75, v208
	v_exp_f32_e32 v75, v12
	v_sub_f32_e32 v12, v76, v208
	v_exp_f32_e32 v76, v12
	v_sub_f32_e32 v12, v77, v208
	v_exp_f32_e32 v77, v12
	ds_read_b128 v[158:161], v226
	ds_read_b128 v[146:149], v226 offset:2048
	v_mfma_f32_32x32x16_bf16 v[18:33], v[138:141], v[8:11], v[18:33]
	v_sub_f32_e32 v8, v78, v208
	v_exp_f32_e32 v78, v8
	v_sub_f32_e32 v8, v79, v208
	v_exp_f32_e32 v79, v8
	v_sub_f32_e32 v8, v80, v208
	v_exp_f32_e32 v80, v8
	v_sub_f32_e32 v8, v81, v208
	v_exp_f32_e32 v81, v8
	ds_read_b128 v[150:153], v2 offset:4096
	ds_read_b128 v[8:11], v2 offset:6144
	v_mfma_f32_32x32x16_bf16 v[34:49], v[134:137], v[4:7], v[34:49]
	v_sub_f32_e32 v4, v50, v208
	v_exp_f32_e32 v50, v4
	v_sub_f32_e32 v4, v51, v208
	v_exp_f32_e32 v51, v4
	v_sub_f32_e32 v4, v52, v208
	v_exp_f32_e32 v52, v4
	v_sub_f32_e32 v4, v53, v208
	v_exp_f32_e32 v53, v4
	ds_read_b128 v[12:15], v226 offset:4096
	ds_read_b128 v[4:7], v226 offset:6144
	s_waitcnt lgkmcnt(14)
	v_mfma_f32_32x32x16_bf16 v[18:33], v[134:137], v[174:177], v[18:33]
	v_sub_f32_e32 v2, v54, v208
	v_exp_f32_e32 v54, v2
	v_sub_f32_e32 v2, v55, v208
	v_exp_f32_e32 v55, v2
	v_sub_f32_e32 v2, v56, v208
	v_exp_f32_e32 v56, v2
	v_sub_f32_e32 v2, v57, v208
	v_exp_f32_e32 v57, v2
	v_mfma_f32_32x32x16_bf16 v[34:49], v[130:133], v[170:173], v[34:49]
	v_sub_f32_e32 v2, v58, v208
	v_exp_f32_e32 v58, v2
	v_sub_f32_e32 v2, v59, v208
	v_exp_f32_e32 v59, v2
	v_sub_f32_e32 v2, v60, v208
	v_exp_f32_e32 v60, v2
	v_sub_f32_e32 v2, v61, v208
	v_exp_f32_e32 v61, v2
	v_mfma_f32_32x32x16_bf16 v[18:33], v[130:133], v[166:169], v[18:33]
	v_sub_f32_e32 v2, v62, v208
	v_exp_f32_e32 v62, v2
	v_sub_f32_e32 v2, v63, v208
	v_exp_f32_e32 v63, v2
	v_sub_f32_e32 v2, v64, v208
	v_exp_f32_e32 v64, v2
	v_sub_f32_e32 v2, v65, v208
	v_exp_f32_e32 v65, v2
	s_waitcnt vmcnt(2) lgkmcnt(0)
	s_barrier
	s_andn2_b64 vcc, exec, s[6:7]
	v_add_u32_e32 v2, s23, v195
	s_cbranch_vccnz .LBB0_1911
	ds_read_b128 v[166:169], v2 offset:49248
	ds_read_b128 v[170:173], v2 offset:49216
	ds_read_b128 v[174:177], v2 offset:49184
	ds_read_b128 v[178:181], v2 offset:49152
	s_waitcnt lgkmcnt(3)
	v_pk_mul_f32 v[46:47], v[46:47], v[166:167]
	s_waitcnt lgkmcnt(2)
	v_pk_mul_f32 v[42:43], v[42:43], v[170:171]
	s_waitcnt lgkmcnt(1)
	v_pk_mul_f32 v[38:39], v[38:39], v[174:175]
	v_pk_mul_f32 v[48:49], v[48:49], v[168:169]
	v_pk_mul_f32 v[44:45], v[44:45], v[172:173]
	v_pk_mul_f32 v[40:41], v[40:41], v[176:177]
	s_waitcnt lgkmcnt(0)
	v_pk_mul_f32 v[36:37], v[36:37], v[180:181]
	v_pk_mul_f32 v[34:35], v[34:35], v[178:179]
	v_pk_mul_f32 v[30:31], v[30:31], v[166:167]
	v_pk_mul_f32 v[26:27], v[26:27], v[170:171]
	v_pk_mul_f32 v[22:23], v[22:23], v[174:175]
	v_pk_mul_f32 v[32:33], v[32:33], v[168:169]
	v_pk_mul_f32 v[28:29], v[28:29], v[172:173]
	v_pk_mul_f32 v[24:25], v[24:25], v[176:177]
	v_pk_mul_f32 v[20:21], v[20:21], v[180:181]
	v_pk_mul_f32 v[18:19], v[18:19], v[178:179]

.LBB0_1915:
	ds_read_b128 v[66:69], v196 offset:256
	ds_read_b128 v[70:73], v196 offset:288
	ds_read_b128 v[50:53], v196 offset:384
	ds_read_b128 v[54:57], v196 offset:416
	ds_read_b128 v[74:77], v196 offset:320
	ds_read_b128 v[78:81], v196 offset:352
	ds_read_b128 v[58:61], v196 offset:448
	ds_read_b128 v[62:65], v196 offset:480
	s_waitcnt lgkmcnt(14)
	v_mfma_f32_32x32x16_bf16 v[34:49], v[142:145], v[170:173], v[34:49]
	v_sub_f32_e32 v4, v98, v208
	v_exp_f32_e32 v98, v4
	v_sub_f32_e32 v4, v99, v208
	v_exp_f32_e32 v99, v4
	v_sub_f32_e32 v4, v100, v208
	v_exp_f32_e32 v100, v4
	v_sub_f32_e32 v4, v101, v208
	v_exp_f32_e32 v101, v4
	v_mfma_f32_32x32x16_bf16 v[18:33], v[142:145], v[166:169], v[18:33]
	v_sub_f32_e32 v4, v102, v208
	v_exp_f32_e32 v102, v4
	v_sub_f32_e32 v4, v103, v208
	v_exp_f32_e32 v103, v4
	v_sub_f32_e32 v4, v104, v208
	v_exp_f32_e32 v104, v4
	v_sub_f32_e32 v4, v105, v208
	v_exp_f32_e32 v105, v4
	v_add_u32_e32 v4, s80, v210
	v_add_u32_e32 v226, s80, v224
	ds_read_b128 v[174:177], v4
	ds_read_b128 v[170:173], v4 offset:2048
	v_mfma_f32_32x32x16_bf16 v[34:49], v[138:141], v[162:165], v[34:49]
	v_sub_f32_e32 v5, v106, v208
	v_exp_f32_e32 v106, v5
	v_sub_f32_e32 v5, v107, v208
	v_exp_f32_e32 v107, v5
	v_sub_f32_e32 v5, v108, v208
	v_exp_f32_e32 v108, v5
	v_sub_f32_e32 v5, v109, v208
	v_exp_f32_e32 v109, v5
	ds_read_b128 v[166:169], v226
	ds_read_b128 v[162:165], v226 offset:2048
	v_mfma_f32_32x32x16_bf16 v[18:33], v[138:141], v[154:157], v[18:33]
	v_sub_f32_e32 v5, v110, v208
	v_exp_f32_e32 v110, v5
	v_sub_f32_e32 v5, v111, v208
	v_exp_f32_e32 v111, v5
	v_sub_f32_e32 v5, v112, v208
	v_exp_f32_e32 v112, v5
	v_sub_f32_e32 v5, v113, v208
	v_exp_f32_e32 v113, v5
	ds_read_b128 v[158:161], v4 offset:4096
	ds_read_b128 v[154:157], v4 offset:6144
	v_mfma_f32_32x32x16_bf16 v[34:49], v[134:137], v[146:149], v[34:49]
	v_sub_f32_e32 v5, v82, v208
	v_exp_f32_e32 v82, v5
	v_sub_f32_e32 v5, v83, v208
	v_exp_f32_e32 v83, v5
	v_sub_f32_e32 v5, v84, v208
	v_exp_f32_e32 v84, v5
	v_sub_f32_e32 v5, v85, v208
	v_exp_f32_e32 v85, v5
	ds_read_b128 v[150:153], v226 offset:4096
	ds_read_b128 v[146:149], v226 offset:6144
	s_waitcnt lgkmcnt(14)
	v_mfma_f32_32x32x16_bf16 v[18:33], v[134:137], v[182:185], v[18:33]
	v_sub_f32_e32 v4, v86, v208
	v_exp_f32_e32 v86, v4
	v_sub_f32_e32 v4, v87, v208
	v_exp_f32_e32 v87, v4
	v_sub_f32_e32 v4, v88, v208
	v_exp_f32_e32 v88, v4
	v_sub_f32_e32 v4, v89, v208
	v_exp_f32_e32 v89, v4
	v_mfma_f32_32x32x16_bf16 v[34:49], v[130:133], v[178:181], v[34:49]
	v_sub_f32_e32 v4, v90, v208
	v_exp_f32_e32 v90, v4
	v_sub_f32_e32 v4, v91, v208
	v_exp_f32_e32 v91, v4
	v_sub_f32_e32 v4, v92, v208
	v_exp_f32_e32 v92, v4
	v_sub_f32_e32 v4, v93, v208
	v_exp_f32_e32 v93, v4
	v_mfma_f32_32x32x16_bf16 v[18:33], v[130:133], v[8:11], v[18:33]
	v_sub_f32_e32 v4, v94, v208
	v_exp_f32_e32 v94, v4
	v_sub_f32_e32 v4, v95, v208
	v_exp_f32_e32 v95, v4
	v_sub_f32_e32 v4, v96, v208
	v_exp_f32_e32 v96, v4
	v_sub_f32_e32 v4, v97, v208
	v_exp_f32_e32 v97, v4
	s_waitcnt vmcnt(2) lgkmcnt(0)
	s_barrier
	s_andn2_b64 vcc, exec, s[6:7]
	s_cbranch_vccnz .LBB0_1917
	ds_read_b128 v[4:7], v2 offset:49248
	ds_read_b128 v[8:11], v2 offset:49216
	ds_read_b128 v[12:15], v2 offset:49184
	ds_read_b128 v[178:181], v2 offset:49152
	s_waitcnt lgkmcnt(3)
	v_pk_mul_f32 v[46:47], v[46:47], v[4:5]
	s_waitcnt lgkmcnt(2)
	v_pk_mul_f32 v[42:43], v[42:43], v[8:9]
	s_waitcnt lgkmcnt(1)
	v_pk_mul_f32 v[38:39], v[38:39], v[12:13]
	v_pk_mul_f32 v[48:49], v[48:49], v[6:7]
	v_pk_mul_f32 v[44:45], v[44:45], v[10:11]
	v_pk_mul_f32 v[40:41], v[40:41], v[14:15]
	s_waitcnt lgkmcnt(0)
	v_pk_mul_f32 v[36:37], v[36:37], v[180:181]
	v_pk_mul_f32 v[34:35], v[34:35], v[178:179]
	v_pk_mul_f32 v[30:31], v[30:31], v[4:5]
	v_pk_mul_f32 v[26:27], v[26:27], v[8:9]
	v_pk_mul_f32 v[22:23], v[22:23], v[12:13]
	v_pk_mul_f32 v[32:33], v[32:33], v[6:7]
	v_pk_mul_f32 v[28:29], v[28:29], v[10:11]
	v_pk_mul_f32 v[24:25], v[24:25], v[14:15]
	v_pk_mul_f32 v[20:21], v[20:21], v[180:181]
	v_pk_mul_f32 v[18:19], v[18:19], v[178:179]

.LBB0_1930:
	ds_read_b128 v[98:101], v213
	ds_read_b128 v[102:105], v213 offset:32
	ds_read_b128 v[82:85], v213 offset:128
	ds_read_b128 v[86:89], v213 offset:160
	ds_read_b128 v[106:109], v213 offset:64
	ds_read_b128 v[110:113], v213 offset:96
	ds_read_b128 v[90:93], v213 offset:192
	ds_read_b128 v[94:97], v213 offset:224
	s_waitcnt lgkmcnt(14)
	v_mfma_f32_32x32x16_bf16 v[34:49], v[142:145], v[190:193], v[34:49]
	v_sub_f32_e32 v66, v66, v208
	v_sub_f32_e32 v67, v67, v208
	v_sub_f32_e32 v68, v68, v208
	v_sub_f32_e32 v69, v69, v208
	v_exp_f32_e32 v66, v66
	v_exp_f32_e32 v67, v67
	v_exp_f32_e32 v68, v68
	v_exp_f32_e32 v69, v69
	v_mfma_f32_32x32x16_bf16 v[18:33], v[142:145], v[174:177], v[18:33]
	v_sub_f32_e32 v70, v70, v208
	v_sub_f32_e32 v71, v71, v208
	v_sub_f32_e32 v72, v72, v208
	v_sub_f32_e32 v73, v73, v208
	v_exp_f32_e32 v70, v70
	v_exp_f32_e32 v71, v71
	v_exp_f32_e32 v72, v72
	v_exp_f32_e32 v73, v73
	v_add_u32_e32 v142, s84, v210
	v_add_u32_e32 v226, s84, v224
	ds_read_b128 v[174:177], v142
	ds_read_b128 v[170:173], v142 offset:2048
	v_mfma_f32_32x32x16_bf16 v[34:49], v[138:141], v[186:189], v[34:49]
	v_sub_f32_e32 v74, v74, v208
	v_sub_f32_e32 v75, v75, v208
	v_sub_f32_e32 v76, v76, v208
	v_sub_f32_e32 v77, v77, v208
	v_exp_f32_e32 v74, v74
	v_exp_f32_e32 v75, v75
	v_exp_f32_e32 v76, v76
	v_exp_f32_e32 v77, v77
	ds_read_b128 v[166:169], v226
	ds_read_b128 v[162:165], v226 offset:2048
	v_mfma_f32_32x32x16_bf16 v[18:33], v[138:141], v[182:185], v[18:33]
	v_sub_f32_e32 v78, v78, v208
	v_sub_f32_e32 v79, v79, v208
	v_sub_f32_e32 v80, v80, v208
	v_sub_f32_e32 v81, v81, v208
	v_exp_f32_e32 v78, v78
	v_exp_f32_e32 v79, v79
	v_exp_f32_e32 v80, v80
	v_exp_f32_e32 v81, v81
	ds_read_b128 v[158:161], v142 offset:4096
	ds_read_b128 v[154:157], v142 offset:6144
	v_mfma_f32_32x32x16_bf16 v[34:49], v[134:137], v[178:181], v[34:49]
	v_sub_f32_e32 v50, v50, v208
	v_sub_f32_e32 v51, v51, v208
	v_sub_f32_e32 v52, v52, v208
	v_sub_f32_e32 v53, v53, v208
	v_exp_f32_e32 v50, v50
	v_exp_f32_e32 v51, v51
	v_exp_f32_e32 v52, v52
	v_exp_f32_e32 v53, v53
	ds_read_b128 v[150:153], v226 offset:4096
	ds_read_b128 v[146:149], v226 offset:6144
	s_waitcnt lgkmcnt(14)
	v_mfma_f32_32x32x16_bf16 v[18:33], v[134:137], v[12:15], v[18:33]
	v_sub_f32_e32 v12, v54, v208
	v_exp_f32_e32 v54, v12
	v_sub_f32_e32 v12, v55, v208
	v_exp_f32_e32 v55, v12
	v_sub_f32_e32 v12, v56, v208
	v_exp_f32_e32 v56, v12
	v_sub_f32_e32 v12, v57, v208
	v_exp_f32_e32 v57, v12
	v_mfma_f32_32x32x16_bf16 v[34:49], v[130:133], v[8:11], v[34:49]
	v_sub_f32_e32 v8, v58, v208
	v_exp_f32_e32 v58, v8
	v_sub_f32_e32 v8, v59, v208
	v_exp_f32_e32 v59, v8
	v_sub_f32_e32 v8, v60, v208
	v_exp_f32_e32 v60, v8
	v_sub_f32_e32 v8, v61, v208
	v_exp_f32_e32 v61, v8
	v_mfma_f32_32x32x16_bf16 v[18:33], v[130:133], v[4:7], v[18:33]
	v_sub_f32_e32 v4, v62, v208
	v_exp_f32_e32 v62, v4
	v_sub_f32_e32 v4, v63, v208
	v_exp_f32_e32 v63, v4
	v_sub_f32_e32 v4, v64, v208
	v_exp_f32_e32 v64, v4
	v_sub_f32_e32 v4, v65, v208
	v_exp_f32_e32 v65, v4
	s_mov_b64 s[4:5], -1
	s_and_b64 vcc, exec, s[34:35]
	s_cbranch_vccz .LBB0_1966
	s_add_i32 s4, s8, -2
	s_cmp_ge_i32 s4, s85
	s_mov_b64 s[4:5], -1
	s_cbranch_scc0 .LBB0_1933
	s_waitcnt vmcnt(0) lgkmcnt(0)
	s_barrier
	s_mov_b64 s[4:5], 0

.LBB0_1948:
	s_waitcnt lgkmcnt(14)
	v_mfma_f32_32x32x16_bf16 v[34:49], v[142:145], v[194:197], v[34:49]
	v_sub_f32_e32 v98, v98, v208
	v_sub_f32_e32 v99, v99, v208
	v_sub_f32_e32 v100, v100, v208
	v_sub_f32_e32 v101, v101, v208
	v_exp_f32_e32 v98, v98
	v_exp_f32_e32 v99, v99
	v_exp_f32_e32 v100, v100
	v_exp_f32_e32 v101, v101
	s_waitcnt lgkmcnt(12)
	v_mfma_f32_32x32x16_bf16 v[18:33], v[142:145], v[190:193], v[18:33]
	v_sub_f32_e32 v102, v102, v208
	v_sub_f32_e32 v103, v103, v208
	v_sub_f32_e32 v104, v104, v208
	v_sub_f32_e32 v105, v105, v208
	v_exp_f32_e32 v102, v102
	v_exp_f32_e32 v103, v103
	v_exp_f32_e32 v104, v104
	v_exp_f32_e32 v105, v105
	s_and_b64 vcc, exec, s[6:7]
	v_add_u32_e32 v142, s80, v210
	v_add_u32_e32 v226, s80, v224
	s_cbranch_vccnz .LBB0_1950
	ds_read_b128 v[174:177], v142
	ds_read_b128 v[170:173], v142 offset:2048
.LBB0_1950:
	s_waitcnt lgkmcnt(10)
	v_mfma_f32_32x32x16_bf16 v[34:49], v[138:141], v[186:189], v[34:49]
	v_sub_f32_e32 v106, v106, v208
	v_sub_f32_e32 v107, v107, v208
	v_sub_f32_e32 v108, v108, v208
	v_sub_f32_e32 v109, v109, v208
	v_exp_f32_e32 v106, v106
	v_exp_f32_e32 v107, v107
	v_exp_f32_e32 v108, v108
	v_exp_f32_e32 v109, v109
	s_and_b64 vcc, exec, s[6:7]
	s_cbranch_vccnz .LBB0_1952
	ds_read_b128 v[166:169], v226
	ds_read_b128 v[162:165], v226 offset:2048
.LBB0_1952:
	s_waitcnt lgkmcnt(8)
	v_mfma_f32_32x32x16_bf16 v[18:33], v[138:141], v[182:185], v[18:33]
	v_sub_f32_e32 v110, v110, v208
	v_sub_f32_e32 v111, v111, v208
	v_sub_f32_e32 v112, v112, v208
	v_sub_f32_e32 v113, v113, v208
	v_exp_f32_e32 v110, v110
	v_exp_f32_e32 v111, v111
	v_exp_f32_e32 v112, v112
	v_exp_f32_e32 v113, v113
	s_and_b64 vcc, exec, s[6:7]
	s_cbranch_vccnz .LBB0_1954
	ds_read_b128 v[158:161], v142 offset:4096
	ds_read_b128 v[154:157], v142 offset:6144
.LBB0_1954:
	s_waitcnt lgkmcnt(6)
	v_mfma_f32_32x32x16_bf16 v[34:49], v[134:137], v[178:181], v[34:49]
	v_sub_f32_e32 v82, v82, v208
	v_sub_f32_e32 v83, v83, v208
	v_sub_f32_e32 v84, v84, v208
	v_sub_f32_e32 v85, v85, v208
	v_exp_f32_e32 v82, v82
	v_exp_f32_e32 v83, v83
	v_exp_f32_e32 v84, v84
	v_exp_f32_e32 v85, v85
	s_and_b64 vcc, exec, s[6:7]
	s_cbranch_vccnz .LBB0_1956
	ds_read_b128 v[150:153], v226 offset:4096
	ds_read_b128 v[146:149], v226 offset:6144

.LBB0_1977:
	v_add_u32_e32 v82, s80, v206
	ds_read_b64_tr_b16 v[10:11], v82 offset:24576
	ds_read_b64_tr_b16 v[12:13], v82 offset:25088
	v_cvt_pk_bf16_f32 v6, v66, v67
	v_cvt_pk_bf16_f32 v7, v68, v69
	v_cvt_pk_bf16_f32 v8, v70, v71
	v_cvt_pk_bf16_f32 v9, v72, v73
	ds_read_b64_tr_b16 v[14:15], v82 offset:25600
	ds_read_b64_tr_b16 v[16:17], v82 offset:26112
	s_waitcnt lgkmcnt(2)
	v_mfma_f32_32x32x16_bf16 v[34:49], v[6:9], v[10:13], v[34:49]
	ds_read_b64_tr_b16 v[10:11], v82 offset:28672
	ds_read_b64_tr_b16 v[12:13], v82 offset:29184
	v_add_f32_e32 v5, v66, v67
	v_add_f32_e32 v5, v68, v5
	v_add_f32_e32 v5, v69, v5
	v_add_f32_e32 v5, v70, v5
	ds_read_b64_tr_b16 v[66:67], v82 offset:29696
	ds_read_b64_tr_b16 v[68:69], v82 offset:30208
	v_add_f32_e32 v5, v71, v5
	s_waitcnt lgkmcnt(2)
	v_mfma_f32_32x32x16_bf16 v[18:33], v[6:9], v[10:13], v[18:33]
	v_add_f32_e32 v5, v72, v5
	v_cvt_pk_bf16_f32 v6, v74, v75
	v_cvt_pk_bf16_f32 v7, v76, v77
	v_cvt_pk_bf16_f32 v8, v78, v79
	v_cvt_pk_bf16_f32 v9, v80, v81
	v_add_f32_e32 v5, v73, v5
	v_add_f32_e32 v5, v74, v5
	v_mfma_f32_32x32x16_bf16 v[34:49], v[6:9], v[14:17], v[34:49]
	v_add_f32_e32 v5, v75, v5
	v_add_f32_e32 v5, v76, v5
	v_add_f32_e32 v5, v77, v5
	v_add_f32_e32 v5, v78, v5
	v_add_f32_e32 v5, v79, v5
	v_add_f32_e32 v5, v80, v5
	v_cvt_pk_bf16_f32 v10, v50, v51
	s_waitcnt lgkmcnt(0)
	v_mfma_f32_32x32x16_bf16 v[18:33], v[6:9], v[66:69], v[18:33]
	ds_read_b64_tr_b16 v[6:7], v82 offset:26624
	ds_read_b64_tr_b16 v[8:9], v82 offset:27136
	v_cvt_pk_bf16_f32 v11, v52, v53
	v_cvt_pk_bf16_f32 v12, v54, v55
	v_cvt_pk_bf16_f32 v13, v56, v57
	ds_read_b64_tr_b16 v[14:15], v82 offset:27648
	ds_read_b64_tr_b16 v[16:17], v82 offset:28160
	v_add_f32_e32 v5, v81, v5
	v_add_f32_e32 v5, v50, v5
	s_waitcnt lgkmcnt(2)
	v_mfma_f32_32x32x16_bf16 v[34:49], v[10:13], v[6:9], v[34:49]
	ds_read_b64_tr_b16 v[6:7], v82 offset:30720
	ds_read_b64_tr_b16 v[8:9], v82 offset:31232
	v_add_f32_e32 v5, v51, v5
	v_add_f32_e32 v5, v52, v5
	v_add_f32_e32 v5, v53, v5
	v_add_f32_e32 v5, v54, v5
	v_add_f32_e32 v5, v55, v5
	v_add_f32_e32 v5, v56, v5
	s_waitcnt lgkmcnt(0)
	v_mfma_f32_32x32x16_bf16 v[18:33], v[10:13], v[6:9], v[18:33]
	ds_read_b64_tr_b16 v[50:51], v82 offset:31744
	ds_read_b64_tr_b16 v[52:53], v82 offset:32256
	v_add_f32_e32 v5, v57, v5
	v_add_f32_e32 v5, v58, v5
	v_add_f32_e32 v5, v59, v5
	v_add_f32_e32 v5, v60, v5
	v_cvt_pk_bf16_f32 v6, v58, v59
	v_cvt_pk_bf16_f32 v7, v60, v61
	v_cvt_pk_bf16_f32 v8, v62, v63
	v_cvt_pk_bf16_f32 v9, v64, v65
	v_add_f32_e32 v5, v61, v5
	v_mfma_f32_32x32x16_bf16 v[34:49], v[6:9], v[14:17], v[34:49]
	v_add_f32_e32 v5, v62, v5
	v_add_f32_e32 v5, v63, v5
	v_add_f32_e32 v5, v64, v5
	v_add_f32_e32 v5, v65, v5
	v_add_f32_e32 v2, v2, v5
	v_mov_b32_e32 v5, v2
	s_nop 1
	v_permlane32_swap_b32_e32 v2, v5
	s_waitcnt lgkmcnt(0)
	v_mfma_f32_32x32x16_bf16 v[18:33], v[6:9], v[50:53], v[18:33]
	v_cmp_gt_u32_e32 vcc, 32, v202
	s_and_saveexec_b64 s[0:1], vcc
	v_add_f32_e32 v2, v2, v5
	ds_write_b32 v207, v2 offset:49280
	s_or_b64 exec, exec, s[0:1]
	s_waitcnt lgkmcnt(0)
	ds_read_b128 v[6:9], v4 offset:49280
	ds_read_b128 v[10:13], v4 offset:49312
	s_sub_i32 s0, 0x1f00, s71
	s_lshl_b64 s[4:5], s[30:31], 11
	s_add_u32 s1, s60, s4
	s_waitcnt lgkmcnt(1)
	v_rcp_f32_e32 v2, v6
	v_rcp_f32_e32 v5, v7
	v_rcp_f32_e32 v14, v8
	v_rcp_f32_e32 v15, v9
	s_waitcnt lgkmcnt(0)
	v_rcp_f32_e32 v16, v10
	ds_read_b128 v[6:9], v4 offset:49344
	v_rcp_f32_e32 v17, v11
	v_rcp_f32_e32 v50, v12
	v_rcp_f32_e32 v51, v13
	ds_read_b128 v[10:13], v4 offset:49376
	s_addc_u32 s5, s61, s5
	s_lshl_b32 s4, s76, 12
	s_add_i32 s6, s4, 16
	s_waitcnt lgkmcnt(1)
	v_rcp_f32_e32 v4, v6
	v_rcp_f32_e32 v6, v7
	v_rcp_f32_e32 v7, v8
	v_rcp_f32_e32 v8, v9
	s_waitcnt lgkmcnt(0)
	v_rcp_f32_e32 v9, v10
	v_rcp_f32_e32 v10, v11
	v_rcp_f32_e32 v11, v12
	v_rcp_f32_e32 v12, v13
	v_lshl_add_u32 v13, v204, 1, s6
	v_lshlrev_b32_e32 v52, 7, v205
	v_mul_f32_e32 v34, v34, v2
	v_mul_f32_e32 v2, v18, v2
	v_add_u32_e32 v53, v13, v52
	v_cvt_pk_bf16_f32 v2, v2, v3
	ds_write_b16 v53, v2 offset:51264
	v_mul_f32_e32 v2, v35, v5
	v_cvt_pk_bf16_f32 v2, v2, v3
	ds_write_b16 v53, v2 offset:51328
	v_mul_f32_e32 v2, v19, v5
	v_cvt_pk_bf16_f32 v2, v2, v3
	ds_write_b16 v53, v2 offset:51392
	v_mul_f32_e32 v2, v36, v14
	v_cvt_pk_bf16_f32 v2, v2, v3
	ds_write_b16 v53, v2 offset:51456
	v_mul_f32_e32 v2, v20, v14
	v_cvt_pk_bf16_f32 v2, v2, v3
	ds_write_b16 v53, v2 offset:51520
	v_mul_f32_e32 v2, v37, v15
	v_cvt_pk_bf16_f32 v2, v2, v3
	ds_write_b16 v53, v2 offset:51584
	v_mul_f32_e32 v2, v21, v15
	v_cvt_pk_bf16_f32 v2, v2, v3
	ds_write_b16 v53, v2 offset:51648
	v_or_b32_e32 v2, 0x400, v52
	v_mul_f32_e32 v5, v38, v16
	v_add_u32_e32 v2, v13, v2
	v_cvt_pk_bf16_f32 v5, v5, v3
	v_cvt_pk_bf16_f32 v34, v34, v3
	ds_write_b16 v53, v34 offset:51200
	ds_write_b16 v2, v5 offset:51200
	v_mul_f32_e32 v5, v22, v16
	v_cvt_pk_bf16_f32 v5, v5, v3
	ds_write_b16 v2, v5 offset:51264
	v_or_b32_e32 v2, 0x480, v52
	v_mul_f32_e32 v5, v39, v17
	v_add_u32_e32 v2, v13, v2
	v_cvt_pk_bf16_f32 v5, v5, v3
	ds_write_b16 v2, v5 offset:51200
	v_mul_f32_e32 v5, v23, v17
	v_cvt_pk_bf16_f32 v5, v5, v3
	ds_write_b16 v2, v5 offset:51264
	v_or_b32_e32 v2, 0x500, v52
	v_mul_f32_e32 v5, v40, v50
	v_add_u32_e32 v2, v13, v2
	v_cvt_pk_bf16_f32 v5, v5, v3
	ds_write_b16 v2, v5 offset:51200
	v_mul_f32_e32 v5, v24, v50
	v_cvt_pk_bf16_f32 v5, v5, v3
	ds_write_b16 v2, v5 offset:51264
	v_or_b32_e32 v2, 0x580, v52
	v_mul_f32_e32 v5, v41, v51
	v_add_u32_e32 v2, v13, v2
	v_cvt_pk_bf16_f32 v5, v5, v3
	ds_write_b16 v2, v5 offset:51200
	v_mul_f32_e32 v5, v25, v51
	v_cvt_pk_bf16_f32 v5, v5, v3
	ds_write_b16 v2, v5 offset:51264
	v_or_b32_e32 v2, 0x800, v52
	v_mul_f32_e32 v5, v42, v4
	v_mul_f32_e32 v4, v26, v4
	v_add_u32_e32 v2, v13, v2
	v_cvt_pk_bf16_f32 v4, v4, v3
	v_cvt_pk_bf16_f32 v5, v5, v3
	ds_write_b16 v2, v5 offset:51200
	ds_write_b16 v2, v4 offset:51264
	v_or_b32_e32 v2, 0x880, v52
	v_mul_f32_e32 v4, v43, v6
	v_add_u32_e32 v2, v13, v2
	v_cvt_pk_bf16_f32 v4, v4, v3
	ds_write_b16 v2, v4 offset:51200
	v_mul_f32_e32 v4, v27, v6
	v_cvt_pk_bf16_f32 v4, v4, v3
	ds_write_b16 v2, v4 offset:51264
	v_or_b32_e32 v2, 0x900, v52
	v_mul_f32_e32 v4, v44, v7
	v_add_u32_e32 v2, v13, v2
	v_cvt_pk_bf16_f32 v4, v4, v3
	ds_write_b16 v2, v4 offset:51200
	v_mul_f32_e32 v4, v28, v7
	v_cvt_pk_bf16_f32 v4, v4, v3
	ds_write_b16 v2, v4 offset:51264
	v_or_b32_e32 v2, 0x980, v52
	v_mul_f32_e32 v4, v45, v8
	v_add_u32_e32 v2, v13, v2
	v_cvt_pk_bf16_f32 v4, v4, v3
	ds_write_b16 v2, v4 offset:51200
	v_mul_f32_e32 v4, v29, v8
	v_cvt_pk_bf16_f32 v4, v4, v3
	ds_write_b16 v2, v4 offset:51264
	v_or_b32_e32 v2, 0xc00, v52
	v_mul_f32_e32 v4, v46, v9
	v_add_u32_e32 v2, v13, v2
	v_cvt_pk_bf16_f32 v4, v4, v3
	ds_write_b16 v2, v4 offset:51200
	v_mul_f32_e32 v4, v30, v9
	v_cvt_pk_bf16_f32 v4, v4, v3
	ds_write_b16 v2, v4 offset:51264
	v_or_b32_e32 v2, 0xc80, v52
	v_mul_f32_e32 v4, v47, v10
	v_add_u32_e32 v2, v13, v2
	v_cvt_pk_bf16_f32 v4, v4, v3
	ds_write_b16 v2, v4 offset:51200
	v_mul_f32_e32 v4, v31, v10
	v_cvt_pk_bf16_f32 v4, v4, v3
	ds_write_b16 v2, v4 offset:51264
	v_or_b32_e32 v2, 0xd00, v52
	v_mul_f32_e32 v4, v48, v11
	v_add_u32_e32 v2, v13, v2
	v_cvt_pk_bf16_f32 v4, v4, v3
	ds_write_b16 v2, v4 offset:51200
	v_mul_f32_e32 v4, v32, v11
	v_cvt_pk_bf16_f32 v4, v4, v3
	ds_write_b16 v2, v4 offset:51264
	v_or_b32_e32 v2, 0xd80, v52
	v_mul_f32_e32 v4, v49, v12
	v_add_u32_e32 v2, v13, v2
	v_cvt_pk_bf16_f32 v4, v4, v3
	ds_write_b16 v2, v4 offset:51200
	v_mul_f32_e32 v4, v33, v12
	v_cvt_pk_bf16_f32 v4, v4, v3
	ds_write_b16 v2, v4 offset:51264
	s_lshl_b32 s34, s81, 1
	v_lshlrev_b32_e32 v2, 1, v203
	s_add_u32 s4, s1, s34
	v_and_b32_e32 v2, 0x70, v2
	s_addc_u32 s5, s5, 0
	v_lshrrev_b32_e32 v16, 3, v202
	v_add_u32_e32 v17, s6, v2
	s_waitcnt lgkmcnt(0)
	v_lshl_add_u64 v[12:13], s[4:5], 0, v[2:3]
	v_lshl_add_u32 v2, v16, 7, v17
	v_or_b32_e32 v18, 8, v16
	ds_read_b128 v[4:7], v2 offset:51200
	v_lshl_add_u32 v8, v18, 7, v17
	ds_read_b128 v[8:11], v8 offset:51200
	v_lshlrev_b32_e32 v2, 11, v16
	v_lshl_add_u64 v[14:15], v[12:13], 0, v[2:3]
	v_lshlrev_b32_e32 v2, 11, v18
	s_waitcnt lgkmcnt(1)
	global_store_dwordx4 v[14:15], v[4:7], off
	v_mov_b32_e32 v44, v0
	s_lshr_b32 s36, s70, 6
	v_lshl_add_u64 v[4:5], v[12:13], 0, v[2:3]
	v_or_b32_e32 v2, 16, v16
	s_waitcnt lgkmcnt(0)
	global_store_dwordx4 v[4:5], v[8:11], off
	v_lshl_add_u32 v4, v2, 7, v17
	v_or_b32_e32 v16, 24, v16
	ds_read_b128 v[4:7], v4 offset:51200
	v_lshl_add_u32 v8, v16, 7, v17
	ds_read_b128 v[8:11], v8 offset:51200
	v_lshlrev_b32_e32 v2, 11, v2
	v_lshl_add_u64 v[14:15], v[12:13], 0, v[2:3]
	v_lshlrev_b32_e32 v2, 11, v16
	s_waitcnt lgkmcnt(1)
	global_store_dwordx4 v[14:15], v[4:7], off
	s_mov_b32 s39, 1
	s_movk_i32 s7, 0x4000
	v_lshl_add_u64 v[4:5], v[12:13], 0, v[2:3]
	s_waitcnt lgkmcnt(0)
	global_store_dwordx4 v[4:5], v[8:11], off
	s_waitcnt lgkmcnt(0)
	s_barrier
	v_mov_b32_e32 v214, 0
	v_readfirstlane_b32 s6, v44
	s_ashr_i32 s35, s6, 6
	s_add_u32 s0, s24, s0
	s_addc_u32 s1, s25, 0
	s_lshl_b32 s8, s35, 5
	s_ashr_i32 s4, s8, 31
	s_add_u32 s24, s0, s8
	s_addc_u32 s25, s1, s4
	s_lshl_b64 s[0:1], s[24:25], 10
	s_add_u32 s0, s96, s0
	s_addc_u32 s1, s97, s1
	s_add_u32 s0, s0, s34
	s_addc_u32 s1, s1, 0
	s_and_b32 s4, s6, 0x3fffffc0
	v_and_b32_e32 v204, 63, v44
	s_lshl_b32 s4, s4, 2
	s_add_i32 s30, s4, 16
	v_lshlrev_b32_e32 v2, 10, v204
	s_lshl_b32 s4, s35, 3
	v_lshl_add_u64 v[4:5], s[26:27], 0, v[2:3]
	s_ashr_i32 s5, s4, 31
	v_lshl_add_u64 v[196:197], s[4:5], 1, v[4:5]
	v_bfe_u32 v220, v44, 2, 6
	v_bfe_u32 v221, v44, 4, 2
	v_and_b32_e32 v222, 3, v44
	v_xor_b32_e32 v221, v221, v222
	v_bfe_u32 v222, v44, 8, 1
	v_lshl_add_u32 v221, v222, 2, v221
	v_lshlrev_b32_e32 v221, 4, v221
	v_lshl_add_u32 v220, v220, 10, v221
	v_mov_b32_e32 v221, 0
	v_lshl_add_u64 v[196:197], s[26:27], 0, v[220:221]
	s_lshl_b32 s4, s35, 4
	v_bfe_u32 v2, v44, 2, 4
	v_and_or_b32 v2, s4, 48, v2
	s_ashr_i32 s4, s6, 3
	s_andn2_b32 s4, s4, 31
	v_lshlrev_b32_e32 v2, 10, v2
	s_ashr_i32 s5, s4, 31
	s_lshl_b32 s37, s35, 10
	v_lshl_add_u64 v[4:5], s[28:29], 0, v[2:3]
	v_lshlrev_b32_e32 v205, 3, v44
	s_cmp_lg_u32 16, -1
	v_lshl_add_u64 v[4:5], s[4:5], 1, v[4:5]
	v_and_b32_e32 v45, 24, v205
	s_cselect_b32 s4, 16, 0
	v_bfe_u32 v100, v44, 5, 1
	v_lshlrev_b32_e32 v2, 1, v45
	s_add_i32 s37, s37, s4
	s_mov_b32 s4, m0
	s_mov_b32 m0, s37
	s_nop 0
	global_load_lds_dwordx4 v[196:197], off
	s_mov_b32 m0, s4
	v_and_b32_e32 v206, 31, v44
	v_lshl_add_u64 v[200:201], v[4:5], 0, v[2:3]
	s_add_i32 s38, s37, 0x6000
	s_mov_b32 s4, m0
	s_mov_b32 m0, s38
	s_nop 0
	global_load_lds_dwordx4 v[200:201], off
	s_mov_b32 m0, s4
	v_lshlrev_b32_e32 v192, 4, v100
	v_lshl_add_u64 v[4:5], v[196:197], 0, s[10:11]
	s_add_i32 s4, s37, 0x2000
	s_mov_b32 s5, m0
	s_mov_b32 m0, s4
	s_nop 0
	global_load_lds_dwordx4 v[4:5], off
	s_mov_b32 m0, s5
	v_lshl_or_b32 v2, v206, 10, v192
	global_load_dwordx4 v[128:131], v2, s[0:1]
	global_load_dwordx4 v[124:127], v2, s[0:1] offset:32
	global_load_dwordx4 v[116:119], v2, s[0:1] offset:64
	global_load_dwordx4 v[108:111], v2, s[0:1] offset:96
	v_lshlrev_b32_e32 v2, 10, v100
	v_lshlrev_b32_e32 v4, 4, v206
	v_add3_u32 v211, 16, v2, v4
	v_bfe_u32 v222, v206, 2, 2
	v_and_b32_e32 v223, 1, v222
	v_xor_b32_e32 v223, v223, v100
	v_and_b32_e32 v222, 2, v222
	v_or_b32_e32 v222, v222, v223
	v_lshlrev_b32_e32 v222, 4, v222
	v_lshl_add_u32 v211, v206, 6, v222
	v_xor_b32_e32 v225, 32, v211
	v_add_u32_e32 v211, 16, v211
	v_add_u32_e32 v225, 16, v225
	v_lshl_add_u64 v[4:5], v[196:197], 0, s[12:13]
	s_add_i32 s0, s37, 0x4000
	s_mov_b32 s1, m0
	s_mov_b32 m0, s0
	s_nop 0
	global_load_lds_dwordx4 v[4:5], off
	s_mov_b32 m0, s1
	s_waitcnt vmcnt(3) lgkmcnt(0)
	s_barrier
	ds_read_b128 v[20:23], v211
	v_add_u32_e32 v2, 16, v192
	v_add_u32_e32 v32, 0x14800, v2
	ds_read_b128 v[4:7], v32
	ds_read_b128 v[8:11], v32 offset:32
	ds_read_b128 v[12:15], v32 offset:64
	ds_read_b128 v[16:19], v32 offset:96
	ds_read_b128 v[36:39], v211 offset:2048
	s_waitcnt vmcnt(3) lgkmcnt(1)
	v_mfma_f32_32x32x16_bf16 v[4:19], v[20:23], v[128:131], v[4:19]
	ds_read_b128 v[20:23], v32 offset:128
	ds_read_b128 v[24:27], v32 offset:160
	ds_read_b128 v[28:31], v32 offset:192
	ds_read_b128 v[32:35], v32 offset:224
	v_add_u32_e32 v2, 0x14900, v2
	s_lshl_b32 s5, s69, 8
	s_addk_i32 s5, 0xe1c0
	v_lshlrev_b32_e32 v208, 2, v100
	s_mov_b32 s4, 0
	s_mov_b32 s6, 5
	s_waitcnt lgkmcnt(0)
	v_mfma_f32_32x32x16_bf16 v[20:35], v[36:39], v[128:131], v[20:35]
	ds_read_b128 v[36:39], v225
	ds_read_b128 v[40:43], v225 offset:2048
	s_movk_i32 s27, 0x2000
	s_add_i32 s26, s36, -5
	v_lshl_add_u32 v207, v206, 2, s30
	v_add_u32_e32 v193, s65, v192
	v_lshl_add_u64 v[188:189], v[200:201], 0, s[14:15]
	v_lshl_add_u64 v[190:191], v[196:197], 0, s[16:17]
	s_waitcnt vmcnt(2) lgkmcnt(1)
	v_mfma_f32_32x32x16_bf16 v[4:19], v[36:39], v[124:127], v[4:19]
	v_lshl_add_u64 v[202:203], v[200:201], 0, s[20:21]
	s_waitcnt lgkmcnt(0)
	v_mfma_f32_32x32x16_bf16 v[20:35], v[40:43], v[124:127], v[20:35]
	ds_read_b128 v[36:39], v211 offset:4096
	ds_read_b128 v[40:43], v211 offset:6144
	s_waitcnt vmcnt(1) lgkmcnt(1)
	v_mfma_f32_32x32x16_bf16 v[4:19], v[36:39], v[116:119], v[4:19]
	ds_read_b128 v[36:39], v225 offset:4096
	s_waitcnt lgkmcnt(1)
	v_mfma_f32_32x32x16_bf16 v[20:35], v[40:43], v[116:119], v[20:35]
	v_lshlrev_b32_e32 v40, 1, v44
	v_and_b32_e32 v46, 32, v40
	ds_read_b128 v[40:43], v225 offset:6144
	s_waitcnt vmcnt(0) lgkmcnt(0)
	s_barrier
	s_waitcnt vmcnt(0) lgkmcnt(1)
	v_mfma_f32_32x32x16_bf16 v[4:19], v[36:39], v[108:111], v[4:19]
	v_lshlrev_b32_e32 v38, 4, v44
	v_add3_u32 v36, 16, v46, v45
	v_lshlrev_b32_e32 v37, 8, v100
	v_and_b32_e32 v38, 0xc0, v38
	v_add3_u32 v209, v36, v37, v38
	s_nop 6
	v_max_f32_e32 v36, v5, v5
	s_waitcnt lgkmcnt(0)
	v_mfma_f32_32x32x16_bf16 v[20:35], v[40:43], v[108:111], v[20:35]
	v_max_f32_e32 v37, v4, v4
	v_max_f32_e32 v36, v37, v36
	s_nop 9
	v_max3_f32 v37, v6, v7, v21
	v_max3_f32 v36, v36, v20, v22
	v_max3_f32 v36, v36, v23, v8
	v_max3_f32 v37, v37, v10, v11
	v_max3_f32 v36, v36, v9, v24
	v_max3_f32 v37, v37, v26, v27
	v_max3_f32 v36, v36, v25, v12
	v_max3_f32 v37, v37, v14, v15
	v_max3_f32 v36, v36, v13, v28
	v_max3_f32 v37, v37, v30, v31
	v_max3_f32 v36, v36, v29, v16
	v_max3_f32 v37, v37, v18, v19
	v_max3_f32 v36, v36, v17, v32
	v_max3_f32 v37, v37, v34, v35
	v_max3_f32 v68, v36, v33, v37
	v_lshl_add_u64 v[36:37], v[196:197], 0, s[14:15]
	s_mov_b32 s0, m0
	s_mov_b32 m0, s37
	s_nop 0
	global_load_lds_dwordx4 v[36:37], off
	s_mov_b32 m0, s0
	v_mov_b32_e32 v69, v68
	v_lshl_add_u64 v[36:37], v[200:201], 0, s[10:11]
	s_add_i32 s0, s37, 0x8000
	s_mov_b32 s1, m0
	s_mov_b32 m0, s0
	s_nop 0
	global_load_lds_dwordx4 v[36:37], off
	s_mov_b32 m0, s1
	v_permlane32_swap_b32_e32 v68, v69
	ds_read_b128 v[160:163], v211 offset:8192
	ds_read_b128 v[156:159], v211 offset:10240
	ds_read_b128 v[152:155], v225 offset:8192
	ds_read_b128 v[148:151], v225 offset:10240
	ds_read_b128 v[144:147], v211 offset:12288
	ds_read_b128 v[140:143], v211 offset:14336
	ds_read_b128 v[136:139], v225 offset:12288
	ds_read_b128 v[132:135], v225 offset:14336
	s_waitcnt vmcnt(2) lgkmcnt(0)
	s_barrier
	ds_read_b128 v[36:39], v2 offset:128
	ds_read_b128 v[40:43], v2 offset:160
	ds_read_b128 v[44:47], v2 offset:192
	ds_read_b128 v[48:51], v2 offset:224
	ds_read_b128 v[52:55], v2
	ds_read_b128 v[56:59], v2 offset:32
	ds_read_b128 v[60:63], v2 offset:64
	ds_read_b128 v[64:67], v2 offset:96
	v_max_f32_e32 v2, v69, v69
	v_max_f32_e32 v68, v68, v68
	v_max_f32_e32 v210, v68, v2
	v_sub_f32_e32 v2, v20, v210
	v_exp_f32_e32 v68, v2
	v_sub_f32_e32 v2, v21, v210
	v_exp_f32_e32 v69, v2
	v_sub_f32_e32 v2, v22, v210
	v_exp_f32_e32 v70, v2
	v_sub_f32_e32 v2, v23, v210
	v_exp_f32_e32 v71, v2
	v_sub_f32_e32 v2, v24, v210
	v_exp_f32_e32 v72, v2
	v_sub_f32_e32 v2, v25, v210
	v_exp_f32_e32 v73, v2
	v_sub_f32_e32 v2, v26, v210
	v_exp_f32_e32 v74, v2
	v_sub_f32_e32 v2, v27, v210
	v_exp_f32_e32 v75, v2
	v_sub_f32_e32 v2, v28, v210
	v_exp_f32_e32 v76, v2
	v_sub_f32_e32 v2, v29, v210
	v_exp_f32_e32 v77, v2
	v_sub_f32_e32 v2, v30, v210
	v_exp_f32_e32 v78, v2
	v_sub_f32_e32 v2, v31, v210
	v_exp_f32_e32 v79, v2
	v_sub_f32_e32 v2, v32, v210
	v_exp_f32_e32 v80, v2
	v_sub_f32_e32 v2, v33, v210
	v_exp_f32_e32 v81, v2
	v_sub_f32_e32 v2, v34, v210
	v_exp_f32_e32 v82, v2
	v_sub_f32_e32 v2, v35, v210
	v_exp_f32_e32 v83, v2
	v_sub_f32_e32 v2, v4, v210
	v_exp_f32_e32 v84, v2
	v_sub_f32_e32 v2, v5, v210
	v_exp_f32_e32 v85, v2
	v_sub_f32_e32 v2, v6, v210
	v_exp_f32_e32 v86, v2
	v_sub_f32_e32 v2, v7, v210
	v_exp_f32_e32 v87, v2
	v_sub_f32_e32 v2, v8, v210
	v_exp_f32_e32 v88, v2
	v_sub_f32_e32 v2, v9, v210
	v_exp_f32_e32 v89, v2
	v_sub_f32_e32 v2, v10, v210
	v_exp_f32_e32 v90, v2
	v_sub_f32_e32 v2, v11, v210
	v_exp_f32_e32 v91, v2
	v_sub_f32_e32 v2, v12, v210
	v_exp_f32_e32 v92, v2
	v_sub_f32_e32 v2, v13, v210
	v_exp_f32_e32 v93, v2
	v_sub_f32_e32 v2, v14, v210
	v_exp_f32_e32 v94, v2
	v_sub_f32_e32 v2, v15, v210
	v_exp_f32_e32 v95, v2
	v_sub_f32_e32 v2, v16, v210
	v_exp_f32_e32 v96, v2
	v_sub_f32_e32 v2, v17, v210
	v_exp_f32_e32 v97, v2
	v_sub_f32_e32 v2, v18, v210
	v_exp_f32_e32 v98, v2
	v_sub_f32_e32 v2, v19, v210
	v_exp_f32_e32 v99, v2
	v_or_b32_e32 v2, s5, v208
	s_lshl_b32 s5, s22, 12
	v_mov_b32_e32 v16, v3
	v_mov_b32_e32 v17, v3
	v_subrev_u32_e32 v212, s5, v2
	v_mov_b32_e32 v2, v3
	v_mov_b32_e32 v4, v3
	v_mov_b32_e32 v5, v3
	v_mov_b32_e32 v6, v3
	v_mov_b32_e32 v7, v3
	v_mov_b32_e32 v8, v3
	v_mov_b32_e32 v9, v3
	v_mov_b32_e32 v10, v3
	v_mov_b32_e32 v11, v3
	v_mov_b32_e32 v12, v3
	v_mov_b32_e32 v13, v3
	v_mov_b32_e32 v14, v3
	v_mov_b32_e32 v15, v3
	v_mov_b64_e32 v[34:35], v[16:17]
	s_add_i32 s5, 16, 0x14c00
	v_mov_b64_e32 v[32:33], v[14:15]
	v_mov_b64_e32 v[30:31], v[12:13]
	v_mov_b64_e32 v[28:29], v[10:11]
	v_mov_b64_e32 v[26:27], v[8:9]
	v_mov_b64_e32 v[24:25], v[6:7]
	v_mov_b64_e32 v[22:23], v[4:5]
	v_mov_b64_e32 v[20:21], v[2:3]
	v_mov_b64_e32 v[18:19], v[16:17]
	v_cmp_gt_u32_e64 s[0:1], 32, v204
	v_add_u32_e32 v213, s5, v192
	v_mov_b64_e32 v[16:17], v[14:15]
	v_mov_b64_e32 v[14:15], v[12:13]
	v_mov_b64_e32 v[12:13], v[10:11]
	v_mov_b64_e32 v[10:11], v[8:9]
	v_mov_b64_e32 v[8:9], v[6:7]
	v_mov_b64_e32 v[6:7], v[4:5]
	v_mov_b64_e32 v[4:5], v[2:3]

.LBB0_1984:
	ds_read_b128 v[84:87], v193
	ds_read_b128 v[88:91], v193 offset:32
	ds_read_b128 v[68:71], v193 offset:128
	ds_read_b128 v[72:75], v193 offset:160
	ds_read_b128 v[92:95], v193 offset:64
	ds_read_b128 v[96:99], v193 offset:96
	ds_read_b128 v[76:79], v193 offset:192
	ds_read_b128 v[80:83], v193 offset:224
	s_waitcnt lgkmcnt(14)
	v_mfma_f32_32x32x16_bf16 v[20:35], v[120:123], v[184:187], v[20:35]
	v_sub_f32_e32 v2, v52, v210
	v_exp_f32_e32 v52, v2
	v_sub_f32_e32 v2, v53, v210
	v_exp_f32_e32 v53, v2
	v_sub_f32_e32 v2, v54, v210
	v_exp_f32_e32 v54, v2
	v_sub_f32_e32 v2, v55, v210
	v_exp_f32_e32 v55, v2
	v_mfma_f32_32x32x16_bf16 v[4:19], v[120:123], v[160:163], v[4:19]
	v_sub_f32_e32 v2, v56, v210
	v_exp_f32_e32 v56, v2
	v_sub_f32_e32 v2, v57, v210
	v_exp_f32_e32 v57, v2
	v_sub_f32_e32 v2, v58, v210
	v_exp_f32_e32 v58, v2
	v_sub_f32_e32 v2, v59, v210
	v_exp_f32_e32 v59, v2
	v_add_u32_e32 v2, s7, v211
	v_add_u32_e32 v227, s7, v225
	ds_read_b128 v[160:163], v2
	ds_read_b128 v[152:155], v2 offset:2048
	v_mfma_f32_32x32x16_bf16 v[20:35], v[112:115], v[156:159], v[20:35]
	v_sub_f32_e32 v60, v60, v210
	v_sub_f32_e32 v61, v61, v210
	v_sub_f32_e32 v62, v62, v210
	v_sub_f32_e32 v63, v63, v210
	v_exp_f32_e32 v60, v60
	v_exp_f32_e32 v61, v61
	v_exp_f32_e32 v62, v62
	v_exp_f32_e32 v63, v63
	ds_read_b128 v[156:159], v227
	ds_read_b128 v[144:147], v227 offset:2048
	v_mfma_f32_32x32x16_bf16 v[4:19], v[112:115], v[180:183], v[4:19]
	v_sub_f32_e32 v64, v64, v210
	v_sub_f32_e32 v65, v65, v210
	v_sub_f32_e32 v66, v66, v210
	v_sub_f32_e32 v67, v67, v210
	v_exp_f32_e32 v64, v64
	v_exp_f32_e32 v65, v65
	v_exp_f32_e32 v66, v66
	v_exp_f32_e32 v67, v67
	ds_read_b128 v[148:151], v2 offset:4096
	ds_read_b128 v[136:139], v2 offset:6144
	v_mfma_f32_32x32x16_bf16 v[20:35], v[104:107], v[176:179], v[20:35]
	v_sub_f32_e32 v36, v36, v210
	v_sub_f32_e32 v37, v37, v210
	v_sub_f32_e32 v38, v38, v210
	v_sub_f32_e32 v39, v39, v210
	v_exp_f32_e32 v36, v36
	v_exp_f32_e32 v37, v37
	v_exp_f32_e32 v38, v38
	v_exp_f32_e32 v39, v39
	ds_read_b128 v[140:143], v227 offset:4096
	ds_read_b128 v[132:135], v227 offset:6144
	s_waitcnt lgkmcnt(14)
	v_mfma_f32_32x32x16_bf16 v[4:19], v[104:107], v[172:175], v[4:19]
	v_sub_f32_e32 v2, v40, v210
	v_exp_f32_e32 v40, v2
	v_sub_f32_e32 v2, v41, v210
	v_exp_f32_e32 v41, v2
	v_sub_f32_e32 v2, v42, v210
	v_exp_f32_e32 v42, v2
	v_sub_f32_e32 v2, v43, v210
	v_exp_f32_e32 v43, v2
	v_mfma_f32_32x32x16_bf16 v[20:35], v[100:103], v[168:171], v[20:35]
	v_sub_f32_e32 v2, v44, v210
	v_exp_f32_e32 v44, v2
	v_sub_f32_e32 v2, v45, v210
	v_exp_f32_e32 v45, v2
	v_sub_f32_e32 v2, v46, v210
	v_exp_f32_e32 v46, v2
	v_sub_f32_e32 v2, v47, v210
	v_exp_f32_e32 v47, v2
	v_mfma_f32_32x32x16_bf16 v[4:19], v[100:103], v[164:167], v[4:19]
	v_sub_f32_e32 v2, v48, v210
	v_exp_f32_e32 v48, v2
	v_sub_f32_e32 v2, v49, v210
	v_exp_f32_e32 v49, v2
	v_sub_f32_e32 v2, v50, v210
	v_exp_f32_e32 v50, v2
	v_sub_f32_e32 v2, v51, v210
	v_exp_f32_e32 v51, v2
	s_waitcnt vmcnt(2) lgkmcnt(0)
	s_barrier
	s_andn2_b64 vcc, exec, s[22:23]
	v_add_u32_e32 v2, s30, v192
	s_cbranch_vccnz .LBB0_1986
	ds_read_b128 v[164:167], v2 offset:49248
	ds_read_b128 v[168:171], v2 offset:49216
	ds_read_b128 v[172:175], v2 offset:49184
	ds_read_b128 v[176:179], v2 offset:49152
	s_waitcnt lgkmcnt(3)
	v_pk_mul_f32 v[32:33], v[32:33], v[164:165]
	s_waitcnt lgkmcnt(2)
	v_pk_mul_f32 v[28:29], v[28:29], v[168:169]
	s_waitcnt lgkmcnt(1)
	v_pk_mul_f32 v[24:25], v[24:25], v[172:173]
	v_pk_mul_f32 v[34:35], v[34:35], v[166:167]
	v_pk_mul_f32 v[30:31], v[30:31], v[170:171]
	v_pk_mul_f32 v[26:27], v[26:27], v[174:175]
	s_waitcnt lgkmcnt(0)
	v_pk_mul_f32 v[22:23], v[22:23], v[178:179]
	v_pk_mul_f32 v[20:21], v[20:21], v[176:177]
	v_pk_mul_f32 v[16:17], v[16:17], v[164:165]
	v_pk_mul_f32 v[12:13], v[12:13], v[168:169]
	v_pk_mul_f32 v[8:9], v[8:9], v[172:173]
	v_pk_mul_f32 v[18:19], v[18:19], v[166:167]
	v_pk_mul_f32 v[14:15], v[14:15], v[170:171]
	v_pk_mul_f32 v[10:11], v[10:11], v[174:175]
	v_pk_mul_f32 v[6:7], v[6:7], v[178:179]
	v_pk_mul_f32 v[4:5], v[4:5], v[176:177]

.LBB0_1990:
	ds_read_b128 v[52:55], v193 offset:256
	ds_read_b128 v[56:59], v193 offset:288
	ds_read_b128 v[36:39], v193 offset:384
	ds_read_b128 v[40:43], v193 offset:416
	ds_read_b128 v[60:63], v193 offset:320
	ds_read_b128 v[64:67], v193 offset:352
	ds_read_b128 v[44:47], v193 offset:448
	ds_read_b128 v[48:51], v193 offset:480
	s_waitcnt lgkmcnt(14)
	v_mfma_f32_32x32x16_bf16 v[20:35], v[120:123], v[184:187], v[20:35]
	v_sub_f32_e32 v84, v84, v210
	v_sub_f32_e32 v85, v85, v210
	v_sub_f32_e32 v86, v86, v210
	v_sub_f32_e32 v87, v87, v210
	v_exp_f32_e32 v84, v84
	v_exp_f32_e32 v85, v85
	v_exp_f32_e32 v86, v86
	v_exp_f32_e32 v87, v87
	v_mfma_f32_32x32x16_bf16 v[4:19], v[120:123], v[160:163], v[4:19]
	v_sub_f32_e32 v88, v88, v210
	v_sub_f32_e32 v89, v89, v210
	v_sub_f32_e32 v90, v90, v210
	v_sub_f32_e32 v91, v91, v210
	v_exp_f32_e32 v88, v88
	v_exp_f32_e32 v89, v89
	v_exp_f32_e32 v90, v90
	v_exp_f32_e32 v91, v91
	v_add_u32_e32 v120, s58, v211
	v_add_u32_e32 v227, s58, v225
	ds_read_b128 v[160:163], v120
	ds_read_b128 v[156:159], v120 offset:2048
	v_mfma_f32_32x32x16_bf16 v[20:35], v[112:115], v[152:155], v[20:35]
	v_sub_f32_e32 v92, v92, v210
	v_sub_f32_e32 v93, v93, v210
	v_sub_f32_e32 v94, v94, v210
	v_sub_f32_e32 v95, v95, v210
	v_exp_f32_e32 v92, v92
	v_exp_f32_e32 v93, v93
	v_exp_f32_e32 v94, v94
	v_exp_f32_e32 v95, v95
	ds_read_b128 v[152:155], v227
	ds_read_b128 v[148:151], v227 offset:2048
	v_mfma_f32_32x32x16_bf16 v[4:19], v[112:115], v[180:183], v[4:19]
	v_sub_f32_e32 v96, v96, v210
	v_sub_f32_e32 v97, v97, v210
	v_sub_f32_e32 v98, v98, v210
	v_sub_f32_e32 v99, v99, v210
	v_exp_f32_e32 v96, v96
	v_exp_f32_e32 v97, v97
	v_exp_f32_e32 v98, v98
	v_exp_f32_e32 v99, v99
	ds_read_b128 v[144:147], v120 offset:4096
	ds_read_b128 v[140:143], v120 offset:6144
	v_mfma_f32_32x32x16_bf16 v[20:35], v[104:107], v[176:179], v[20:35]
	v_sub_f32_e32 v68, v68, v210
	v_sub_f32_e32 v69, v69, v210
	v_sub_f32_e32 v70, v70, v210
	v_sub_f32_e32 v71, v71, v210
	v_exp_f32_e32 v68, v68
	v_exp_f32_e32 v69, v69
	v_exp_f32_e32 v70, v70
	v_exp_f32_e32 v71, v71
	ds_read_b128 v[136:139], v227 offset:4096
	ds_read_b128 v[132:135], v227 offset:6144
	s_waitcnt lgkmcnt(14)
	v_mfma_f32_32x32x16_bf16 v[4:19], v[104:107], v[172:175], v[4:19]
	v_sub_f32_e32 v72, v72, v210
	v_sub_f32_e32 v73, v73, v210
	v_sub_f32_e32 v74, v74, v210
	v_sub_f32_e32 v75, v75, v210
	v_exp_f32_e32 v72, v72
	v_exp_f32_e32 v73, v73
	v_exp_f32_e32 v74, v74
	v_exp_f32_e32 v75, v75
	v_mfma_f32_32x32x16_bf16 v[20:35], v[100:103], v[168:171], v[20:35]
	v_sub_f32_e32 v76, v76, v210
	v_sub_f32_e32 v77, v77, v210
	v_sub_f32_e32 v78, v78, v210
	v_sub_f32_e32 v79, v79, v210
	v_exp_f32_e32 v76, v76
	v_exp_f32_e32 v77, v77
	v_exp_f32_e32 v78, v78
	v_exp_f32_e32 v79, v79
	v_mfma_f32_32x32x16_bf16 v[4:19], v[100:103], v[164:167], v[4:19]
	v_sub_f32_e32 v80, v80, v210
	v_sub_f32_e32 v81, v81, v210
	v_sub_f32_e32 v82, v82, v210
	v_sub_f32_e32 v83, v83, v210
	v_exp_f32_e32 v80, v80
	v_exp_f32_e32 v81, v81
	v_exp_f32_e32 v82, v82
	v_exp_f32_e32 v83, v83
	s_waitcnt vmcnt(2) lgkmcnt(0)
	s_barrier
	s_andn2_b64 vcc, exec, s[22:23]
	s_cbranch_vccnz .LBB0_1992
	ds_read_b128 v[164:167], v2 offset:49248
	ds_read_b128 v[168:171], v2 offset:49216
	ds_read_b128 v[172:175], v2 offset:49184
	ds_read_b128 v[176:179], v2 offset:49152
	s_waitcnt lgkmcnt(3)
	v_pk_mul_f32 v[32:33], v[32:33], v[164:165]
	s_waitcnt lgkmcnt(2)
	v_pk_mul_f32 v[28:29], v[28:29], v[168:169]
	s_waitcnt lgkmcnt(1)
	v_pk_mul_f32 v[24:25], v[24:25], v[172:173]
	v_pk_mul_f32 v[34:35], v[34:35], v[166:167]
	v_pk_mul_f32 v[30:31], v[30:31], v[170:171]
	v_pk_mul_f32 v[26:27], v[26:27], v[174:175]
	s_waitcnt lgkmcnt(0)
	v_pk_mul_f32 v[22:23], v[22:23], v[178:179]
	v_pk_mul_f32 v[20:21], v[20:21], v[176:177]
	v_pk_mul_f32 v[16:17], v[16:17], v[164:165]
	v_pk_mul_f32 v[12:13], v[12:13], v[168:169]
	v_pk_mul_f32 v[8:9], v[8:9], v[172:173]
	v_pk_mul_f32 v[18:19], v[18:19], v[166:167]
	v_pk_mul_f32 v[14:15], v[14:15], v[170:171]
	v_pk_mul_f32 v[10:11], v[10:11], v[174:175]
	v_pk_mul_f32 v[6:7], v[6:7], v[178:179]
	v_pk_mul_f32 v[4:5], v[4:5], v[176:177]

.LBB0_2004:
	ds_read_b128 v[84:87], v213
	ds_read_b128 v[88:91], v213 offset:32
	ds_read_b128 v[68:71], v213 offset:128
	ds_read_b128 v[72:75], v213 offset:160
	ds_read_b128 v[92:95], v213 offset:64
	ds_read_b128 v[96:99], v213 offset:96
	ds_read_b128 v[76:79], v213 offset:192
	ds_read_b128 v[80:83], v213 offset:224
	s_waitcnt lgkmcnt(14)
	v_mfma_f32_32x32x16_bf16 v[20:35], v[120:123], v[188:191], v[20:35]
	v_sub_f32_e32 v52, v52, v210
	v_sub_f32_e32 v53, v53, v210
	v_sub_f32_e32 v54, v54, v210
	v_sub_f32_e32 v55, v55, v210
	v_exp_f32_e32 v52, v52
	v_exp_f32_e32 v53, v53
	v_exp_f32_e32 v54, v54
	v_exp_f32_e32 v55, v55
	v_mfma_f32_32x32x16_bf16 v[4:19], v[120:123], v[160:163], v[4:19]
	v_sub_f32_e32 v56, v56, v210
	v_sub_f32_e32 v57, v57, v210
	v_sub_f32_e32 v58, v58, v210
	v_sub_f32_e32 v59, v59, v210
	v_exp_f32_e32 v56, v56
	v_exp_f32_e32 v57, v57
	v_exp_f32_e32 v58, v58
	v_exp_f32_e32 v59, v59
	v_add_u32_e32 v120, s59, v211
	v_add_u32_e32 v227, s59, v225
	ds_read_b128 v[160:163], v120
	ds_read_b128 v[156:159], v120 offset:2048
	v_mfma_f32_32x32x16_bf16 v[20:35], v[112:115], v[184:187], v[20:35]
	v_sub_f32_e32 v60, v60, v210
	v_sub_f32_e32 v61, v61, v210
	v_sub_f32_e32 v62, v62, v210
	v_sub_f32_e32 v63, v63, v210
	v_exp_f32_e32 v60, v60
	v_exp_f32_e32 v61, v61
	v_exp_f32_e32 v62, v62
	v_exp_f32_e32 v63, v63
	ds_read_b128 v[152:155], v227
	ds_read_b128 v[148:151], v227 offset:2048
	v_mfma_f32_32x32x16_bf16 v[4:19], v[112:115], v[180:183], v[4:19]
	v_sub_f32_e32 v64, v64, v210
	v_sub_f32_e32 v65, v65, v210
	v_sub_f32_e32 v66, v66, v210
	v_sub_f32_e32 v67, v67, v210
	v_exp_f32_e32 v64, v64
	v_exp_f32_e32 v65, v65
	v_exp_f32_e32 v66, v66
	v_exp_f32_e32 v67, v67
	ds_read_b128 v[144:147], v120 offset:4096
	ds_read_b128 v[140:143], v120 offset:6144
	v_mfma_f32_32x32x16_bf16 v[20:35], v[104:107], v[176:179], v[20:35]
	v_sub_f32_e32 v36, v36, v210
	v_sub_f32_e32 v37, v37, v210
	v_sub_f32_e32 v38, v38, v210
	v_sub_f32_e32 v39, v39, v210
	v_exp_f32_e32 v36, v36
	v_exp_f32_e32 v37, v37
	v_exp_f32_e32 v38, v38
	v_exp_f32_e32 v39, v39
	ds_read_b128 v[136:139], v227 offset:4096
	ds_read_b128 v[132:135], v227 offset:6144
	s_waitcnt lgkmcnt(14)
	v_mfma_f32_32x32x16_bf16 v[4:19], v[104:107], v[172:175], v[4:19]
	v_sub_f32_e32 v40, v40, v210
	v_sub_f32_e32 v41, v41, v210
	v_sub_f32_e32 v42, v42, v210
	v_sub_f32_e32 v43, v43, v210
	v_exp_f32_e32 v40, v40
	v_exp_f32_e32 v41, v41
	v_exp_f32_e32 v42, v42
	v_exp_f32_e32 v43, v43
	v_mfma_f32_32x32x16_bf16 v[20:35], v[100:103], v[168:171], v[20:35]
	v_sub_f32_e32 v44, v44, v210
	v_sub_f32_e32 v45, v45, v210
	v_sub_f32_e32 v46, v46, v210
	v_sub_f32_e32 v47, v47, v210
	v_exp_f32_e32 v44, v44
	v_exp_f32_e32 v45, v45
	v_exp_f32_e32 v46, v46
	v_exp_f32_e32 v47, v47
	v_mfma_f32_32x32x16_bf16 v[4:19], v[100:103], v[164:167], v[4:19]
	v_sub_f32_e32 v48, v48, v210
	v_sub_f32_e32 v49, v49, v210
	v_sub_f32_e32 v50, v50, v210
	v_sub_f32_e32 v51, v51, v210
	v_exp_f32_e32 v48, v48
	v_exp_f32_e32 v49, v49
	v_exp_f32_e32 v50, v50
	v_exp_f32_e32 v51, v51
	s_mov_b64 s[4:5], -1
	s_and_b64 vcc, exec, s[22:23]
	s_cbranch_vccz .LBB0_2040
	s_add_i32 s4, s6, -2
	s_cmp_ge_u32 s4, s69
	s_mov_b64 s[4:5], -1
	s_cbranch_scc0 .LBB0_2007
	s_waitcnt vmcnt(0) lgkmcnt(0)
	s_barrier
	s_mov_b64 s[4:5], 0

.LBB0_2022:
	s_waitcnt lgkmcnt(14)
	v_mfma_f32_32x32x16_bf16 v[20:35], v[120:123], v[188:191], v[20:35]
	v_sub_f32_e32 v84, v84, v210
	v_sub_f32_e32 v85, v85, v210
	v_sub_f32_e32 v86, v86, v210
	v_sub_f32_e32 v87, v87, v210
	v_exp_f32_e32 v84, v84
	v_exp_f32_e32 v85, v85
	v_exp_f32_e32 v86, v86
	v_exp_f32_e32 v87, v87
	s_waitcnt lgkmcnt(12)
	v_mfma_f32_32x32x16_bf16 v[4:19], v[120:123], v[192:195], v[4:19]
	v_sub_f32_e32 v88, v88, v210
	v_sub_f32_e32 v89, v89, v210
	v_sub_f32_e32 v90, v90, v210
	v_sub_f32_e32 v91, v91, v210
	v_exp_f32_e32 v88, v88
	v_exp_f32_e32 v89, v89
	v_exp_f32_e32 v90, v90
	v_exp_f32_e32 v91, v91
	s_and_b64 vcc, exec, s[6:7]
	v_add_u32_e32 v120, s58, v211
	v_add_u32_e32 v227, s58, v225
	s_cbranch_vccnz .LBB0_2024
	ds_read_b128 v[160:163], v120
	ds_read_b128 v[156:159], v120 offset:2048
.LBB0_2024:
	s_waitcnt lgkmcnt(10)
	v_mfma_f32_32x32x16_bf16 v[20:35], v[112:115], v[184:187], v[20:35]
	v_sub_f32_e32 v92, v92, v210
	v_sub_f32_e32 v93, v93, v210
	v_sub_f32_e32 v94, v94, v210
	v_sub_f32_e32 v95, v95, v210
	v_exp_f32_e32 v92, v92
	v_exp_f32_e32 v93, v93
	v_exp_f32_e32 v94, v94
	v_exp_f32_e32 v95, v95
	s_and_b64 vcc, exec, s[6:7]
	s_cbranch_vccnz .LBB0_2026
	ds_read_b128 v[152:155], v227
	ds_read_b128 v[148:151], v227 offset:2048
.LBB0_2026:
	s_waitcnt lgkmcnt(8)
	v_mfma_f32_32x32x16_bf16 v[4:19], v[112:115], v[180:183], v[4:19]
	v_sub_f32_e32 v96, v96, v210
	v_sub_f32_e32 v97, v97, v210
	v_sub_f32_e32 v98, v98, v210
	v_sub_f32_e32 v99, v99, v210
	v_exp_f32_e32 v96, v96
	v_exp_f32_e32 v97, v97
	v_exp_f32_e32 v98, v98
	v_exp_f32_e32 v99, v99
	s_and_b64 vcc, exec, s[6:7]
	s_cbranch_vccnz .LBB0_2028
	ds_read_b128 v[144:147], v120 offset:4096
	ds_read_b128 v[140:143], v120 offset:6144
.LBB0_2028:
	s_waitcnt lgkmcnt(6)
	v_mfma_f32_32x32x16_bf16 v[20:35], v[104:107], v[176:179], v[20:35]
	v_sub_f32_e32 v68, v68, v210
	v_sub_f32_e32 v69, v69, v210
	v_sub_f32_e32 v70, v70, v210
	v_sub_f32_e32 v71, v71, v210
	v_exp_f32_e32 v68, v68
	v_exp_f32_e32 v69, v69
	v_exp_f32_e32 v70, v70
	v_exp_f32_e32 v71, v71
	s_and_b64 vcc, exec, s[6:7]
	s_cbranch_vccnz .LBB0_2030
	ds_read_b128 v[136:139], v227 offset:4096
	ds_read_b128 v[132:135], v227 offset:6144
